# GEMM K-loops: s_setprio 0 moved from before to after the barrier that ends each MFMA segment
# speedup vs baseline: 1.0187x; 1.0067x over previous
; #define PG8_STAGE(bufoff, gbase, voff) do { _Pragma("unroll") for (int _i = 0; _i < 2; ++_i) \
;         __builtin_amdgcn_global_load_lds((const unsigned*)((const char*)(gbase) + (voff)[_i]), (LAS unsigned*)(lds + (bufoff) + ldsw + _i * 8192), 16, 0, 0); } while (0)
; #define PG8_LDA(dst, b, h) do { _Pragma("unroll") for (int m = 0; m < 4; ++m) _Pragma("unroll") for (int k = 0; k < 2; ++k) dst[m][k] = *(const LAS bf16x8*)(lds + PG8_SA(b, h) + aoff + m * 2048 + k * 1024); } while (0)
; #define PG8_LDB(dst, b, h) do { _Pragma("unroll") for (int n = 0; n < 2; ++n) _Pragma("unroll") for (int k = 0; k < 2; ++k) dst[n][k] = *(const LAS bf16x8*)(lds + PG8_SB(b, h) + boff + n * 2048 + k * 1024); } while (0)
; #define PG8_MMA(ai, bj, At, Bt) do { __builtin_amdgcn_s_setprio(1); _Pragma("unroll") for (int m = 0; m < 4; ++m) _Pragma("unroll") for (int n = 0; n < 2; ++n) _Pragma("unroll") for (int k = 0; k < 2; ++k) \
;         acc[ai][bj][m][n] = __builtin_amdgcn_mfma_f32_16x16x32_bf16(Bt[n][k], At[m][k], acc[ai][bj][m][n], 0, 0, 0); __builtin_amdgcn_s_setprio(0); } while (0)
; #define PG8_WAIT_V(n) asm volatile("s_waitcnt vmcnt(" #n ")" ::: "memory")
; #define PG8_WAIT_L(n) asm volatile("s_waitcnt lgkmcnt(" #n ")" ::: "memory")
; #define PG8_BAR __builtin_amdgcn_s_barrier()
; template <class Epi, class Sched, bool ALIGN_EPI, bool LAST_FUSED = false, bool PERM = false, bool CARRY = false>
; __device__ __forceinline__ void gemm_phase(LAS unsigned char* lds, const int tid, const int K, const int lda, const int ldb, const Sched& S, const Epi& E) {
;     ...
;             const bool last = (t == nt - 2);
;             const char* a1 = cA + (size_t)(t + 1) * kstep;
;             const char* a2 = last ? nA : cA + (size_t)(t + 2) * kstep; const char* b2 = last ? nB : cB + (size_t)(t + 2) * kstep;
;             const char* a3 = a2 + kstep; const char* b3 = b2 + kstep;
;             PG8_LDB(B0, 0, 0); PG8_LDB(B1, 0, 1); PG8_SCHED; PG8_LDA(At, 0, 0); PG8_STAGE(PG8_SA(1, 1), a1 + hstepA, voffA);
;             PG8_WAIT_V(8); PG8_WAIT_L(0); PG8_BAR; PG8_MMA(0, 0, At, B0); PG8_MMA(0, 1, At, B1); PG8_BAR; PG8_SCHED;
;             PG8_LDA(At, 0, 1); PG8_STAGE(PG8_SB(0, 0), b2, voffB); PG8_STAGE(PG8_SB(0, 1), b2 + hstepB, voffB); PG8_STAGE(PG8_SA(0, 0), a2, voffA);
;             PG8_WAIT_V(8); PG8_WAIT_L(0); PG8_BAR; PG8_MMA(1, 0, At, B0); PG8_MMA(1, 1, At, B1); PG8_BAR; PG8_SCHED;
.LBB0_279:
	s_add_u32 s4, s2, 0xfff80080
	s_addc_u32 s5, s3, -1
	s_add_i32 s28, 0, 0x10000
	s_cmp_eq_u32 s27, 28
	s_cselect_b32 s37, s43, s5
	s_cselect_b32 s36, s42, s4
	s_cselect_b32 s5, s71, s23
	s_cselect_b32 s4, s70, s22
	s_add_i32 s31, 0, 0x14000
	v_add_u32_e32 v154, s28, v144
	v_add_u32_e32 v170, s31, v144
	ds_read_b128 v[136:139], v154
	ds_read_b128 v[146:149], v154 offset:1024
	ds_read_b128 v[150:153], v154 offset:2048
	ds_read_b128 v[154:157], v154 offset:3072
	ds_read_b128 v[158:161], v170
	ds_read_b128 v[162:165], v170 offset:1024
	ds_read_b128 v[166:169], v170 offset:2048
	ds_read_b128 v[170:173], v170 offset:3072
	v_lshl_add_u64 v[206:207], s[2:3], 0, v[132:133]
	s_add_i32 m0, s52, 0xc000
	ds_read_b128 v[174:177], v145
	ds_read_b128 v[178:181], v145 offset:1024
	ds_read_b128 v[182:185], v145 offset:2048
	ds_read_b128 v[186:189], v145 offset:3072
	ds_read_b128 v[190:193], v145 offset:4096
	ds_read_b128 v[194:197], v145 offset:5120
	ds_read_b128 v[198:201], v145 offset:6144
	ds_read_b128 v[202:205], v145 offset:7168
	global_load_lds_dwordx4 v[206:207], off
	v_lshl_add_u64 v[206:207], s[2:3], 0, v[134:135]
	s_add_i32 m0, s52, 0xe000
	s_nop 0
	global_load_lds_dwordx4 v[206:207], off
	s_waitcnt vmcnt(8)
	s_waitcnt lgkmcnt(0)
	s_barrier
	s_setprio 1
	v_mfma_f32_16x16x32_bf16 v[126:129], v[136:139], v[174:177], v[126:129]
	v_mfma_f32_16x16x32_bf16 v[122:125], v[150:153], v[174:177], v[122:125]
	v_mfma_f32_16x16x32_bf16 v[110:113], v[136:139], v[182:185], v[110:113]
	v_mfma_f32_16x16x32_bf16 v[106:109], v[150:153], v[182:185], v[106:109]
	v_mfma_f32_16x16x32_bf16 v[94:97], v[136:139], v[190:193], v[94:97]
	v_mfma_f32_16x16x32_bf16 v[90:93], v[150:153], v[190:193], v[90:93]
	v_mfma_f32_16x16x32_bf16 v[78:81], v[136:139], v[198:201], v[78:81]
	v_mfma_f32_16x16x32_bf16 v[74:77], v[150:153], v[198:201], v[74:77]
	v_mfma_f32_16x16x32_bf16 v[126:129], v[146:149], v[178:181], v[126:129]
	v_mfma_f32_16x16x32_bf16 v[122:125], v[154:157], v[178:181], v[122:125]
	v_mfma_f32_16x16x32_bf16 v[110:113], v[146:149], v[186:189], v[110:113]
	v_mfma_f32_16x16x32_bf16 v[106:109], v[154:157], v[186:189], v[106:109]
	v_mfma_f32_16x16x32_bf16 v[94:97], v[146:149], v[194:197], v[94:97]
	v_mfma_f32_16x16x32_bf16 v[90:93], v[154:157], v[194:197], v[90:93]
	v_mfma_f32_16x16x32_bf16 v[78:81], v[146:149], v[202:205], v[78:81]
	v_mfma_f32_16x16x32_bf16 v[74:77], v[154:157], v[202:205], v[74:77]
	s_setprio 0
	s_setprio 1
	v_mfma_f32_16x16x32_bf16 v[118:121], v[158:161], v[174:177], v[118:121]
	v_mfma_f32_16x16x32_bf16 v[114:117], v[166:169], v[174:177], v[114:117]
	v_mfma_f32_16x16x32_bf16 v[102:105], v[158:161], v[182:185], v[102:105]
	v_mfma_f32_16x16x32_bf16 v[98:101], v[166:169], v[182:185], v[98:101]
	v_mfma_f32_16x16x32_bf16 v[86:89], v[158:161], v[190:193], v[86:89]
	v_mfma_f32_16x16x32_bf16 v[82:85], v[166:169], v[190:193], v[82:85]
	v_mfma_f32_16x16x32_bf16 v[70:73], v[158:161], v[198:201], v[70:73]
	v_mfma_f32_16x16x32_bf16 v[66:69], v[166:169], v[198:201], v[66:69]
	v_mfma_f32_16x16x32_bf16 v[118:121], v[162:165], v[178:181], v[118:121]
	v_mfma_f32_16x16x32_bf16 v[114:117], v[170:173], v[178:181], v[114:117]
	v_mfma_f32_16x16x32_bf16 v[102:105], v[162:165], v[186:189], v[102:105]
	v_mfma_f32_16x16x32_bf16 v[98:101], v[170:173], v[186:189], v[98:101]
	v_mfma_f32_16x16x32_bf16 v[86:89], v[162:165], v[194:197], v[86:89]
	v_mfma_f32_16x16x32_bf16 v[82:85], v[170:173], v[194:197], v[82:85]
	v_mfma_f32_16x16x32_bf16 v[70:73], v[162:165], v[202:205], v[70:73]
	v_mfma_f32_16x16x32_bf16 v[66:69], v[170:173], v[202:205], v[66:69]
	s_barrier
	s_setprio 0
	s_add_i32 s28, s28, s51
	v_lshl_add_u64 v[206:207], s[4:5], 0, v[0:1]
	s_mov_b32 m0, s28
	ds_read_b128 v[174:177], v145 offset:16384
	ds_read_b128 v[178:181], v145 offset:17408
	ds_read_b128 v[182:185], v145 offset:18432
	ds_read_b128 v[186:189], v145 offset:19456
	ds_read_b128 v[190:193], v145 offset:20480
	ds_read_b128 v[194:197], v145 offset:21504
	ds_read_b128 v[198:201], v145 offset:22528
	ds_read_b128 v[202:205], v145 offset:23552
	global_load_lds_dwordx4 v[206:207], off
	s_add_i32 m0, s28, 0x2000
	s_add_u32 s28, s4, 0x80000
	v_lshl_add_u64 v[208:209], s[4:5], 0, v[130:131]
	s_addc_u32 s29, s5, 0
	s_add_i32 s31, s31, s51
	global_load_lds_dwordx4 v[208:209], off
	v_lshl_add_u64 v[210:211], s[28:29], 0, v[0:1]
	s_mov_b32 m0, s31
	v_lshl_add_u64 v[212:213], s[36:37], 0, v[130:131]
	global_load_lds_dwordx4 v[210:211], off
	v_lshl_add_u64 v[210:211], s[28:29], 0, v[130:131]
	s_add_i32 m0, s31, 0x2000
	s_nop 0
	global_load_lds_dwordx4 v[210:211], off
	v_lshl_add_u64 v[210:211], s[36:37], 0, v[0:1]
	s_mov_b32 m0, s52
	s_nop 0
	global_load_lds_dwordx4 v[210:211], off
	s_mov_b32 m0, s53
	s_nop 0
	global_load_lds_dwordx4 v[212:213], off
	s_waitcnt vmcnt(8)
	s_waitcnt lgkmcnt(0)
	s_barrier
; #define PG8_STAGE(bufoff, gbase, voff) do { _Pragma("unroll") for (int _i = 0; _i < 2; ++_i) \
;         __builtin_amdgcn_global_load_lds((const unsigned*)((const char*)(gbase) + (voff)[_i]), (LAS unsigned*)(lds + (bufoff) + ldsw + _i * 8192), 16, 0, 0); } while (0)
; #define PG8_LDA(dst, b, h) do { _Pragma("unroll") for (int m = 0; m < 4; ++m) _Pragma("unroll") for (int k = 0; k < 2; ++k) dst[m][k] = *(const LAS bf16x8*)(lds + PG8_SA(b, h) + aoff + m * 2048 + k * 1024); } while (0)
; #define PG8_LDB(dst, b, h) do { _Pragma("unroll") for (int n = 0; n < 2; ++n) _Pragma("unroll") for (int k = 0; k < 2; ++k) dst[n][k] = *(const LAS bf16x8*)(lds + PG8_SB(b, h) + boff + n * 2048 + k * 1024); } while (0)
; #define PG8_MMA(ai, bj, At, Bt) do { __builtin_amdgcn_s_setprio(1); _Pragma("unroll") for (int m = 0; m < 4; ++m) _Pragma("unroll") for (int n = 0; n < 2; ++n) _Pragma("unroll") for (int k = 0; k < 2; ++k) \
;         acc[ai][bj][m][n] = __builtin_amdgcn_mfma_f32_16x16x32_bf16(Bt[n][k], At[m][k], acc[ai][bj][m][n], 0, 0, 0); __builtin_amdgcn_s_setprio(0); } while (0)
; #define PG8_WAIT_V(n) asm volatile("s_waitcnt vmcnt(" #n ")" ::: "memory")
; #define PG8_WAIT_L(n) asm volatile("s_waitcnt lgkmcnt(" #n ")" ::: "memory")
; #define PG8_BAR __builtin_amdgcn_s_barrier()
; #define PG8_SCHED __builtin_amdgcn_sched_barrier(0)
; template <class Epi, class Sched, bool ALIGN_EPI, bool LAST_FUSED = false, bool PERM = false, bool CARRY = false>
; __device__ __forceinline__ void gemm_phase(LAS unsigned char* lds, const int tid, const int K, const int lda, const int ldb, const Sched& S, const Epi& E) {
;     ...
;             PG8_LDB(B0, 0, 0); PG8_LDB(B1, 0, 1); PG8_SCHED; PG8_LDA(At, 0, 0); PG8_STAGE(PG8_SA(1, 1), a1 + hstepA, voffA);
;             PG8_WAIT_V(8); PG8_WAIT_L(0); PG8_BAR; PG8_MMA(0, 0, At, B0); PG8_MMA(0, 1, At, B1); PG8_BAR; PG8_SCHED;
;             PG8_LDA(At, 0, 1); PG8_STAGE(PG8_SB(0, 0), b2, voffB); PG8_STAGE(PG8_SB(0, 1), b2 + hstepB, voffB); PG8_STAGE(PG8_SA(0, 0), a2, voffA);
;             PG8_WAIT_V(8); PG8_WAIT_L(0); PG8_BAR; PG8_MMA(1, 0, At, B0); PG8_MMA(1, 1, At, B1); PG8_BAR; PG8_SCHED;
;             PG8_LDB(B0, 1, 0); PG8_LDB(B1, 1, 1); PG8_SCHED; PG8_LDA(At, 1, 0); PG8_STAGE(PG8_SA(0, 1), a2 + hstepA, voffA);
;             PG8_WAIT_V(8); PG8_WAIT_L(0); PG8_BAR; PG8_MMA(0, 0, At, B0); PG8_MMA(0, 1, At, B1); PG8_BAR; PG8_SCHED;
	s_setprio 1
	v_mfma_f32_16x16x32_bf16 v[62:65], v[136:139], v[174:177], v[62:65]
	v_mfma_f32_16x16x32_bf16 v[58:61], v[150:153], v[174:177], v[58:61]
	v_mfma_f32_16x16x32_bf16 v[46:49], v[136:139], v[182:185], v[46:49]
	v_mfma_f32_16x16x32_bf16 v[42:45], v[150:153], v[182:185], v[42:45]
	v_mfma_f32_16x16x32_bf16 v[30:33], v[136:139], v[190:193], v[30:33]
	v_mfma_f32_16x16x32_bf16 v[26:29], v[150:153], v[190:193], v[26:29]
	v_mfma_f32_16x16x32_bf16 v[14:17], v[136:139], v[198:201], v[14:17]
	v_mfma_f32_16x16x32_bf16 v[10:13], v[150:153], v[198:201], v[10:13]
	v_mfma_f32_16x16x32_bf16 v[62:65], v[146:149], v[178:181], v[62:65]
	v_mfma_f32_16x16x32_bf16 v[58:61], v[154:157], v[178:181], v[58:61]
	v_mfma_f32_16x16x32_bf16 v[46:49], v[146:149], v[186:189], v[46:49]
	v_mfma_f32_16x16x32_bf16 v[42:45], v[154:157], v[186:189], v[42:45]
	v_mfma_f32_16x16x32_bf16 v[30:33], v[146:149], v[194:197], v[30:33]
	v_mfma_f32_16x16x32_bf16 v[26:29], v[154:157], v[194:197], v[26:29]
	v_mfma_f32_16x16x32_bf16 v[14:17], v[146:149], v[202:205], v[14:17]
	v_mfma_f32_16x16x32_bf16 v[10:13], v[154:157], v[202:205], v[10:13]
	s_setprio 0
	s_setprio 1
	v_mfma_f32_16x16x32_bf16 v[54:57], v[158:161], v[174:177], v[54:57]
	v_mfma_f32_16x16x32_bf16 v[50:53], v[166:169], v[174:177], v[50:53]
	v_mfma_f32_16x16x32_bf16 v[38:41], v[158:161], v[182:185], v[38:41]
	v_mfma_f32_16x16x32_bf16 v[34:37], v[166:169], v[182:185], v[34:37]
	v_mfma_f32_16x16x32_bf16 v[22:25], v[158:161], v[190:193], v[22:25]
	v_mfma_f32_16x16x32_bf16 v[18:21], v[166:169], v[190:193], v[18:21]
	v_mfma_f32_16x16x32_bf16 v[6:9], v[158:161], v[198:201], v[6:9]
	v_mfma_f32_16x16x32_bf16 v[2:5], v[166:169], v[198:201], v[2:5]
	v_mfma_f32_16x16x32_bf16 v[54:57], v[162:165], v[178:181], v[54:57]
	v_mfma_f32_16x16x32_bf16 v[50:53], v[170:173], v[178:181], v[50:53]
	v_mfma_f32_16x16x32_bf16 v[38:41], v[162:165], v[186:189], v[38:41]
	v_mfma_f32_16x16x32_bf16 v[34:37], v[170:173], v[186:189], v[34:37]
	v_mfma_f32_16x16x32_bf16 v[22:25], v[162:165], v[194:197], v[22:25]
	v_mfma_f32_16x16x32_bf16 v[18:21], v[170:173], v[194:197], v[18:21]
	v_mfma_f32_16x16x32_bf16 v[6:9], v[162:165], v[202:205], v[6:9]
	v_mfma_f32_16x16x32_bf16 v[2:5], v[170:173], v[202:205], v[2:5]
	s_barrier
	s_setprio 0
	s_add_i32 s31, 0, 0x18000
	s_add_i32 s35, 0, 0x1c000
	v_add_u32_e32 v154, s31, v144
	v_add_u32_e32 v170, s35, v144
	ds_read_b128 v[136:139], v154
	ds_read_b128 v[146:149], v154 offset:1024
	ds_read_b128 v[150:153], v154 offset:2048
	ds_read_b128 v[154:157], v154 offset:3072
	ds_read_b128 v[158:161], v170
	ds_read_b128 v[162:165], v170 offset:1024
	ds_read_b128 v[166:169], v170 offset:2048
	ds_read_b128 v[170:173], v170 offset:3072
	s_add_u32 s28, s36, 0x80000
	s_addc_u32 s29, s37, 0
	s_mov_b32 m0, s54
	v_lshl_add_u64 v[214:215], s[28:29], 0, v[0:1]
	ds_read_b128 v[174:177], v145 offset:32768
	ds_read_b128 v[178:181], v145 offset:33792
	ds_read_b128 v[182:185], v145 offset:34816
	ds_read_b128 v[186:189], v145 offset:35840
	ds_read_b128 v[190:193], v145 offset:36864
	ds_read_b128 v[194:197], v145 offset:37888
	ds_read_b128 v[198:201], v145 offset:38912
	ds_read_b128 v[202:205], v145 offset:39936
	global_load_lds_dwordx4 v[214:215], off
	v_lshl_add_u64 v[214:215], s[28:29], 0, v[130:131]
	s_mov_b32 m0, s55
	s_nop 0
	global_load_lds_dwordx4 v[214:215], off
	s_waitcnt vmcnt(8)
	s_waitcnt lgkmcnt(0)
	s_barrier
	s_setprio 1
	v_mfma_f32_16x16x32_bf16 v[126:129], v[136:139], v[174:177], v[126:129]
	v_mfma_f32_16x16x32_bf16 v[122:125], v[150:153], v[174:177], v[122:125]
	v_mfma_f32_16x16x32_bf16 v[110:113], v[136:139], v[182:185], v[110:113]
	v_mfma_f32_16x16x32_bf16 v[106:109], v[150:153], v[182:185], v[106:109]
	v_mfma_f32_16x16x32_bf16 v[94:97], v[136:139], v[190:193], v[94:97]
	v_mfma_f32_16x16x32_bf16 v[90:93], v[150:153], v[190:193], v[90:93]
	v_mfma_f32_16x16x32_bf16 v[78:81], v[136:139], v[198:201], v[78:81]
	v_mfma_f32_16x16x32_bf16 v[74:77], v[150:153], v[198:201], v[74:77]
	v_mfma_f32_16x16x32_bf16 v[126:129], v[146:149], v[178:181], v[126:129]
	v_mfma_f32_16x16x32_bf16 v[122:125], v[154:157], v[178:181], v[122:125]
	v_mfma_f32_16x16x32_bf16 v[110:113], v[146:149], v[186:189], v[110:113]
	v_mfma_f32_16x16x32_bf16 v[106:109], v[154:157], v[186:189], v[106:109]
	v_mfma_f32_16x16x32_bf16 v[94:97], v[146:149], v[194:197], v[94:97]
	v_mfma_f32_16x16x32_bf16 v[90:93], v[154:157], v[194:197], v[90:93]
	v_mfma_f32_16x16x32_bf16 v[78:81], v[146:149], v[202:205], v[78:81]
	v_mfma_f32_16x16x32_bf16 v[74:77], v[154:157], v[202:205], v[74:77]
	s_setprio 0
	s_setprio 1
	v_mfma_f32_16x16x32_bf16 v[118:121], v[158:161], v[174:177], v[118:121]
	v_mfma_f32_16x16x32_bf16 v[114:117], v[166:169], v[174:177], v[114:117]
	v_mfma_f32_16x16x32_bf16 v[102:105], v[158:161], v[182:185], v[102:105]
	v_mfma_f32_16x16x32_bf16 v[98:101], v[166:169], v[182:185], v[98:101]
	v_mfma_f32_16x16x32_bf16 v[86:89], v[158:161], v[190:193], v[86:89]
	v_mfma_f32_16x16x32_bf16 v[82:85], v[166:169], v[190:193], v[82:85]
	v_mfma_f32_16x16x32_bf16 v[70:73], v[158:161], v[198:201], v[70:73]
	v_mfma_f32_16x16x32_bf16 v[66:69], v[166:169], v[198:201], v[66:69]
	v_mfma_f32_16x16x32_bf16 v[118:121], v[162:165], v[178:181], v[118:121]
	v_mfma_f32_16x16x32_bf16 v[114:117], v[170:173], v[178:181], v[114:117]
	v_mfma_f32_16x16x32_bf16 v[102:105], v[162:165], v[186:189], v[102:105]
	v_mfma_f32_16x16x32_bf16 v[98:101], v[170:173], v[186:189], v[98:101]
	v_mfma_f32_16x16x32_bf16 v[86:89], v[162:165], v[194:197], v[86:89]
	v_mfma_f32_16x16x32_bf16 v[82:85], v[170:173], v[194:197], v[82:85]
	v_mfma_f32_16x16x32_bf16 v[70:73], v[162:165], v[202:205], v[70:73]
	v_mfma_f32_16x16x32_bf16 v[66:69], v[170:173], v[202:205], v[66:69]
	s_barrier
; #define PG8_STAGE(bufoff, gbase, voff) do { _Pragma("unroll") for (int _i = 0; _i < 2; ++_i) \
;         __builtin_amdgcn_global_load_lds((const unsigned*)((const char*)(gbase) + (voff)[_i]), (LAS unsigned*)(lds + (bufoff) + ldsw + _i * 8192), 16, 0, 0); } while (0)
; #define PG8_LDA(dst, b, h) do { _Pragma("unroll") for (int m = 0; m < 4; ++m) _Pragma("unroll") for (int k = 0; k < 2; ++k) dst[m][k] = *(const LAS bf16x8*)(lds + PG8_SA(b, h) + aoff + m * 2048 + k * 1024); } while (0)
; #define PG8_MMA(ai, bj, At, Bt) do { __builtin_amdgcn_s_setprio(1); _Pragma("unroll") for (int m = 0; m < 4; ++m) _Pragma("unroll") for (int n = 0; n < 2; ++n) _Pragma("unroll") for (int k = 0; k < 2; ++k) \
;         acc[ai][bj][m][n] = __builtin_amdgcn_mfma_f32_16x16x32_bf16(Bt[n][k], At[m][k], acc[ai][bj][m][n], 0, 0, 0); __builtin_amdgcn_s_setprio(0); } while (0)
; #define PG8_WAIT_V(n) asm volatile("s_waitcnt vmcnt(" #n ")" ::: "memory")
; #define PG8_WAIT_L(n) asm volatile("s_waitcnt lgkmcnt(" #n ")" ::: "memory")
; #define PG8_BAR __builtin_amdgcn_s_barrier()
; #define PG8_SCHED __builtin_amdgcn_sched_barrier(0)
; template <class Epi, class Sched, bool ALIGN_EPI, bool LAST_FUSED = false, bool PERM = false, bool CARRY = false>
; __device__ __forceinline__ void gemm_phase(LAS unsigned char* lds, const int tid, const int K, const int lda, const int ldb, const Sched& S, const Epi& E) {
;     ...
;             PG8_LDA(At, 1, 1); PG8_STAGE(PG8_SB(1, 0), b3, voffB); PG8_STAGE(PG8_SB(1, 1), b3 + hstepB, voffB); PG8_STAGE(PG8_SA(1, 0), a3, voffA);
;             PG8_WAIT_V(8); PG8_WAIT_L(0); PG8_BAR; PG8_MMA(1, 0, At, B0); PG8_MMA(1, 1, At, B1); PG8_BAR; PG8_SCHED;
;         }
;         if constexpr (ALIGN_EPI) { if (wr == 0) PG8_BAR; }
	s_setprio 0
	s_add_i32 s28, s31, s51
	v_lshl_add_u64 v[206:207], v[206:207], 0, s[68:69]
	s_mov_b32 m0, s28
	ds_read_b128 v[174:177], v145 offset:49152
	ds_read_b128 v[178:181], v145 offset:50176
	ds_read_b128 v[182:185], v145 offset:51200
	ds_read_b128 v[186:189], v145 offset:52224
	ds_read_b128 v[190:193], v145 offset:53248
	ds_read_b128 v[194:197], v145 offset:54272
	ds_read_b128 v[198:201], v145 offset:55296
	ds_read_b128 v[202:205], v145 offset:56320
	global_load_lds_dwordx4 v[206:207], off
	s_add_i32 m0, s28, 0x2000
	s_add_u32 s4, s4, 0x80080
	v_lshl_add_u64 v[206:207], v[208:209], 0, s[68:69]
	s_addc_u32 s5, s5, 0
	s_add_i32 s28, s35, s51
	global_load_lds_dwordx4 v[206:207], off
	v_lshl_add_u64 v[206:207], s[4:5], 0, v[0:1]
	s_mov_b32 m0, s28
	s_nop 0
	global_load_lds_dwordx4 v[206:207], off
	v_lshl_add_u64 v[206:207], s[4:5], 0, v[130:131]
	s_add_i32 m0, s28, 0x2000
	s_nop 0
	global_load_lds_dwordx4 v[206:207], off
	v_lshl_add_u64 v[206:207], v[210:211], 0, s[68:69]
	s_mov_b32 m0, s57
	s_nop 0
	global_load_lds_dwordx4 v[206:207], off
	v_lshl_add_u64 v[206:207], v[212:213], 0, s[68:69]
	s_mov_b32 m0, s58
	s_nop 0
	global_load_lds_dwordx4 v[206:207], off
	s_waitcnt vmcnt(8)
	s_waitcnt lgkmcnt(0)
	s_barrier
	s_setprio 1
	v_mfma_f32_16x16x32_bf16 v[62:65], v[136:139], v[174:177], v[62:65]
	v_mfma_f32_16x16x32_bf16 v[58:61], v[150:153], v[174:177], v[58:61]
	v_mfma_f32_16x16x32_bf16 v[46:49], v[136:139], v[182:185], v[46:49]
	v_mfma_f32_16x16x32_bf16 v[42:45], v[150:153], v[182:185], v[42:45]
	v_mfma_f32_16x16x32_bf16 v[30:33], v[136:139], v[190:193], v[30:33]
	v_mfma_f32_16x16x32_bf16 v[26:29], v[150:153], v[190:193], v[26:29]
	v_mfma_f32_16x16x32_bf16 v[14:17], v[136:139], v[198:201], v[14:17]
	v_mfma_f32_16x16x32_bf16 v[10:13], v[150:153], v[198:201], v[10:13]
	v_mfma_f32_16x16x32_bf16 v[62:65], v[146:149], v[178:181], v[62:65]
	v_mfma_f32_16x16x32_bf16 v[58:61], v[154:157], v[178:181], v[58:61]
	v_mfma_f32_16x16x32_bf16 v[46:49], v[146:149], v[186:189], v[46:49]
	v_mfma_f32_16x16x32_bf16 v[42:45], v[154:157], v[186:189], v[42:45]
	v_mfma_f32_16x16x32_bf16 v[30:33], v[146:149], v[194:197], v[30:33]
	v_mfma_f32_16x16x32_bf16 v[26:29], v[154:157], v[194:197], v[26:29]
	v_mfma_f32_16x16x32_bf16 v[14:17], v[146:149], v[202:205], v[14:17]
	v_mfma_f32_16x16x32_bf16 v[10:13], v[154:157], v[202:205], v[10:13]
	s_setprio 0
	s_setprio 1
	v_mfma_f32_16x16x32_bf16 v[54:57], v[158:161], v[174:177], v[54:57]
	v_mfma_f32_16x16x32_bf16 v[50:53], v[166:169], v[174:177], v[50:53]
	v_mfma_f32_16x16x32_bf16 v[38:41], v[158:161], v[182:185], v[38:41]
	v_mfma_f32_16x16x32_bf16 v[34:37], v[166:169], v[182:185], v[34:37]
	v_mfma_f32_16x16x32_bf16 v[22:25], v[158:161], v[190:193], v[22:25]
	v_mfma_f32_16x16x32_bf16 v[18:21], v[166:169], v[190:193], v[18:21]
	v_mfma_f32_16x16x32_bf16 v[6:9], v[158:161], v[198:201], v[6:9]
	v_mfma_f32_16x16x32_bf16 v[2:5], v[166:169], v[198:201], v[2:5]
	v_mfma_f32_16x16x32_bf16 v[54:57], v[162:165], v[178:181], v[54:57]
	v_mfma_f32_16x16x32_bf16 v[50:53], v[170:173], v[178:181], v[50:53]
	v_mfma_f32_16x16x32_bf16 v[38:41], v[162:165], v[186:189], v[38:41]
	v_mfma_f32_16x16x32_bf16 v[34:37], v[170:173], v[186:189], v[34:37]
	v_mfma_f32_16x16x32_bf16 v[22:25], v[162:165], v[194:197], v[22:25]
	v_mfma_f32_16x16x32_bf16 v[18:21], v[170:173], v[194:197], v[18:21]
	v_mfma_f32_16x16x32_bf16 v[6:9], v[162:165], v[202:205], v[6:9]
	v_mfma_f32_16x16x32_bf16 v[2:5], v[170:173], v[202:205], v[2:5]
	s_barrier
	s_setprio 0
	s_add_i32 s27, s27, 2
	s_add_u32 s2, s2, 0x100
	s_addc_u32 s3, s3, 0
	s_add_u32 s22, s22, 0x100
	s_addc_u32 s23, s23, 0
	s_cmp_gt_u32 s27, 29
	s_cbranch_scc0 .LBB0_279
	s_and_b64 vcc, exec, s[18:19]
	s_cbranch_vccz .LBB0_282
	s_barrier

; #define PG8_STAGE(bufoff, gbase, voff) do { _Pragma("unroll") for (int _i = 0; _i < 2; ++_i) \
;         __builtin_amdgcn_global_load_lds((const unsigned*)((const char*)(gbase) + (voff)[_i]), (LAS unsigned*)(lds + (bufoff) + ldsw + _i * 8192), 16, 0, 0); } while (0)
; #define PG8_LDA(dst, b, h) do { _Pragma("unroll") for (int m = 0; m < 4; ++m) _Pragma("unroll") for (int k = 0; k < 2; ++k) dst[m][k] = *(const LAS bf16x8*)(lds + PG8_SA(b, h) + aoff + m * 2048 + k * 1024); } while (0)
; #define PG8_LDB(dst, b, h) do { _Pragma("unroll") for (int n = 0; n < 2; ++n) _Pragma("unroll") for (int k = 0; k < 2; ++k) dst[n][k] = *(const LAS bf16x8*)(lds + PG8_SB(b, h) + boff + n * 2048 + k * 1024); } while (0)
; #define PG8_WAIT_V(n) asm volatile("s_waitcnt vmcnt(" #n ")" ::: "memory")
; #define PG8_WAIT_L(n) asm volatile("s_waitcnt lgkmcnt(" #n ")" ::: "memory")
; #define PG8_BAR __builtin_amdgcn_s_barrier()
; #define PG8_SCHED __builtin_amdgcn_sched_barrier(0)
; template <class Epi, class Sched, bool ALIGN_EPI, bool LAST_FUSED = false, bool PERM = false, bool CARRY = false>
; __device__ __forceinline__ void gemm_phase(LAS unsigned char* lds, const int tid, const int K, const int lda, const int ldb, const Sched& S, const Epi& E) {
;     ...
;         const bool has_next = S.next(KD_IDX(ui + 1), nxt);
;         const char* nA = has_next ? nxt.a : cA; const char* nB = has_next ? nxt.b : cB; const int nt = cur.nt;
; #pragma unroll 1
;         for (int t = 0; t < nt; t += 2) {
;             const bool last = (t == nt - 2);
;             const char* a1 = cA + (size_t)(t + 1) * kstep;
;             const char* a2 = last ? nA : cA + (size_t)(t + 2) * kstep; const char* b2 = last ? nB : cB + (size_t)(t + 2) * kstep;
;             const char* a3 = a2 + kstep; const char* b3 = b2 + kstep;
;             PG8_LDB(B0, 0, 0); PG8_LDB(B1, 0, 1); PG8_SCHED; PG8_LDA(At, 0, 0); PG8_STAGE(PG8_SA(1, 1), a1 + hstepA, voffA);
;             PG8_WAIT_V(8); PG8_WAIT_L(0); PG8_BAR; PG8_MMA(0, 0, At, B0); PG8_MMA(0, 1, At, B1); PG8_BAR; PG8_SCHED;
;             PG8_LDA(At, 0, 1); PG8_STAGE(PG8_SB(0, 0), b2, voffB); PG8_STAGE(PG8_SB(0, 1), b2 + hstepB, voffB); PG8_STAGE(PG8_SA(0, 0), a2, voffA);
;             PG8_WAIT_V(8); PG8_WAIT_L(0); PG8_BAR; PG8_MMA(1, 0, At, B0); PG8_MMA(1, 1, At, B1); PG8_BAR; PG8_SCHED;
.LBB0_512:
	s_add_u32 s28, s4, 0xfff80080
	s_addc_u32 s29, s5, -1
	s_add_i32 s31, 0, 0x10000
	s_cmp_eq_u32 s24, 28
	s_cselect_b32 s41, s87, s29
	s_cselect_b32 s40, s86, s28
	v_add_u32_e32 v148, s31, v160
	s_cselect_b32 s37, s39, s23
	s_cselect_b32 s36, s38, s22
	s_add_i32 s35, 0, 0x14000
	ds_read_b128 v[140:143], v148
	ds_read_b128 v[144:147], v148 offset:1024
	ds_read_b128 v[162:165], v148 offset:2048
	ds_read_b128 v[166:169], v148 offset:3072
	v_add_u32_e32 v148, s35, v160
	ds_read_b128 v[170:173], v148
	ds_read_b128 v[174:177], v148 offset:1024
	ds_read_b128 v[178:181], v148 offset:2048
	ds_read_b128 v[182:185], v148 offset:3072
	v_lshl_add_u64 v[148:149], s[4:5], 0, v[136:137]
	s_add_i32 m0, s54, 0xc000
	ds_read_b128 v[186:189], v161
	ds_read_b128 v[190:193], v161 offset:1024
	ds_read_b128 v[194:197], v161 offset:2048
	ds_read_b128 v[198:201], v161 offset:3072
	ds_read_b128 v[202:205], v161 offset:4096
	ds_read_b128 v[206:209], v161 offset:5120
	ds_read_b128 v[210:213], v161 offset:6144
	ds_read_b128 v[214:217], v161 offset:7168
	global_load_lds_dwordx4 v[148:149], off
	v_lshl_add_u64 v[148:149], s[4:5], 0, v[138:139]
	s_add_i32 m0, s54, 0xe000
	s_nop 0
	global_load_lds_dwordx4 v[148:149], off
	s_waitcnt vmcnt(8)
	s_waitcnt lgkmcnt(0)
	s_barrier
	s_setprio 1
	v_mfma_f32_16x16x32_bf16 v[126:129], v[140:143], v[186:189], v[126:129]
	v_mfma_f32_16x16x32_bf16 v[122:125], v[162:165], v[186:189], v[122:125]
	v_mfma_f32_16x16x32_bf16 v[110:113], v[140:143], v[194:197], v[110:113]
	v_mfma_f32_16x16x32_bf16 v[106:109], v[162:165], v[194:197], v[106:109]
	v_mfma_f32_16x16x32_bf16 v[94:97], v[140:143], v[202:205], v[94:97]
	v_mfma_f32_16x16x32_bf16 v[90:93], v[162:165], v[202:205], v[90:93]
	v_mfma_f32_16x16x32_bf16 v[78:81], v[140:143], v[210:213], v[78:81]
	v_mfma_f32_16x16x32_bf16 v[74:77], v[162:165], v[210:213], v[74:77]
	v_mfma_f32_16x16x32_bf16 v[126:129], v[144:147], v[190:193], v[126:129]
	v_mfma_f32_16x16x32_bf16 v[122:125], v[166:169], v[190:193], v[122:125]
	v_mfma_f32_16x16x32_bf16 v[110:113], v[144:147], v[198:201], v[110:113]
	v_mfma_f32_16x16x32_bf16 v[106:109], v[166:169], v[198:201], v[106:109]
	v_mfma_f32_16x16x32_bf16 v[94:97], v[144:147], v[206:209], v[94:97]
	v_mfma_f32_16x16x32_bf16 v[90:93], v[166:169], v[206:209], v[90:93]
	v_mfma_f32_16x16x32_bf16 v[78:81], v[144:147], v[214:217], v[78:81]
	v_mfma_f32_16x16x32_bf16 v[74:77], v[166:169], v[214:217], v[74:77]
	s_setprio 0
	s_setprio 1
	v_mfma_f32_16x16x32_bf16 v[118:121], v[170:173], v[186:189], v[118:121]
	v_mfma_f32_16x16x32_bf16 v[114:117], v[178:181], v[186:189], v[114:117]
	v_mfma_f32_16x16x32_bf16 v[102:105], v[170:173], v[194:197], v[102:105]
	v_mfma_f32_16x16x32_bf16 v[98:101], v[178:181], v[194:197], v[98:101]
	v_mfma_f32_16x16x32_bf16 v[86:89], v[170:173], v[202:205], v[86:89]
	v_mfma_f32_16x16x32_bf16 v[82:85], v[178:181], v[202:205], v[82:85]
	v_mfma_f32_16x16x32_bf16 v[70:73], v[170:173], v[210:213], v[70:73]
	v_mfma_f32_16x16x32_bf16 v[66:69], v[178:181], v[210:213], v[66:69]
	v_mfma_f32_16x16x32_bf16 v[118:121], v[174:177], v[190:193], v[118:121]
	v_mfma_f32_16x16x32_bf16 v[114:117], v[182:185], v[190:193], v[114:117]
	v_mfma_f32_16x16x32_bf16 v[102:105], v[174:177], v[198:201], v[102:105]
	v_mfma_f32_16x16x32_bf16 v[98:101], v[182:185], v[198:201], v[98:101]
	v_mfma_f32_16x16x32_bf16 v[86:89], v[174:177], v[206:209], v[86:89]
	v_mfma_f32_16x16x32_bf16 v[82:85], v[182:185], v[206:209], v[82:85]
	v_mfma_f32_16x16x32_bf16 v[70:73], v[174:177], v[214:217], v[70:73]
	v_mfma_f32_16x16x32_bf16 v[66:69], v[182:185], v[214:217], v[66:69]
	s_barrier
	s_setprio 0
	s_add_i32 s28, s31, s52
	v_lshl_add_u64 v[148:149], s[36:37], 0, v[0:1]
	s_mov_b32 m0, s28
	ds_read_b128 v[186:189], v161 offset:16384
	ds_read_b128 v[190:193], v161 offset:17408
	ds_read_b128 v[194:197], v161 offset:18432
	ds_read_b128 v[198:201], v161 offset:19456
	ds_read_b128 v[202:205], v161 offset:20480
	ds_read_b128 v[206:209], v161 offset:21504
	ds_read_b128 v[210:213], v161 offset:22528
	ds_read_b128 v[214:217], v161 offset:23552
	global_load_lds_dwordx4 v[148:149], off
	s_add_i32 m0, s28, 0x2000
	s_add_u32 s28, s36, 0x80000
	v_lshl_add_u64 v[152:153], s[36:37], 0, v[130:131]
	s_addc_u32 s29, s37, 0
	s_add_i32 s31, s35, s52
	global_load_lds_dwordx4 v[152:153], off
	v_lshl_add_u64 v[156:157], s[28:29], 0, v[0:1]
	s_mov_b32 m0, s31
	v_lshl_add_u64 v[218:219], s[40:41], 0, v[132:133]
	global_load_lds_dwordx4 v[156:157], off
	v_lshl_add_u64 v[156:157], s[28:29], 0, v[130:131]
	s_add_i32 m0, s31, 0x2000
	s_nop 0
	global_load_lds_dwordx4 v[156:157], off
	v_lshl_add_u64 v[156:157], s[40:41], 0, v[134:135]
	s_mov_b32 m0, s54
	s_nop 0
	global_load_lds_dwordx4 v[156:157], off
	s_mov_b32 m0, s55
	s_nop 0
	global_load_lds_dwordx4 v[218:219], off
	s_waitcnt vmcnt(8)
	s_waitcnt lgkmcnt(0)
	s_barrier
; #define PG8_STAGE(bufoff, gbase, voff) do { _Pragma("unroll") for (int _i = 0; _i < 2; ++_i) \
;         __builtin_amdgcn_global_load_lds((const unsigned*)((const char*)(gbase) + (voff)[_i]), (LAS unsigned*)(lds + (bufoff) + ldsw + _i * 8192), 16, 0, 0); } while (0)
; #define PG8_LDA(dst, b, h) do { _Pragma("unroll") for (int m = 0; m < 4; ++m) _Pragma("unroll") for (int k = 0; k < 2; ++k) dst[m][k] = *(const LAS bf16x8*)(lds + PG8_SA(b, h) + aoff + m * 2048 + k * 1024); } while (0)
; #define PG8_LDB(dst, b, h) do { _Pragma("unroll") for (int n = 0; n < 2; ++n) _Pragma("unroll") for (int k = 0; k < 2; ++k) dst[n][k] = *(const LAS bf16x8*)(lds + PG8_SB(b, h) + boff + n * 2048 + k * 1024); } while (0)
; #define PG8_MMA(ai, bj, At, Bt) do { __builtin_amdgcn_s_setprio(1); _Pragma("unroll") for (int m = 0; m < 4; ++m) _Pragma("unroll") for (int n = 0; n < 2; ++n) _Pragma("unroll") for (int k = 0; k < 2; ++k) \
;         acc[ai][bj][m][n] = __builtin_amdgcn_mfma_f32_16x16x32_bf16(Bt[n][k], At[m][k], acc[ai][bj][m][n], 0, 0, 0); __builtin_amdgcn_s_setprio(0); } while (0)
; #define PG8_WAIT_V(n) asm volatile("s_waitcnt vmcnt(" #n ")" ::: "memory")
; #define PG8_WAIT_L(n) asm volatile("s_waitcnt lgkmcnt(" #n ")" ::: "memory")
; #define PG8_BAR __builtin_amdgcn_s_barrier()
; #define PG8_SCHED __builtin_amdgcn_sched_barrier(0)
; template <class Epi, class Sched, bool ALIGN_EPI, bool LAST_FUSED = false, bool PERM = false, bool CARRY = false>
; __device__ __forceinline__ void gemm_phase(LAS unsigned char* lds, const int tid, const int K, const int lda, const int ldb, const Sched& S, const Epi& E) {
;     ...
;             PG8_WAIT_V(8); PG8_WAIT_L(0); PG8_BAR; PG8_MMA(1, 0, At, B0); PG8_MMA(1, 1, At, B1); PG8_BAR; PG8_SCHED;
;             PG8_LDB(B0, 1, 0); PG8_LDB(B1, 1, 1); PG8_SCHED; PG8_LDA(At, 1, 0); PG8_STAGE(PG8_SA(0, 1), a2 + hstepA, voffA);
;             PG8_WAIT_V(8); PG8_WAIT_L(0); PG8_BAR; PG8_MMA(0, 0, At, B0); PG8_MMA(0, 1, At, B1); PG8_BAR; PG8_SCHED;
;             PG8_LDA(At, 1, 1); PG8_STAGE(PG8_SB(1, 0), b3, voffB); PG8_STAGE(PG8_SB(1, 1), b3 + hstepB, voffB); PG8_STAGE(PG8_SA(1, 0), a3, voffA);
;             PG8_WAIT_V(8); PG8_WAIT_L(0); PG8_BAR; PG8_MMA(1, 0, At, B0); PG8_MMA(1, 1, At, B1); PG8_BAR; PG8_SCHED;
	s_setprio 1
	v_mfma_f32_16x16x32_bf16 v[62:65], v[140:143], v[186:189], v[62:65]
	v_mfma_f32_16x16x32_bf16 v[58:61], v[162:165], v[186:189], v[58:61]
	v_mfma_f32_16x16x32_bf16 v[46:49], v[140:143], v[194:197], v[46:49]
	v_mfma_f32_16x16x32_bf16 v[42:45], v[162:165], v[194:197], v[42:45]
	v_mfma_f32_16x16x32_bf16 v[30:33], v[140:143], v[202:205], v[30:33]
	v_mfma_f32_16x16x32_bf16 v[26:29], v[162:165], v[202:205], v[26:29]
	v_mfma_f32_16x16x32_bf16 v[14:17], v[140:143], v[210:213], v[14:17]
	v_mfma_f32_16x16x32_bf16 v[10:13], v[162:165], v[210:213], v[10:13]
	v_mfma_f32_16x16x32_bf16 v[62:65], v[144:147], v[190:193], v[62:65]
	v_mfma_f32_16x16x32_bf16 v[58:61], v[166:169], v[190:193], v[58:61]
	v_mfma_f32_16x16x32_bf16 v[46:49], v[144:147], v[198:201], v[46:49]
	v_mfma_f32_16x16x32_bf16 v[42:45], v[166:169], v[198:201], v[42:45]
	v_mfma_f32_16x16x32_bf16 v[30:33], v[144:147], v[206:209], v[30:33]
	v_mfma_f32_16x16x32_bf16 v[26:29], v[166:169], v[206:209], v[26:29]
	v_mfma_f32_16x16x32_bf16 v[14:17], v[144:147], v[214:217], v[14:17]
	v_mfma_f32_16x16x32_bf16 v[10:13], v[166:169], v[214:217], v[10:13]
	s_setprio 0
	s_setprio 1
	v_mfma_f32_16x16x32_bf16 v[54:57], v[170:173], v[186:189], v[54:57]
	v_mfma_f32_16x16x32_bf16 v[50:53], v[178:181], v[186:189], v[50:53]
	v_mfma_f32_16x16x32_bf16 v[38:41], v[170:173], v[194:197], v[38:41]
	v_mfma_f32_16x16x32_bf16 v[34:37], v[178:181], v[194:197], v[34:37]
	v_mfma_f32_16x16x32_bf16 v[22:25], v[170:173], v[202:205], v[22:25]
	v_mfma_f32_16x16x32_bf16 v[18:21], v[178:181], v[202:205], v[18:21]
	v_mfma_f32_16x16x32_bf16 v[6:9], v[170:173], v[210:213], v[6:9]
	v_mfma_f32_16x16x32_bf16 v[2:5], v[178:181], v[210:213], v[2:5]
	v_mfma_f32_16x16x32_bf16 v[54:57], v[174:177], v[190:193], v[54:57]
	v_mfma_f32_16x16x32_bf16 v[50:53], v[182:185], v[190:193], v[50:53]
	v_mfma_f32_16x16x32_bf16 v[38:41], v[174:177], v[198:201], v[38:41]
	v_mfma_f32_16x16x32_bf16 v[34:37], v[182:185], v[198:201], v[34:37]
	v_mfma_f32_16x16x32_bf16 v[22:25], v[174:177], v[206:209], v[22:25]
	v_mfma_f32_16x16x32_bf16 v[18:21], v[182:185], v[206:209], v[18:21]
	v_mfma_f32_16x16x32_bf16 v[6:9], v[174:177], v[214:217], v[6:9]
	v_mfma_f32_16x16x32_bf16 v[2:5], v[182:185], v[214:217], v[2:5]
	s_barrier
	s_setprio 0
	s_add_i32 s31, 0, 0x18000
	v_add_u32_e32 v150, s31, v160
	s_add_i32 s35, 0, 0x1c000
	ds_read_b128 v[140:143], v150
	ds_read_b128 v[144:147], v150 offset:1024
	ds_read_b128 v[162:165], v150 offset:2048
	ds_read_b128 v[166:169], v150 offset:3072
	v_add_u32_e32 v150, s35, v160
	ds_read_b128 v[170:173], v150
	ds_read_b128 v[174:177], v150 offset:1024
	ds_read_b128 v[178:181], v150 offset:2048
	ds_read_b128 v[182:185], v150 offset:3072
	s_add_u32 s28, s40, 0x80000
	s_addc_u32 s29, s41, 0
	s_mov_b32 m0, s56
	v_lshl_add_u64 v[220:221], s[28:29], 0, v[134:135]
	ds_read_b128 v[186:189], v161 offset:32768
	ds_read_b128 v[190:193], v161 offset:33792
	ds_read_b128 v[194:197], v161 offset:34816
	ds_read_b128 v[198:201], v161 offset:35840
	ds_read_b128 v[202:205], v161 offset:36864
	ds_read_b128 v[206:209], v161 offset:37888
	ds_read_b128 v[210:213], v161 offset:38912
	ds_read_b128 v[214:217], v161 offset:39936
	global_load_lds_dwordx4 v[220:221], off
	v_lshl_add_u64 v[220:221], s[28:29], 0, v[132:133]
	s_mov_b32 m0, s57
	s_nop 0
	global_load_lds_dwordx4 v[220:221], off
	s_waitcnt vmcnt(8)
	s_waitcnt lgkmcnt(0)
	s_barrier
	s_setprio 1
	v_mfma_f32_16x16x32_bf16 v[126:129], v[140:143], v[186:189], v[126:129]
	v_mfma_f32_16x16x32_bf16 v[122:125], v[162:165], v[186:189], v[122:125]
	v_mfma_f32_16x16x32_bf16 v[110:113], v[140:143], v[194:197], v[110:113]
	v_mfma_f32_16x16x32_bf16 v[106:109], v[162:165], v[194:197], v[106:109]
	v_mfma_f32_16x16x32_bf16 v[94:97], v[140:143], v[202:205], v[94:97]
	v_mfma_f32_16x16x32_bf16 v[90:93], v[162:165], v[202:205], v[90:93]
	v_mfma_f32_16x16x32_bf16 v[78:81], v[140:143], v[210:213], v[78:81]
	v_mfma_f32_16x16x32_bf16 v[74:77], v[162:165], v[210:213], v[74:77]
	v_mfma_f32_16x16x32_bf16 v[126:129], v[144:147], v[190:193], v[126:129]
	v_mfma_f32_16x16x32_bf16 v[122:125], v[166:169], v[190:193], v[122:125]
	v_mfma_f32_16x16x32_bf16 v[110:113], v[144:147], v[198:201], v[110:113]
	v_mfma_f32_16x16x32_bf16 v[106:109], v[166:169], v[198:201], v[106:109]
	v_mfma_f32_16x16x32_bf16 v[94:97], v[144:147], v[206:209], v[94:97]
	v_mfma_f32_16x16x32_bf16 v[90:93], v[166:169], v[206:209], v[90:93]
	v_mfma_f32_16x16x32_bf16 v[78:81], v[144:147], v[214:217], v[78:81]
	v_mfma_f32_16x16x32_bf16 v[74:77], v[166:169], v[214:217], v[74:77]
	s_setprio 0
	s_setprio 1
	v_mfma_f32_16x16x32_bf16 v[118:121], v[170:173], v[186:189], v[118:121]
	v_mfma_f32_16x16x32_bf16 v[114:117], v[178:181], v[186:189], v[114:117]
	v_mfma_f32_16x16x32_bf16 v[102:105], v[170:173], v[194:197], v[102:105]
	v_mfma_f32_16x16x32_bf16 v[98:101], v[178:181], v[194:197], v[98:101]
	v_mfma_f32_16x16x32_bf16 v[86:89], v[170:173], v[202:205], v[86:89]
	v_mfma_f32_16x16x32_bf16 v[82:85], v[178:181], v[202:205], v[82:85]
	v_mfma_f32_16x16x32_bf16 v[70:73], v[170:173], v[210:213], v[70:73]
	v_mfma_f32_16x16x32_bf16 v[66:69], v[178:181], v[210:213], v[66:69]
	v_mfma_f32_16x16x32_bf16 v[118:121], v[174:177], v[190:193], v[118:121]
	v_mfma_f32_16x16x32_bf16 v[114:117], v[182:185], v[190:193], v[114:117]
	v_mfma_f32_16x16x32_bf16 v[102:105], v[174:177], v[198:201], v[102:105]
	v_mfma_f32_16x16x32_bf16 v[98:101], v[182:185], v[198:201], v[98:101]
	v_mfma_f32_16x16x32_bf16 v[86:89], v[174:177], v[206:209], v[86:89]
	v_mfma_f32_16x16x32_bf16 v[82:85], v[182:185], v[206:209], v[82:85]
	v_mfma_f32_16x16x32_bf16 v[70:73], v[174:177], v[214:217], v[70:73]
	v_mfma_f32_16x16x32_bf16 v[66:69], v[182:185], v[214:217], v[66:69]
	s_barrier
; #define PG8_STAGE(bufoff, gbase, voff) do { _Pragma("unroll") for (int _i = 0; _i < 2; ++_i) \
;         __builtin_amdgcn_global_load_lds((const unsigned*)((const char*)(gbase) + (voff)[_i]), (LAS unsigned*)(lds + (bufoff) + ldsw + _i * 8192), 16, 0, 0); } while (0)
; #define PG8_LDA(dst, b, h) do { _Pragma("unroll") for (int m = 0; m < 4; ++m) _Pragma("unroll") for (int k = 0; k < 2; ++k) dst[m][k] = *(const LAS bf16x8*)(lds + PG8_SA(b, h) + aoff + m * 2048 + k * 1024); } while (0)
; #define PG8_MMA(ai, bj, At, Bt) do { __builtin_amdgcn_s_setprio(1); _Pragma("unroll") for (int m = 0; m < 4; ++m) _Pragma("unroll") for (int n = 0; n < 2; ++n) _Pragma("unroll") for (int k = 0; k < 2; ++k) \
;         acc[ai][bj][m][n] = __builtin_amdgcn_mfma_f32_16x16x32_bf16(Bt[n][k], At[m][k], acc[ai][bj][m][n], 0, 0, 0); __builtin_amdgcn_s_setprio(0); } while (0)
; #define PG8_WAIT_V(n) asm volatile("s_waitcnt vmcnt(" #n ")" ::: "memory")
; #define PG8_WAIT_L(n) asm volatile("s_waitcnt lgkmcnt(" #n ")" ::: "memory")
; #define PG8_BAR __builtin_amdgcn_s_barrier()
; #define PG8_SCHED __builtin_amdgcn_sched_barrier(0)
; template <class Epi, class Sched, bool ALIGN_EPI, bool LAST_FUSED = false, bool PERM = false, bool CARRY = false>
; __device__ __forceinline__ void gemm_phase(LAS unsigned char* lds, const int tid, const int K, const int lda, const int ldb, const Sched& S, const Epi& E) {
;     ...
;             PG8_LDA(At, 1, 1); PG8_STAGE(PG8_SB(1, 0), b3, voffB); PG8_STAGE(PG8_SB(1, 1), b3 + hstepB, voffB); PG8_STAGE(PG8_SA(1, 0), a3, voffA);
;             PG8_WAIT_V(8); PG8_WAIT_L(0); PG8_BAR; PG8_MMA(1, 0, At, B0); PG8_MMA(1, 1, At, B1); PG8_BAR; PG8_SCHED;
;         }
;         if constexpr (ALIGN_EPI) { if (wr == 0) PG8_BAR; }
	s_setprio 0
	s_add_i32 s28, s31, s52
	v_lshl_add_u64 v[148:149], v[148:149], 0, s[68:69]
	s_mov_b32 m0, s28
	ds_read_b128 v[186:189], v161 offset:49152
	ds_read_b128 v[190:193], v161 offset:50176
	ds_read_b128 v[194:197], v161 offset:51200
	ds_read_b128 v[198:201], v161 offset:52224
	ds_read_b128 v[202:205], v161 offset:53248
	ds_read_b128 v[206:209], v161 offset:54272
	ds_read_b128 v[210:213], v161 offset:55296
	ds_read_b128 v[214:217], v161 offset:56320
	global_load_lds_dwordx4 v[148:149], off
	s_add_i32 m0, s28, 0x2000
	s_add_u32 s28, s36, 0x80080
	v_lshl_add_u64 v[148:149], v[152:153], 0, s[68:69]
	s_addc_u32 s29, s37, 0
	s_add_i32 s31, s35, s52
	global_load_lds_dwordx4 v[148:149], off
	v_lshl_add_u64 v[148:149], s[28:29], 0, v[0:1]
	s_mov_b32 m0, s31
	s_nop 0
	global_load_lds_dwordx4 v[148:149], off
	v_lshl_add_u64 v[148:149], s[28:29], 0, v[130:131]
	s_add_i32 m0, s31, 0x2000
	s_nop 0
	global_load_lds_dwordx4 v[148:149], off
	v_lshl_add_u64 v[148:149], v[156:157], 0, s[68:69]
	s_mov_b32 m0, s59
	s_nop 0
	global_load_lds_dwordx4 v[148:149], off
	v_lshl_add_u64 v[148:149], v[218:219], 0, s[68:69]
	s_mov_b32 m0, s60
	s_nop 0
	global_load_lds_dwordx4 v[148:149], off
	s_waitcnt vmcnt(8)
	s_waitcnt lgkmcnt(0)
	s_barrier
	s_setprio 1
	v_mfma_f32_16x16x32_bf16 v[62:65], v[140:143], v[186:189], v[62:65]
	v_mfma_f32_16x16x32_bf16 v[58:61], v[162:165], v[186:189], v[58:61]
	v_mfma_f32_16x16x32_bf16 v[46:49], v[140:143], v[194:197], v[46:49]
	v_mfma_f32_16x16x32_bf16 v[42:45], v[162:165], v[194:197], v[42:45]
	v_mfma_f32_16x16x32_bf16 v[30:33], v[140:143], v[202:205], v[30:33]
	v_mfma_f32_16x16x32_bf16 v[26:29], v[162:165], v[202:205], v[26:29]
	v_mfma_f32_16x16x32_bf16 v[14:17], v[140:143], v[210:213], v[14:17]
	v_mfma_f32_16x16x32_bf16 v[10:13], v[162:165], v[210:213], v[10:13]
	v_mfma_f32_16x16x32_bf16 v[62:65], v[144:147], v[190:193], v[62:65]
	v_mfma_f32_16x16x32_bf16 v[58:61], v[166:169], v[190:193], v[58:61]
	v_mfma_f32_16x16x32_bf16 v[46:49], v[144:147], v[198:201], v[46:49]
	v_mfma_f32_16x16x32_bf16 v[42:45], v[166:169], v[198:201], v[42:45]
	v_mfma_f32_16x16x32_bf16 v[30:33], v[144:147], v[206:209], v[30:33]
	v_mfma_f32_16x16x32_bf16 v[26:29], v[166:169], v[206:209], v[26:29]
	v_mfma_f32_16x16x32_bf16 v[14:17], v[144:147], v[214:217], v[14:17]
	v_mfma_f32_16x16x32_bf16 v[10:13], v[166:169], v[214:217], v[10:13]
	s_setprio 0
	s_setprio 1
	v_mfma_f32_16x16x32_bf16 v[54:57], v[170:173], v[186:189], v[54:57]
	v_mfma_f32_16x16x32_bf16 v[50:53], v[178:181], v[186:189], v[50:53]
	v_mfma_f32_16x16x32_bf16 v[38:41], v[170:173], v[194:197], v[38:41]
	v_mfma_f32_16x16x32_bf16 v[34:37], v[178:181], v[194:197], v[34:37]
	v_mfma_f32_16x16x32_bf16 v[22:25], v[170:173], v[202:205], v[22:25]
	v_mfma_f32_16x16x32_bf16 v[18:21], v[178:181], v[202:205], v[18:21]
	v_mfma_f32_16x16x32_bf16 v[6:9], v[170:173], v[210:213], v[6:9]
	v_mfma_f32_16x16x32_bf16 v[2:5], v[178:181], v[210:213], v[2:5]
	v_mfma_f32_16x16x32_bf16 v[54:57], v[174:177], v[190:193], v[54:57]
	v_mfma_f32_16x16x32_bf16 v[50:53], v[182:185], v[190:193], v[50:53]
	v_mfma_f32_16x16x32_bf16 v[38:41], v[174:177], v[198:201], v[38:41]
	v_mfma_f32_16x16x32_bf16 v[34:37], v[182:185], v[198:201], v[34:37]
	v_mfma_f32_16x16x32_bf16 v[22:25], v[174:177], v[206:209], v[22:25]
	v_mfma_f32_16x16x32_bf16 v[18:21], v[182:185], v[206:209], v[18:21]
	v_mfma_f32_16x16x32_bf16 v[6:9], v[174:177], v[214:217], v[6:9]
	v_mfma_f32_16x16x32_bf16 v[2:5], v[182:185], v[214:217], v[2:5]
	s_barrier
	s_setprio 0
	s_add_i32 s24, s24, 2
	s_add_u32 s4, s4, 0x100
	s_addc_u32 s5, s5, 0
	s_add_u32 s22, s22, 0x100
	s_addc_u32 s23, s23, 0
	s_cmp_gt_u32 s24, 29
	s_cbranch_scc0 .LBB0_512
	s_and_b64 vcc, exec, s[78:79]
	s_cbranch_vccz .LBB0_515
	s_barrier

; #define PG8_STAGE(bufoff, gbase, voff) do { _Pragma("unroll") for (int _i = 0; _i < 2; ++_i) \
;         __builtin_amdgcn_global_load_lds((const unsigned*)((const char*)(gbase) + (voff)[_i]), (LAS unsigned*)(lds + (bufoff) + ldsw + _i * 8192), 16, 0, 0); } while (0)
; #define PG8_LDA(dst, b, h) do { _Pragma("unroll") for (int m = 0; m < 4; ++m) _Pragma("unroll") for (int k = 0; k < 2; ++k) dst[m][k] = *(const LAS bf16x8*)(lds + PG8_SA(b, h) + aoff + m * 2048 + k * 1024); } while (0)
; #define PG8_LDB(dst, b, h) do { _Pragma("unroll") for (int n = 0; n < 2; ++n) _Pragma("unroll") for (int k = 0; k < 2; ++k) dst[n][k] = *(const LAS bf16x8*)(lds + PG8_SB(b, h) + boff + n * 2048 + k * 1024); } while (0)
; #define PG8_WAIT_V(n) asm volatile("s_waitcnt vmcnt(" #n ")" ::: "memory")
; template <class Epi, class Sched, bool ALIGN_EPI, bool LAST_FUSED = false, bool PERM = false, bool CARRY = false>
; __device__ __forceinline__ void gemm_phase(LAS unsigned char* lds, const int tid, const int K, const int lda, const int ldb, const Sched& S, const Epi& E) {
;     ...
;         const bool has_next = S.next(KD_IDX(ui + 1), nxt);
;         const char* nA = has_next ? nxt.a : cA; const char* nB = has_next ? nxt.b : cB; const int nt = cur.nt;
; #pragma unroll 1
;         for (int t = 0; t < nt; t += 2) {
;             const bool last = (t == nt - 2);
;             const char* a1 = cA + (size_t)(t + 1) * kstep;
;             const char* a2 = last ? nA : cA + (size_t)(t + 2) * kstep; const char* b2 = last ? nB : cB + (size_t)(t + 2) * kstep;
;             const char* a3 = a2 + kstep; const char* b3 = b2 + kstep;
;             PG8_LDB(B0, 0, 0); PG8_LDB(B1, 0, 1); PG8_SCHED; PG8_LDA(At, 0, 0); PG8_STAGE(PG8_SA(1, 1), a1 + hstepA, voffA);
;             PG8_WAIT_V(8); PG8_WAIT_L(0); PG8_BAR; PG8_MMA(0, 0, At, B0); PG8_MMA(0, 1, At, B1); PG8_BAR; PG8_SCHED;
;             PG8_LDA(At, 0, 1); PG8_STAGE(PG8_SB(0, 0), b2, voffB); PG8_STAGE(PG8_SB(0, 1), b2 + hstepB, voffB); PG8_STAGE(PG8_SA(0, 0), a2, voffA);
;             PG8_WAIT_V(8); PG8_WAIT_L(0); PG8_BAR; PG8_MMA(1, 0, At, B0); PG8_MMA(1, 1, At, B1); PG8_BAR; PG8_SCHED;
;             PG8_LDB(B0, 1, 0); PG8_LDB(B1, 1, 1); PG8_SCHED; PG8_LDA(At, 1, 0); PG8_STAGE(PG8_SA(0, 1), a2 + hstepA, voffA);
;             PG8_WAIT_V(8); PG8_WAIT_L(0); PG8_BAR; PG8_MMA(0, 0, At, B0); PG8_MMA(0, 1, At, B1); PG8_BAR; PG8_SCHED;
.LBB0_601:
	s_add_u32 s23, s30, s15
	s_addc_u32 s27, s31, 0
	s_add_u32 s35, s23, 0x100
	s_addc_u32 s42, s27, 0
	s_and_b64 s[28:29], s[40:41], exec
	s_cselect_b32 s47, s17, s42
	s_cselect_b32 s46, s16, s35
	s_add_u32 s15, s36, s15
	s_addc_u32 s28, s37, 0
	s_add_u32 s15, s15, 0x100
	s_addc_u32 s35, s28, 0
	s_add_i32 s75, 0, 0x10000
	s_and_b64 s[28:29], s[40:41], exec
	s_cselect_b32 s49, s19, s35
	s_cselect_b32 s48, s18, s15
	s_add_i32 s41, 0, 0x14000
	s_add_u32 s52, s23, 0x80080
	s_addc_u32 s53, s27, 0
	s_add_i32 s45, s75, s59
	s_add_i32 m0, s60, 0xc000
	s_add_i32 s77, s60, 0xe000
	s_add_i32 s29, s45, 0x2000
	s_add_u32 s50, s48, 0x80000
	v_add_u32_e32 v154, s75, v144
	v_add_u32_e32 v170, s41, v144
	s_addc_u32 s51, s49, 0
	s_add_i32 s44, s41, s59
	ds_read_b128 v[136:139], v154
	ds_read_b128 v[146:149], v154 offset:1024
	ds_read_b128 v[150:153], v154 offset:2048
	ds_read_b128 v[154:157], v154 offset:3072
	ds_read_b128 v[158:161], v170
	ds_read_b128 v[162:165], v170 offset:1024
	ds_read_b128 v[166:169], v170 offset:2048
	ds_read_b128 v[170:173], v170 offset:3072
	s_add_i32 s35, s44, 0x2000
	s_add_i32 s28, 0, 0x18000
	s_add_i32 s27, 0, 0x1c000
	s_add_u32 s42, s46, 0x80000
	s_addc_u32 s43, s47, 0
	s_add_i32 s23, s28, s59
	s_add_i32 s15, s23, 0x2000
	s_add_u32 s40, s48, 0x80080
	s_addc_u32 s41, s49, 0
	s_add_i32 s76, s27, s59
	s_add_i32 s75, s76, 0x2000
	v_lshl_add_u64 v[206:207], s[52:53], 0, v[134:135]
	ds_read_b128 v[174:177], v145
	ds_read_b128 v[178:181], v145 offset:1024
	ds_read_b128 v[182:185], v145 offset:2048
	ds_read_b128 v[186:189], v145 offset:3072
	ds_read_b128 v[190:193], v145 offset:4096
	ds_read_b128 v[194:197], v145 offset:5120
	ds_read_b128 v[198:201], v145 offset:6144
	ds_read_b128 v[202:205], v145 offset:7168
	global_load_lds_dwordx4 v[206:207], off
	v_lshl_add_u64 v[206:207], s[52:53], 0, v[132:133]
	s_mov_b32 m0, s77
	s_nop 0
	global_load_lds_dwordx4 v[206:207], off
	s_waitcnt vmcnt(8)
	s_waitcnt lgkmcnt(0)
	s_barrier
	s_setprio 1
	v_mfma_f32_16x16x32_bf16 v[126:129], v[136:139], v[174:177], v[126:129]
	v_mfma_f32_16x16x32_bf16 v[122:125], v[150:153], v[174:177], v[122:125]
	v_mfma_f32_16x16x32_bf16 v[110:113], v[136:139], v[182:185], v[110:113]
	v_mfma_f32_16x16x32_bf16 v[106:109], v[150:153], v[182:185], v[106:109]
	v_mfma_f32_16x16x32_bf16 v[94:97], v[136:139], v[190:193], v[94:97]
	v_mfma_f32_16x16x32_bf16 v[90:93], v[150:153], v[190:193], v[90:93]
	v_mfma_f32_16x16x32_bf16 v[78:81], v[136:139], v[198:201], v[78:81]
	v_mfma_f32_16x16x32_bf16 v[74:77], v[150:153], v[198:201], v[74:77]
	v_mfma_f32_16x16x32_bf16 v[126:129], v[146:149], v[178:181], v[126:129]
	v_mfma_f32_16x16x32_bf16 v[122:125], v[154:157], v[178:181], v[122:125]
	v_mfma_f32_16x16x32_bf16 v[110:113], v[146:149], v[186:189], v[110:113]
	v_mfma_f32_16x16x32_bf16 v[106:109], v[154:157], v[186:189], v[106:109]
	v_mfma_f32_16x16x32_bf16 v[94:97], v[146:149], v[194:197], v[94:97]
	v_mfma_f32_16x16x32_bf16 v[90:93], v[154:157], v[194:197], v[90:93]
	v_mfma_f32_16x16x32_bf16 v[78:81], v[146:149], v[202:205], v[78:81]
	v_mfma_f32_16x16x32_bf16 v[74:77], v[154:157], v[202:205], v[74:77]
	s_setprio 0
	s_setprio 1
	v_mfma_f32_16x16x32_bf16 v[118:121], v[158:161], v[174:177], v[118:121]
	v_mfma_f32_16x16x32_bf16 v[114:117], v[166:169], v[174:177], v[114:117]
	v_mfma_f32_16x16x32_bf16 v[102:105], v[158:161], v[182:185], v[102:105]
	v_mfma_f32_16x16x32_bf16 v[98:101], v[166:169], v[182:185], v[98:101]
	v_mfma_f32_16x16x32_bf16 v[86:89], v[158:161], v[190:193], v[86:89]
	v_mfma_f32_16x16x32_bf16 v[82:85], v[166:169], v[190:193], v[82:85]
	v_mfma_f32_16x16x32_bf16 v[70:73], v[158:161], v[198:201], v[70:73]
	v_mfma_f32_16x16x32_bf16 v[66:69], v[166:169], v[198:201], v[66:69]
	v_mfma_f32_16x16x32_bf16 v[118:121], v[162:165], v[178:181], v[118:121]
	v_mfma_f32_16x16x32_bf16 v[114:117], v[170:173], v[178:181], v[114:117]
	v_mfma_f32_16x16x32_bf16 v[102:105], v[162:165], v[186:189], v[102:105]
	v_mfma_f32_16x16x32_bf16 v[98:101], v[170:173], v[186:189], v[98:101]
	v_mfma_f32_16x16x32_bf16 v[86:89], v[162:165], v[194:197], v[86:89]
	v_mfma_f32_16x16x32_bf16 v[82:85], v[170:173], v[194:197], v[82:85]
	v_mfma_f32_16x16x32_bf16 v[70:73], v[162:165], v[202:205], v[70:73]
	v_mfma_f32_16x16x32_bf16 v[66:69], v[170:173], v[202:205], v[66:69]
	s_barrier
	s_setprio 0
	s_mov_b32 m0, s45
	v_lshl_add_u64 v[206:207], s[48:49], 0, v[0:1]
	ds_read_b128 v[174:177], v145 offset:16384
	ds_read_b128 v[178:181], v145 offset:17408
	ds_read_b128 v[182:185], v145 offset:18432
	ds_read_b128 v[186:189], v145 offset:19456
	ds_read_b128 v[190:193], v145 offset:20480
	ds_read_b128 v[194:197], v145 offset:21504
	ds_read_b128 v[198:201], v145 offset:22528
	ds_read_b128 v[202:205], v145 offset:23552
	global_load_lds_dwordx4 v[206:207], off
	v_lshl_add_u64 v[208:209], s[48:49], 0, v[130:131]
	s_mov_b32 m0, s29
	v_lshl_add_u64 v[210:211], s[50:51], 0, v[0:1]
	global_load_lds_dwordx4 v[208:209], off
	s_mov_b32 m0, s44
	v_lshl_add_u64 v[212:213], s[46:47], 0, v[132:133]
	global_load_lds_dwordx4 v[210:211], off
	v_lshl_add_u64 v[210:211], s[50:51], 0, v[130:131]
	s_mov_b32 m0, s35
	s_nop 0
	global_load_lds_dwordx4 v[210:211], off
	v_lshl_add_u64 v[210:211], s[46:47], 0, v[134:135]
	s_mov_b32 m0, s60
	s_nop 0
	global_load_lds_dwordx4 v[210:211], off
	s_mov_b32 m0, s61
	s_nop 0
	global_load_lds_dwordx4 v[212:213], off
	s_waitcnt vmcnt(8)
	s_waitcnt lgkmcnt(0)
	s_barrier
; #define PG8_STAGE(bufoff, gbase, voff) do { _Pragma("unroll") for (int _i = 0; _i < 2; ++_i) \
;         __builtin_amdgcn_global_load_lds((const unsigned*)((const char*)(gbase) + (voff)[_i]), (LAS unsigned*)(lds + (bufoff) + ldsw + _i * 8192), 16, 0, 0); } while (0)
; #define PG8_LDA(dst, b, h) do { _Pragma("unroll") for (int m = 0; m < 4; ++m) _Pragma("unroll") for (int k = 0; k < 2; ++k) dst[m][k] = *(const LAS bf16x8*)(lds + PG8_SA(b, h) + aoff + m * 2048 + k * 1024); } while (0)
; #define PG8_LDB(dst, b, h) do { _Pragma("unroll") for (int n = 0; n < 2; ++n) _Pragma("unroll") for (int k = 0; k < 2; ++k) dst[n][k] = *(const LAS bf16x8*)(lds + PG8_SB(b, h) + boff + n * 2048 + k * 1024); } while (0)
; #define PG8_MMA(ai, bj, At, Bt) do { __builtin_amdgcn_s_setprio(1); _Pragma("unroll") for (int m = 0; m < 4; ++m) _Pragma("unroll") for (int n = 0; n < 2; ++n) _Pragma("unroll") for (int k = 0; k < 2; ++k) \
;         acc[ai][bj][m][n] = __builtin_amdgcn_mfma_f32_16x16x32_bf16(Bt[n][k], At[m][k], acc[ai][bj][m][n], 0, 0, 0); __builtin_amdgcn_s_setprio(0); } while (0)
; #define PG8_WAIT_V(n) asm volatile("s_waitcnt vmcnt(" #n ")" ::: "memory")
; #define PG8_WAIT_L(n) asm volatile("s_waitcnt lgkmcnt(" #n ")" ::: "memory")
; #define PG8_BAR __builtin_amdgcn_s_barrier()
; #define PG8_SCHED __builtin_amdgcn_sched_barrier(0)
; template <class Epi, class Sched, bool ALIGN_EPI, bool LAST_FUSED = false, bool PERM = false, bool CARRY = false>
; __device__ __forceinline__ void gemm_phase(LAS unsigned char* lds, const int tid, const int K, const int lda, const int ldb, const Sched& S, const Epi& E) {
;     ...
;             PG8_WAIT_V(8); PG8_WAIT_L(0); PG8_BAR; PG8_MMA(1, 0, At, B0); PG8_MMA(1, 1, At, B1); PG8_BAR; PG8_SCHED;
;             PG8_LDB(B0, 1, 0); PG8_LDB(B1, 1, 1); PG8_SCHED; PG8_LDA(At, 1, 0); PG8_STAGE(PG8_SA(0, 1), a2 + hstepA, voffA);
;             PG8_WAIT_V(8); PG8_WAIT_L(0); PG8_BAR; PG8_MMA(0, 0, At, B0); PG8_MMA(0, 1, At, B1); PG8_BAR; PG8_SCHED;
;             PG8_LDA(At, 1, 1); PG8_STAGE(PG8_SB(1, 0), b3, voffB); PG8_STAGE(PG8_SB(1, 1), b3 + hstepB, voffB); PG8_STAGE(PG8_SA(1, 0), a3, voffA);
;             PG8_WAIT_V(8); PG8_WAIT_L(0); PG8_BAR; PG8_MMA(1, 0, At, B0); PG8_MMA(1, 1, At, B1); PG8_BAR; PG8_SCHED;
	s_setprio 1
	v_mfma_f32_16x16x32_bf16 v[62:65], v[136:139], v[174:177], v[62:65]
	v_mfma_f32_16x16x32_bf16 v[58:61], v[150:153], v[174:177], v[58:61]
	v_mfma_f32_16x16x32_bf16 v[46:49], v[136:139], v[182:185], v[46:49]
	v_mfma_f32_16x16x32_bf16 v[42:45], v[150:153], v[182:185], v[42:45]
	v_mfma_f32_16x16x32_bf16 v[30:33], v[136:139], v[190:193], v[30:33]
	v_mfma_f32_16x16x32_bf16 v[26:29], v[150:153], v[190:193], v[26:29]
	v_mfma_f32_16x16x32_bf16 v[14:17], v[136:139], v[198:201], v[14:17]
	v_mfma_f32_16x16x32_bf16 v[10:13], v[150:153], v[198:201], v[10:13]
	v_mfma_f32_16x16x32_bf16 v[62:65], v[146:149], v[178:181], v[62:65]
	v_mfma_f32_16x16x32_bf16 v[58:61], v[154:157], v[178:181], v[58:61]
	v_mfma_f32_16x16x32_bf16 v[46:49], v[146:149], v[186:189], v[46:49]
	v_mfma_f32_16x16x32_bf16 v[42:45], v[154:157], v[186:189], v[42:45]
	v_mfma_f32_16x16x32_bf16 v[30:33], v[146:149], v[194:197], v[30:33]
	v_mfma_f32_16x16x32_bf16 v[26:29], v[154:157], v[194:197], v[26:29]
	v_mfma_f32_16x16x32_bf16 v[14:17], v[146:149], v[202:205], v[14:17]
	v_mfma_f32_16x16x32_bf16 v[10:13], v[154:157], v[202:205], v[10:13]
	s_setprio 0
	s_setprio 1
	v_mfma_f32_16x16x32_bf16 v[54:57], v[158:161], v[174:177], v[54:57]
	v_mfma_f32_16x16x32_bf16 v[50:53], v[166:169], v[174:177], v[50:53]
	v_mfma_f32_16x16x32_bf16 v[38:41], v[158:161], v[182:185], v[38:41]
	v_mfma_f32_16x16x32_bf16 v[34:37], v[166:169], v[182:185], v[34:37]
	v_mfma_f32_16x16x32_bf16 v[22:25], v[158:161], v[190:193], v[22:25]
	v_mfma_f32_16x16x32_bf16 v[18:21], v[166:169], v[190:193], v[18:21]
	v_mfma_f32_16x16x32_bf16 v[6:9], v[158:161], v[198:201], v[6:9]
	v_mfma_f32_16x16x32_bf16 v[2:5], v[166:169], v[198:201], v[2:5]
	v_mfma_f32_16x16x32_bf16 v[54:57], v[162:165], v[178:181], v[54:57]
	v_mfma_f32_16x16x32_bf16 v[50:53], v[170:173], v[178:181], v[50:53]
	v_mfma_f32_16x16x32_bf16 v[38:41], v[162:165], v[186:189], v[38:41]
	v_mfma_f32_16x16x32_bf16 v[34:37], v[170:173], v[186:189], v[34:37]
	v_mfma_f32_16x16x32_bf16 v[22:25], v[162:165], v[194:197], v[22:25]
	v_mfma_f32_16x16x32_bf16 v[18:21], v[170:173], v[194:197], v[18:21]
	v_mfma_f32_16x16x32_bf16 v[6:9], v[162:165], v[202:205], v[6:9]
	v_mfma_f32_16x16x32_bf16 v[2:5], v[170:173], v[202:205], v[2:5]
	s_barrier
	s_setprio 0
	v_add_u32_e32 v154, s28, v144
	v_add_u32_e32 v170, s27, v144
	ds_read_b128 v[136:139], v154
	ds_read_b128 v[146:149], v154 offset:1024
	ds_read_b128 v[150:153], v154 offset:2048
	ds_read_b128 v[154:157], v154 offset:3072
	ds_read_b128 v[158:161], v170
	ds_read_b128 v[162:165], v170 offset:1024
	ds_read_b128 v[166:169], v170 offset:2048
	ds_read_b128 v[170:173], v170 offset:3072
	s_mov_b32 m0, s62
	v_lshl_add_u64 v[214:215], s[42:43], 0, v[134:135]
	ds_read_b128 v[174:177], v145 offset:32768
	ds_read_b128 v[178:181], v145 offset:33792
	ds_read_b128 v[182:185], v145 offset:34816
	ds_read_b128 v[186:189], v145 offset:35840
	ds_read_b128 v[190:193], v145 offset:36864
	ds_read_b128 v[194:197], v145 offset:37888
	ds_read_b128 v[198:201], v145 offset:38912
	ds_read_b128 v[202:205], v145 offset:39936
	global_load_lds_dwordx4 v[214:215], off
	v_lshl_add_u64 v[214:215], s[42:43], 0, v[132:133]
	s_mov_b32 m0, s63
	s_nop 0
	global_load_lds_dwordx4 v[214:215], off
	s_waitcnt vmcnt(8)
	s_waitcnt lgkmcnt(0)
	s_barrier
	s_setprio 1
	v_mfma_f32_16x16x32_bf16 v[126:129], v[136:139], v[174:177], v[126:129]
	v_mfma_f32_16x16x32_bf16 v[122:125], v[150:153], v[174:177], v[122:125]
	v_mfma_f32_16x16x32_bf16 v[110:113], v[136:139], v[182:185], v[110:113]
	v_mfma_f32_16x16x32_bf16 v[106:109], v[150:153], v[182:185], v[106:109]
	v_mfma_f32_16x16x32_bf16 v[94:97], v[136:139], v[190:193], v[94:97]
	v_mfma_f32_16x16x32_bf16 v[90:93], v[150:153], v[190:193], v[90:93]
	v_mfma_f32_16x16x32_bf16 v[78:81], v[136:139], v[198:201], v[78:81]
	v_mfma_f32_16x16x32_bf16 v[74:77], v[150:153], v[198:201], v[74:77]
	v_mfma_f32_16x16x32_bf16 v[126:129], v[146:149], v[178:181], v[126:129]
	v_mfma_f32_16x16x32_bf16 v[122:125], v[154:157], v[178:181], v[122:125]
	v_mfma_f32_16x16x32_bf16 v[110:113], v[146:149], v[186:189], v[110:113]
	v_mfma_f32_16x16x32_bf16 v[106:109], v[154:157], v[186:189], v[106:109]
	v_mfma_f32_16x16x32_bf16 v[94:97], v[146:149], v[194:197], v[94:97]
	v_mfma_f32_16x16x32_bf16 v[90:93], v[154:157], v[194:197], v[90:93]
	v_mfma_f32_16x16x32_bf16 v[78:81], v[146:149], v[202:205], v[78:81]
	v_mfma_f32_16x16x32_bf16 v[74:77], v[154:157], v[202:205], v[74:77]
	s_setprio 0
	s_setprio 1
	v_mfma_f32_16x16x32_bf16 v[118:121], v[158:161], v[174:177], v[118:121]
	v_mfma_f32_16x16x32_bf16 v[114:117], v[166:169], v[174:177], v[114:117]
	v_mfma_f32_16x16x32_bf16 v[102:105], v[158:161], v[182:185], v[102:105]
	v_mfma_f32_16x16x32_bf16 v[98:101], v[166:169], v[182:185], v[98:101]
	v_mfma_f32_16x16x32_bf16 v[86:89], v[158:161], v[190:193], v[86:89]
	v_mfma_f32_16x16x32_bf16 v[82:85], v[166:169], v[190:193], v[82:85]
	v_mfma_f32_16x16x32_bf16 v[70:73], v[158:161], v[198:201], v[70:73]
	v_mfma_f32_16x16x32_bf16 v[66:69], v[166:169], v[198:201], v[66:69]
	v_mfma_f32_16x16x32_bf16 v[118:121], v[162:165], v[178:181], v[118:121]
	v_mfma_f32_16x16x32_bf16 v[114:117], v[170:173], v[178:181], v[114:117]
	v_mfma_f32_16x16x32_bf16 v[102:105], v[162:165], v[186:189], v[102:105]
	v_mfma_f32_16x16x32_bf16 v[98:101], v[170:173], v[186:189], v[98:101]
	v_mfma_f32_16x16x32_bf16 v[86:89], v[162:165], v[194:197], v[86:89]
	v_mfma_f32_16x16x32_bf16 v[82:85], v[170:173], v[194:197], v[82:85]
	v_mfma_f32_16x16x32_bf16 v[70:73], v[162:165], v[202:205], v[70:73]
	v_mfma_f32_16x16x32_bf16 v[66:69], v[170:173], v[202:205], v[66:69]
	s_barrier
; #define PG8_STAGE(bufoff, gbase, voff) do { _Pragma("unroll") for (int _i = 0; _i < 2; ++_i) \
;         __builtin_amdgcn_global_load_lds((const unsigned*)((const char*)(gbase) + (voff)[_i]), (LAS unsigned*)(lds + (bufoff) + ldsw + _i * 8192), 16, 0, 0); } while (0)
; #define PG8_LDA(dst, b, h) do { _Pragma("unroll") for (int m = 0; m < 4; ++m) _Pragma("unroll") for (int k = 0; k < 2; ++k) dst[m][k] = *(const LAS bf16x8*)(lds + PG8_SA(b, h) + aoff + m * 2048 + k * 1024); } while (0)
; #define PG8_MMA(ai, bj, At, Bt) do { __builtin_amdgcn_s_setprio(1); _Pragma("unroll") for (int m = 0; m < 4; ++m) _Pragma("unroll") for (int n = 0; n < 2; ++n) _Pragma("unroll") for (int k = 0; k < 2; ++k) \
;         acc[ai][bj][m][n] = __builtin_amdgcn_mfma_f32_16x16x32_bf16(Bt[n][k], At[m][k], acc[ai][bj][m][n], 0, 0, 0); __builtin_amdgcn_s_setprio(0); } while (0)
; #define PG8_WAIT_V(n) asm volatile("s_waitcnt vmcnt(" #n ")" ::: "memory")
; #define PG8_WAIT_L(n) asm volatile("s_waitcnt lgkmcnt(" #n ")" ::: "memory")
; #define PG8_BAR __builtin_amdgcn_s_barrier()
; #define PG8_SCHED __builtin_amdgcn_sched_barrier(0)
; template <class Epi, class Sched, bool ALIGN_EPI, bool LAST_FUSED = false, bool PERM = false, bool CARRY = false>
; __device__ __forceinline__ void gemm_phase(LAS unsigned char* lds, const int tid, const int K, const int lda, const int ldb, const Sched& S, const Epi& E) {
;     ...
;             PG8_LDA(At, 1, 1); PG8_STAGE(PG8_SB(1, 0), b3, voffB); PG8_STAGE(PG8_SB(1, 1), b3 + hstepB, voffB); PG8_STAGE(PG8_SA(1, 0), a3, voffA);
;             PG8_WAIT_V(8); PG8_WAIT_L(0); PG8_BAR; PG8_MMA(1, 0, At, B0); PG8_MMA(1, 1, At, B1); PG8_BAR; PG8_SCHED;
;         }
	s_setprio 0
	s_mov_b32 m0, s23
	v_lshl_add_u64 v[206:207], v[206:207], 0, s[68:69]
	ds_read_b128 v[174:177], v145 offset:49152
	ds_read_b128 v[178:181], v145 offset:50176
	ds_read_b128 v[182:185], v145 offset:51200
	ds_read_b128 v[186:189], v145 offset:52224
	ds_read_b128 v[190:193], v145 offset:53248
	ds_read_b128 v[194:197], v145 offset:54272
	ds_read_b128 v[198:201], v145 offset:55296
	ds_read_b128 v[202:205], v145 offset:56320
	global_load_lds_dwordx4 v[206:207], off
	v_lshl_add_u64 v[206:207], v[208:209], 0, s[68:69]
	s_mov_b32 m0, s15
	s_nop 0
	global_load_lds_dwordx4 v[206:207], off
	v_lshl_add_u64 v[206:207], s[40:41], 0, v[0:1]
	s_mov_b32 m0, s76
	s_nop 0
	global_load_lds_dwordx4 v[206:207], off
	v_lshl_add_u64 v[206:207], s[40:41], 0, v[130:131]
	s_mov_b32 m0, s75
	s_nop 0
	global_load_lds_dwordx4 v[206:207], off
	v_lshl_add_u64 v[206:207], v[210:211], 0, s[68:69]
	s_mov_b32 m0, s66
	s_nop 0
	global_load_lds_dwordx4 v[206:207], off
	v_lshl_add_u64 v[206:207], v[212:213], 0, s[68:69]
	s_mov_b32 m0, s67
	s_nop 0
	global_load_lds_dwordx4 v[206:207], off
	s_waitcnt vmcnt(8)
	s_waitcnt lgkmcnt(0)
	s_barrier
	s_setprio 1
	v_mfma_f32_16x16x32_bf16 v[62:65], v[136:139], v[174:177], v[62:65]
	v_mfma_f32_16x16x32_bf16 v[58:61], v[150:153], v[174:177], v[58:61]
	v_mfma_f32_16x16x32_bf16 v[46:49], v[136:139], v[182:185], v[46:49]
	v_mfma_f32_16x16x32_bf16 v[42:45], v[150:153], v[182:185], v[42:45]
	v_mfma_f32_16x16x32_bf16 v[30:33], v[136:139], v[190:193], v[30:33]
	v_mfma_f32_16x16x32_bf16 v[26:29], v[150:153], v[190:193], v[26:29]
	v_mfma_f32_16x16x32_bf16 v[14:17], v[136:139], v[198:201], v[14:17]
	v_mfma_f32_16x16x32_bf16 v[10:13], v[150:153], v[198:201], v[10:13]
	v_mfma_f32_16x16x32_bf16 v[62:65], v[146:149], v[178:181], v[62:65]
	v_mfma_f32_16x16x32_bf16 v[58:61], v[154:157], v[178:181], v[58:61]
	v_mfma_f32_16x16x32_bf16 v[46:49], v[146:149], v[186:189], v[46:49]
	v_mfma_f32_16x16x32_bf16 v[42:45], v[154:157], v[186:189], v[42:45]
	v_mfma_f32_16x16x32_bf16 v[30:33], v[146:149], v[194:197], v[30:33]
	v_mfma_f32_16x16x32_bf16 v[26:29], v[154:157], v[194:197], v[26:29]
	v_mfma_f32_16x16x32_bf16 v[14:17], v[146:149], v[202:205], v[14:17]
	v_mfma_f32_16x16x32_bf16 v[10:13], v[154:157], v[202:205], v[10:13]
	s_setprio 0
	s_setprio 1
	v_mfma_f32_16x16x32_bf16 v[54:57], v[158:161], v[174:177], v[54:57]
	v_mfma_f32_16x16x32_bf16 v[50:53], v[166:169], v[174:177], v[50:53]
	v_mfma_f32_16x16x32_bf16 v[38:41], v[158:161], v[182:185], v[38:41]
	v_mfma_f32_16x16x32_bf16 v[34:37], v[166:169], v[182:185], v[34:37]
	v_mfma_f32_16x16x32_bf16 v[22:25], v[158:161], v[190:193], v[22:25]
	v_mfma_f32_16x16x32_bf16 v[18:21], v[166:169], v[190:193], v[18:21]
	v_mfma_f32_16x16x32_bf16 v[6:9], v[158:161], v[198:201], v[6:9]
	v_mfma_f32_16x16x32_bf16 v[2:5], v[166:169], v[198:201], v[2:5]
	v_mfma_f32_16x16x32_bf16 v[54:57], v[162:165], v[178:181], v[54:57]
	v_mfma_f32_16x16x32_bf16 v[50:53], v[170:173], v[178:181], v[50:53]
	v_mfma_f32_16x16x32_bf16 v[38:41], v[162:165], v[186:189], v[38:41]
	v_mfma_f32_16x16x32_bf16 v[34:37], v[170:173], v[186:189], v[34:37]
	v_mfma_f32_16x16x32_bf16 v[22:25], v[162:165], v[194:197], v[22:25]
	v_mfma_f32_16x16x32_bf16 v[18:21], v[170:173], v[194:197], v[18:21]
	v_mfma_f32_16x16x32_bf16 v[6:9], v[162:165], v[202:205], v[6:9]
	v_mfma_f32_16x16x32_bf16 v[2:5], v[170:173], v[202:205], v[2:5]
	s_barrier
	s_setprio 0
	s_movk_i32 s15, 0x100
	s_andn2_b64 vcc, exec, s[38:39]
	s_mov_b64 s[40:41], -1
	s_mov_b64 s[38:39], 0
	s_cbranch_vccz .LBB0_601
	s_and_b64 vcc, exec, s[12:13]
	s_cbranch_vccz .LBB0_604
	s_barrier

; #define PG8_STAGE(bufoff, gbase, voff) do { _Pragma("unroll") for (int _i = 0; _i < 2; ++_i) \
;         __builtin_amdgcn_global_load_lds((const unsigned*)((const char*)(gbase) + (voff)[_i]), (LAS unsigned*)(lds + (bufoff) + ldsw + _i * 8192), 16, 0, 0); } while (0)
; #define PG8_LDA(dst, b, h) do { _Pragma("unroll") for (int m = 0; m < 4; ++m) _Pragma("unroll") for (int k = 0; k < 2; ++k) dst[m][k] = *(const LAS bf16x8*)(lds + PG8_SA(b, h) + aoff + m * 2048 + k * 1024); } while (0)
; #define PG8_LDB(dst, b, h) do { _Pragma("unroll") for (int n = 0; n < 2; ++n) _Pragma("unroll") for (int k = 0; k < 2; ++k) dst[n][k] = *(const LAS bf16x8*)(lds + PG8_SB(b, h) + boff + n * 2048 + k * 1024); } while (0)
; #define PG8_WAIT_V(n) asm volatile("s_waitcnt vmcnt(" #n ")" ::: "memory")
; template <class Epi, class Sched, bool ALIGN_EPI, bool LAST_FUSED = false, bool PERM = false, bool CARRY = false>
; __device__ __forceinline__ void gemm_phase(LAS unsigned char* lds, const int tid, const int K, const int lda, const int ldb, const Sched& S, const Epi& E) {
;     ...
;         const bool has_next = S.next(KD_IDX(ui + 1), nxt);
;         const char* nA = has_next ? nxt.a : cA; const char* nB = has_next ? nxt.b : cB; const int nt = cur.nt;
; #pragma unroll 1
;         for (int t = 0; t < nt; t += 2) {
;             const bool last = (t == nt - 2);
;             const char* a1 = cA + (size_t)(t + 1) * kstep;
;             const char* a2 = last ? nA : cA + (size_t)(t + 2) * kstep; const char* b2 = last ? nB : cB + (size_t)(t + 2) * kstep;
;             const char* a3 = a2 + kstep; const char* b3 = b2 + kstep;
;             PG8_LDB(B0, 0, 0); PG8_LDB(B1, 0, 1); PG8_SCHED; PG8_LDA(At, 0, 0); PG8_STAGE(PG8_SA(1, 1), a1 + hstepA, voffA);
;             PG8_WAIT_V(8); PG8_WAIT_L(0); PG8_BAR; PG8_MMA(0, 0, At, B0); PG8_MMA(0, 1, At, B1); PG8_BAR; PG8_SCHED;
;             PG8_LDA(At, 0, 1); PG8_STAGE(PG8_SB(0, 0), b2, voffB); PG8_STAGE(PG8_SB(0, 1), b2 + hstepB, voffB); PG8_STAGE(PG8_SA(0, 0), a2, voffA);
;             PG8_WAIT_V(8); PG8_WAIT_L(0); PG8_BAR; PG8_MMA(1, 0, At, B0); PG8_MMA(1, 1, At, B1); PG8_BAR; PG8_SCHED;
;             PG8_LDB(B0, 1, 0); PG8_LDB(B1, 1, 1); PG8_SCHED; PG8_LDA(At, 1, 0); PG8_STAGE(PG8_SA(0, 1), a2 + hstepA, voffA);
;             PG8_WAIT_V(8); PG8_WAIT_L(0); PG8_BAR; PG8_MMA(0, 0, At, B0); PG8_MMA(0, 1, At, B1); PG8_BAR; PG8_SCHED;
.LBB0_622:
	s_add_u32 s48, s30, s24
	s_addc_u32 s49, s31, 0
	s_add_u32 s42, s48, 0x100
	s_addc_u32 s43, s49, 0
	s_and_b64 s[40:41], s[38:39], exec
	s_cselect_b32 s43, s15, s43
	s_cselect_b32 s42, s14, s42
	s_add_u32 s24, s26, s24
	s_addc_u32 s40, s27, 0
	s_add_u32 s24, s24, 0x100
	s_addc_u32 s40, s40, 0
	s_add_i32 s62, 0, 0x10000
	s_and_b64 s[38:39], s[38:39], exec
	s_cselect_b32 s47, s17, s40
	s_cselect_b32 s46, s16, s24
	s_add_i32 s39, 0, 0x14000
	s_add_u32 s64, s48, 0x30080
	s_addc_u32 s65, s49, 0
	s_add_i32 s67, s62, s29
	s_add_i32 m0, s45, 0xc000
	s_add_i32 s66, s45, 0xe000
	s_add_i32 s70, s67, 0x2000
	s_add_u32 s48, s46, 0x10000
	v_add_u32_e32 v152, s62, v140
	v_add_u32_e32 v168, s39, v140
	s_addc_u32 s49, s47, 0
	s_add_i32 s71, s39, s29
	ds_read_b128 v[136:139], v152
	ds_read_b128 v[144:147], v152 offset:1024
	ds_read_b128 v[148:151], v152 offset:2048
	ds_read_b128 v[152:155], v152 offset:3072
	ds_read_b128 v[156:159], v168
	ds_read_b128 v[160:163], v168 offset:1024
	ds_read_b128 v[164:167], v168 offset:2048
	ds_read_b128 v[168:171], v168 offset:3072
	s_add_i32 s74, s71, 0x2000
	s_add_i32 s75, 0, 0x18000
	s_add_i32 s76, 0, 0x1c000
	s_add_u32 s40, s42, 0x30000
	s_addc_u32 s41, s43, 0
	s_add_i32 s61, s75, s29
	s_add_i32 s24, s61, 0x2000
	s_add_u32 s38, s46, 0x10080
	s_addc_u32 s39, s47, 0
	s_add_i32 s63, s76, s29
	s_add_i32 s62, s63, 0x2000
	v_lshl_add_u64 v[204:205], s[64:65], 0, v[130:131]
	ds_read_b128 v[172:175], v143
	ds_read_b128 v[176:179], v143 offset:1024
	ds_read_b128 v[180:183], v143 offset:2048
	ds_read_b128 v[184:187], v143 offset:3072
	ds_read_b128 v[188:191], v143 offset:4096
	ds_read_b128 v[192:195], v143 offset:5120
	ds_read_b128 v[196:199], v143 offset:6144
	ds_read_b128 v[200:203], v143 offset:7168
	global_load_lds_dwordx4 v[204:205], off
	v_lshl_add_u64 v[204:205], s[64:65], 0, v[132:133]
	s_mov_b32 m0, s66
	s_nop 0
	global_load_lds_dwordx4 v[204:205], off
	s_waitcnt vmcnt(8)
	s_waitcnt lgkmcnt(0)
	s_barrier
	s_setprio 1
	v_mfma_f32_16x16x32_bf16 v[126:129], v[136:139], v[172:175], v[126:129]
	v_mfma_f32_16x16x32_bf16 v[122:125], v[148:151], v[172:175], v[122:125]
	v_mfma_f32_16x16x32_bf16 v[118:121], v[136:139], v[180:183], v[118:121]
	v_mfma_f32_16x16x32_bf16 v[114:117], v[148:151], v[180:183], v[114:117]
	v_mfma_f32_16x16x32_bf16 v[110:113], v[136:139], v[188:191], v[110:113]
	v_mfma_f32_16x16x32_bf16 v[106:109], v[148:151], v[188:191], v[106:109]
	v_mfma_f32_16x16x32_bf16 v[102:105], v[136:139], v[196:199], v[102:105]
	v_mfma_f32_16x16x32_bf16 v[98:101], v[148:151], v[196:199], v[98:101]
	v_mfma_f32_16x16x32_bf16 v[126:129], v[144:147], v[176:179], v[126:129]
	v_mfma_f32_16x16x32_bf16 v[122:125], v[152:155], v[176:179], v[122:125]
	v_mfma_f32_16x16x32_bf16 v[118:121], v[144:147], v[184:187], v[118:121]
	v_mfma_f32_16x16x32_bf16 v[114:117], v[152:155], v[184:187], v[114:117]
	v_mfma_f32_16x16x32_bf16 v[110:113], v[144:147], v[192:195], v[110:113]
	v_mfma_f32_16x16x32_bf16 v[106:109], v[152:155], v[192:195], v[106:109]
	v_mfma_f32_16x16x32_bf16 v[102:105], v[144:147], v[200:203], v[102:105]
	v_mfma_f32_16x16x32_bf16 v[98:101], v[152:155], v[200:203], v[98:101]
	s_setprio 0
	s_setprio 1
	v_mfma_f32_16x16x32_bf16 v[94:97], v[156:159], v[172:175], v[94:97]
	v_mfma_f32_16x16x32_bf16 v[90:93], v[164:167], v[172:175], v[90:93]
	v_mfma_f32_16x16x32_bf16 v[86:89], v[156:159], v[180:183], v[86:89]
	v_mfma_f32_16x16x32_bf16 v[82:85], v[164:167], v[180:183], v[82:85]
	v_mfma_f32_16x16x32_bf16 v[78:81], v[156:159], v[188:191], v[78:81]
	v_mfma_f32_16x16x32_bf16 v[74:77], v[164:167], v[188:191], v[74:77]
	v_mfma_f32_16x16x32_bf16 v[70:73], v[156:159], v[196:199], v[70:73]
	v_mfma_f32_16x16x32_bf16 v[66:69], v[164:167], v[196:199], v[66:69]
	v_mfma_f32_16x16x32_bf16 v[94:97], v[160:163], v[176:179], v[94:97]
	v_mfma_f32_16x16x32_bf16 v[90:93], v[168:171], v[176:179], v[90:93]
	v_mfma_f32_16x16x32_bf16 v[86:89], v[160:163], v[184:187], v[86:89]
	v_mfma_f32_16x16x32_bf16 v[82:85], v[168:171], v[184:187], v[82:85]
	v_mfma_f32_16x16x32_bf16 v[78:81], v[160:163], v[192:195], v[78:81]
	v_mfma_f32_16x16x32_bf16 v[74:77], v[168:171], v[192:195], v[74:77]
	v_mfma_f32_16x16x32_bf16 v[70:73], v[160:163], v[200:203], v[70:73]
	v_mfma_f32_16x16x32_bf16 v[66:69], v[168:171], v[200:203], v[66:69]
	s_barrier
	s_setprio 0
	s_mov_b32 m0, s67
	v_lshl_add_u64 v[204:205], s[46:47], 0, v[0:1]
	ds_read_b128 v[172:175], v143 offset:16384
	ds_read_b128 v[176:179], v143 offset:17408
	ds_read_b128 v[180:183], v143 offset:18432
	ds_read_b128 v[184:187], v143 offset:19456
	ds_read_b128 v[188:191], v143 offset:20480
	ds_read_b128 v[192:195], v143 offset:21504
	ds_read_b128 v[196:199], v143 offset:22528
	ds_read_b128 v[200:203], v143 offset:23552
	global_load_lds_dwordx4 v[204:205], off
	v_lshl_add_u64 v[206:207], s[46:47], 0, v[134:135]
	s_mov_b32 m0, s70
	v_lshl_add_u64 v[208:209], s[48:49], 0, v[0:1]
	global_load_lds_dwordx4 v[206:207], off
	s_mov_b32 m0, s71
	v_lshl_add_u64 v[210:211], s[42:43], 0, v[132:133]
	global_load_lds_dwordx4 v[208:209], off
	v_lshl_add_u64 v[208:209], s[48:49], 0, v[134:135]
	s_mov_b32 m0, s74
	s_nop 0
	global_load_lds_dwordx4 v[208:209], off
	v_lshl_add_u64 v[208:209], s[42:43], 0, v[130:131]
	s_mov_b32 m0, s45
	s_nop 0
	global_load_lds_dwordx4 v[208:209], off
	s_mov_b32 m0, s50
	s_nop 0
	global_load_lds_dwordx4 v[210:211], off
	s_waitcnt vmcnt(8)
	s_waitcnt lgkmcnt(0)
	s_barrier
; #define PG8_STAGE(bufoff, gbase, voff) do { _Pragma("unroll") for (int _i = 0; _i < 2; ++_i) \
;         __builtin_amdgcn_global_load_lds((const unsigned*)((const char*)(gbase) + (voff)[_i]), (LAS unsigned*)(lds + (bufoff) + ldsw + _i * 8192), 16, 0, 0); } while (0)
; #define PG8_LDA(dst, b, h) do { _Pragma("unroll") for (int m = 0; m < 4; ++m) _Pragma("unroll") for (int k = 0; k < 2; ++k) dst[m][k] = *(const LAS bf16x8*)(lds + PG8_SA(b, h) + aoff + m * 2048 + k * 1024); } while (0)
; #define PG8_LDB(dst, b, h) do { _Pragma("unroll") for (int n = 0; n < 2; ++n) _Pragma("unroll") for (int k = 0; k < 2; ++k) dst[n][k] = *(const LAS bf16x8*)(lds + PG8_SB(b, h) + boff + n * 2048 + k * 1024); } while (0)
; #define PG8_MMA(ai, bj, At, Bt) do { __builtin_amdgcn_s_setprio(1); _Pragma("unroll") for (int m = 0; m < 4; ++m) _Pragma("unroll") for (int n = 0; n < 2; ++n) _Pragma("unroll") for (int k = 0; k < 2; ++k) \
;         acc[ai][bj][m][n] = __builtin_amdgcn_mfma_f32_16x16x32_bf16(Bt[n][k], At[m][k], acc[ai][bj][m][n], 0, 0, 0); __builtin_amdgcn_s_setprio(0); } while (0)
; #define PG8_WAIT_V(n) asm volatile("s_waitcnt vmcnt(" #n ")" ::: "memory")
; #define PG8_WAIT_L(n) asm volatile("s_waitcnt lgkmcnt(" #n ")" ::: "memory")
; #define PG8_BAR __builtin_amdgcn_s_barrier()
; #define PG8_SCHED __builtin_amdgcn_sched_barrier(0)
; template <class Epi, class Sched, bool ALIGN_EPI, bool LAST_FUSED = false, bool PERM = false, bool CARRY = false>
; __device__ __forceinline__ void gemm_phase(LAS unsigned char* lds, const int tid, const int K, const int lda, const int ldb, const Sched& S, const Epi& E) {
;     ...
;             PG8_WAIT_V(8); PG8_WAIT_L(0); PG8_BAR; PG8_MMA(1, 0, At, B0); PG8_MMA(1, 1, At, B1); PG8_BAR; PG8_SCHED;
;             PG8_LDB(B0, 1, 0); PG8_LDB(B1, 1, 1); PG8_SCHED; PG8_LDA(At, 1, 0); PG8_STAGE(PG8_SA(0, 1), a2 + hstepA, voffA);
;             PG8_WAIT_V(8); PG8_WAIT_L(0); PG8_BAR; PG8_MMA(0, 0, At, B0); PG8_MMA(0, 1, At, B1); PG8_BAR; PG8_SCHED;
;             PG8_LDA(At, 1, 1); PG8_STAGE(PG8_SB(1, 0), b3, voffB); PG8_STAGE(PG8_SB(1, 1), b3 + hstepB, voffB); PG8_STAGE(PG8_SA(1, 0), a3, voffA);
;             PG8_WAIT_V(8); PG8_WAIT_L(0); PG8_BAR; PG8_MMA(1, 0, At, B0); PG8_MMA(1, 1, At, B1); PG8_BAR; PG8_SCHED;
	s_setprio 1
	v_mfma_f32_16x16x32_bf16 v[62:65], v[136:139], v[172:175], v[62:65]
	v_mfma_f32_16x16x32_bf16 v[58:61], v[148:151], v[172:175], v[58:61]
	v_mfma_f32_16x16x32_bf16 v[54:57], v[136:139], v[180:183], v[54:57]
	v_mfma_f32_16x16x32_bf16 v[50:53], v[148:151], v[180:183], v[50:53]
	v_mfma_f32_16x16x32_bf16 v[46:49], v[136:139], v[188:191], v[46:49]
	v_mfma_f32_16x16x32_bf16 v[42:45], v[148:151], v[188:191], v[42:45]
	v_mfma_f32_16x16x32_bf16 v[38:41], v[136:139], v[196:199], v[38:41]
	v_mfma_f32_16x16x32_bf16 v[34:37], v[148:151], v[196:199], v[34:37]
	v_mfma_f32_16x16x32_bf16 v[62:65], v[144:147], v[176:179], v[62:65]
	v_mfma_f32_16x16x32_bf16 v[58:61], v[152:155], v[176:179], v[58:61]
	v_mfma_f32_16x16x32_bf16 v[54:57], v[144:147], v[184:187], v[54:57]
	v_mfma_f32_16x16x32_bf16 v[50:53], v[152:155], v[184:187], v[50:53]
	v_mfma_f32_16x16x32_bf16 v[46:49], v[144:147], v[192:195], v[46:49]
	v_mfma_f32_16x16x32_bf16 v[42:45], v[152:155], v[192:195], v[42:45]
	v_mfma_f32_16x16x32_bf16 v[38:41], v[144:147], v[200:203], v[38:41]
	v_mfma_f32_16x16x32_bf16 v[34:37], v[152:155], v[200:203], v[34:37]
	s_setprio 0
	s_setprio 1
	v_mfma_f32_16x16x32_bf16 v[30:33], v[156:159], v[172:175], v[30:33]
	v_mfma_f32_16x16x32_bf16 v[26:29], v[164:167], v[172:175], v[26:29]
	v_mfma_f32_16x16x32_bf16 v[22:25], v[156:159], v[180:183], v[22:25]
	v_mfma_f32_16x16x32_bf16 v[18:21], v[164:167], v[180:183], v[18:21]
	v_mfma_f32_16x16x32_bf16 v[14:17], v[156:159], v[188:191], v[14:17]
	v_mfma_f32_16x16x32_bf16 v[10:13], v[164:167], v[188:191], v[10:13]
	v_mfma_f32_16x16x32_bf16 v[6:9], v[156:159], v[196:199], v[6:9]
	v_mfma_f32_16x16x32_bf16 v[2:5], v[164:167], v[196:199], v[2:5]
	v_mfma_f32_16x16x32_bf16 v[30:33], v[160:163], v[176:179], v[30:33]
	v_mfma_f32_16x16x32_bf16 v[26:29], v[168:171], v[176:179], v[26:29]
	v_mfma_f32_16x16x32_bf16 v[22:25], v[160:163], v[184:187], v[22:25]
	v_mfma_f32_16x16x32_bf16 v[18:21], v[168:171], v[184:187], v[18:21]
	v_mfma_f32_16x16x32_bf16 v[14:17], v[160:163], v[192:195], v[14:17]
	v_mfma_f32_16x16x32_bf16 v[10:13], v[168:171], v[192:195], v[10:13]
	v_mfma_f32_16x16x32_bf16 v[6:9], v[160:163], v[200:203], v[6:9]
	v_mfma_f32_16x16x32_bf16 v[2:5], v[168:171], v[200:203], v[2:5]
	s_barrier
	s_setprio 0
	v_add_u32_e32 v152, s75, v140
	v_add_u32_e32 v168, s76, v140
	ds_read_b128 v[136:139], v152
	ds_read_b128 v[144:147], v152 offset:1024
	ds_read_b128 v[148:151], v152 offset:2048
	ds_read_b128 v[152:155], v152 offset:3072
	ds_read_b128 v[156:159], v168
	ds_read_b128 v[160:163], v168 offset:1024
	ds_read_b128 v[164:167], v168 offset:2048
	ds_read_b128 v[168:171], v168 offset:3072
	s_mov_b32 m0, s51
	v_lshl_add_u64 v[212:213], s[40:41], 0, v[130:131]
	ds_read_b128 v[172:175], v143 offset:32768
	ds_read_b128 v[176:179], v143 offset:33792
	ds_read_b128 v[180:183], v143 offset:34816
	ds_read_b128 v[184:187], v143 offset:35840
	ds_read_b128 v[188:191], v143 offset:36864
	ds_read_b128 v[192:195], v143 offset:37888
	ds_read_b128 v[196:199], v143 offset:38912
	ds_read_b128 v[200:203], v143 offset:39936
	global_load_lds_dwordx4 v[212:213], off
	v_lshl_add_u64 v[212:213], s[40:41], 0, v[132:133]
	s_mov_b32 m0, s52
	s_nop 0
	global_load_lds_dwordx4 v[212:213], off
	s_waitcnt vmcnt(8)
	s_waitcnt lgkmcnt(0)
	s_barrier
	s_setprio 1
	v_mfma_f32_16x16x32_bf16 v[126:129], v[136:139], v[172:175], v[126:129]
	v_mfma_f32_16x16x32_bf16 v[122:125], v[148:151], v[172:175], v[122:125]
	v_mfma_f32_16x16x32_bf16 v[118:121], v[136:139], v[180:183], v[118:121]
	v_mfma_f32_16x16x32_bf16 v[114:117], v[148:151], v[180:183], v[114:117]
	v_mfma_f32_16x16x32_bf16 v[110:113], v[136:139], v[188:191], v[110:113]
	v_mfma_f32_16x16x32_bf16 v[106:109], v[148:151], v[188:191], v[106:109]
	v_mfma_f32_16x16x32_bf16 v[102:105], v[136:139], v[196:199], v[102:105]
	v_mfma_f32_16x16x32_bf16 v[98:101], v[148:151], v[196:199], v[98:101]
	v_mfma_f32_16x16x32_bf16 v[126:129], v[144:147], v[176:179], v[126:129]
	v_mfma_f32_16x16x32_bf16 v[122:125], v[152:155], v[176:179], v[122:125]
	v_mfma_f32_16x16x32_bf16 v[118:121], v[144:147], v[184:187], v[118:121]
	v_mfma_f32_16x16x32_bf16 v[114:117], v[152:155], v[184:187], v[114:117]
	v_mfma_f32_16x16x32_bf16 v[110:113], v[144:147], v[192:195], v[110:113]
	v_mfma_f32_16x16x32_bf16 v[106:109], v[152:155], v[192:195], v[106:109]
	v_mfma_f32_16x16x32_bf16 v[102:105], v[144:147], v[200:203], v[102:105]
	v_mfma_f32_16x16x32_bf16 v[98:101], v[152:155], v[200:203], v[98:101]
	s_setprio 0
	s_setprio 1
	v_mfma_f32_16x16x32_bf16 v[94:97], v[156:159], v[172:175], v[94:97]
	v_mfma_f32_16x16x32_bf16 v[90:93], v[164:167], v[172:175], v[90:93]
	v_mfma_f32_16x16x32_bf16 v[86:89], v[156:159], v[180:183], v[86:89]
	v_mfma_f32_16x16x32_bf16 v[82:85], v[164:167], v[180:183], v[82:85]
	v_mfma_f32_16x16x32_bf16 v[78:81], v[156:159], v[188:191], v[78:81]
	v_mfma_f32_16x16x32_bf16 v[74:77], v[164:167], v[188:191], v[74:77]
	v_mfma_f32_16x16x32_bf16 v[70:73], v[156:159], v[196:199], v[70:73]
	v_mfma_f32_16x16x32_bf16 v[66:69], v[164:167], v[196:199], v[66:69]
	v_mfma_f32_16x16x32_bf16 v[94:97], v[160:163], v[176:179], v[94:97]
	v_mfma_f32_16x16x32_bf16 v[90:93], v[168:171], v[176:179], v[90:93]
	v_mfma_f32_16x16x32_bf16 v[86:89], v[160:163], v[184:187], v[86:89]
	v_mfma_f32_16x16x32_bf16 v[82:85], v[168:171], v[184:187], v[82:85]
	v_mfma_f32_16x16x32_bf16 v[78:81], v[160:163], v[192:195], v[78:81]
	v_mfma_f32_16x16x32_bf16 v[74:77], v[168:171], v[192:195], v[74:77]
	v_mfma_f32_16x16x32_bf16 v[70:73], v[160:163], v[200:203], v[70:73]
	v_mfma_f32_16x16x32_bf16 v[66:69], v[168:171], v[200:203], v[66:69]
	s_barrier
; #define PG8_STAGE(bufoff, gbase, voff) do { _Pragma("unroll") for (int _i = 0; _i < 2; ++_i) \
;         __builtin_amdgcn_global_load_lds((const unsigned*)((const char*)(gbase) + (voff)[_i]), (LAS unsigned*)(lds + (bufoff) + ldsw + _i * 8192), 16, 0, 0); } while (0)
; #define PG8_LDA(dst, b, h) do { _Pragma("unroll") for (int m = 0; m < 4; ++m) _Pragma("unroll") for (int k = 0; k < 2; ++k) dst[m][k] = *(const LAS bf16x8*)(lds + PG8_SA(b, h) + aoff + m * 2048 + k * 1024); } while (0)
; #define PG8_MMA(ai, bj, At, Bt) do { __builtin_amdgcn_s_setprio(1); _Pragma("unroll") for (int m = 0; m < 4; ++m) _Pragma("unroll") for (int n = 0; n < 2; ++n) _Pragma("unroll") for (int k = 0; k < 2; ++k) \
;         acc[ai][bj][m][n] = __builtin_amdgcn_mfma_f32_16x16x32_bf16(Bt[n][k], At[m][k], acc[ai][bj][m][n], 0, 0, 0); __builtin_amdgcn_s_setprio(0); } while (0)
; #define PG8_WAIT_V(n) asm volatile("s_waitcnt vmcnt(" #n ")" ::: "memory")
; #define PG8_WAIT_L(n) asm volatile("s_waitcnt lgkmcnt(" #n ")" ::: "memory")
; #define PG8_BAR __builtin_amdgcn_s_barrier()
; #define PG8_SCHED __builtin_amdgcn_sched_barrier(0)
; template <class Epi, class Sched, bool ALIGN_EPI, bool LAST_FUSED = false, bool PERM = false, bool CARRY = false>
; __device__ __forceinline__ void gemm_phase(LAS unsigned char* lds, const int tid, const int K, const int lda, const int ldb, const Sched& S, const Epi& E) {
;     ...
;             PG8_LDA(At, 1, 1); PG8_STAGE(PG8_SB(1, 0), b3, voffB); PG8_STAGE(PG8_SB(1, 1), b3 + hstepB, voffB); PG8_STAGE(PG8_SA(1, 0), a3, voffA);
;             PG8_WAIT_V(8); PG8_WAIT_L(0); PG8_BAR; PG8_MMA(1, 0, At, B0); PG8_MMA(1, 1, At, B1); PG8_BAR; PG8_SCHED;
;         }
	s_setprio 0
	s_mov_b32 m0, s61
	v_lshl_add_u64 v[204:205], v[204:205], 0, s[68:69]
	ds_read_b128 v[172:175], v143 offset:49152
	ds_read_b128 v[176:179], v143 offset:50176
	ds_read_b128 v[180:183], v143 offset:51200
	ds_read_b128 v[184:187], v143 offset:52224
	ds_read_b128 v[188:191], v143 offset:53248
	ds_read_b128 v[192:195], v143 offset:54272
	ds_read_b128 v[196:199], v143 offset:55296
	ds_read_b128 v[200:203], v143 offset:56320
	global_load_lds_dwordx4 v[204:205], off
	v_lshl_add_u64 v[204:205], v[206:207], 0, s[68:69]
	s_mov_b32 m0, s24
	s_nop 0
	global_load_lds_dwordx4 v[204:205], off
	v_lshl_add_u64 v[204:205], s[38:39], 0, v[0:1]
	s_mov_b32 m0, s63
	s_nop 0
	global_load_lds_dwordx4 v[204:205], off
	v_lshl_add_u64 v[204:205], s[38:39], 0, v[134:135]
	s_mov_b32 m0, s62
	s_nop 0
	global_load_lds_dwordx4 v[204:205], off
	v_lshl_add_u64 v[204:205], v[208:209], 0, s[68:69]
	s_mov_b32 m0, s55
	s_nop 0
	global_load_lds_dwordx4 v[204:205], off
	v_lshl_add_u64 v[204:205], v[210:211], 0, s[68:69]
	s_mov_b32 m0, s56
	s_nop 0
	global_load_lds_dwordx4 v[204:205], off
	s_waitcnt vmcnt(8)
	s_waitcnt lgkmcnt(0)
	s_barrier
	s_setprio 1
	v_mfma_f32_16x16x32_bf16 v[62:65], v[136:139], v[172:175], v[62:65]
	v_mfma_f32_16x16x32_bf16 v[58:61], v[148:151], v[172:175], v[58:61]
	v_mfma_f32_16x16x32_bf16 v[54:57], v[136:139], v[180:183], v[54:57]
	v_mfma_f32_16x16x32_bf16 v[50:53], v[148:151], v[180:183], v[50:53]
	v_mfma_f32_16x16x32_bf16 v[46:49], v[136:139], v[188:191], v[46:49]
	v_mfma_f32_16x16x32_bf16 v[42:45], v[148:151], v[188:191], v[42:45]
	v_mfma_f32_16x16x32_bf16 v[38:41], v[136:139], v[196:199], v[38:41]
	v_mfma_f32_16x16x32_bf16 v[34:37], v[148:151], v[196:199], v[34:37]
	v_mfma_f32_16x16x32_bf16 v[62:65], v[144:147], v[176:179], v[62:65]
	v_mfma_f32_16x16x32_bf16 v[58:61], v[152:155], v[176:179], v[58:61]
	v_mfma_f32_16x16x32_bf16 v[54:57], v[144:147], v[184:187], v[54:57]
	v_mfma_f32_16x16x32_bf16 v[50:53], v[152:155], v[184:187], v[50:53]
	v_mfma_f32_16x16x32_bf16 v[46:49], v[144:147], v[192:195], v[46:49]
	v_mfma_f32_16x16x32_bf16 v[42:45], v[152:155], v[192:195], v[42:45]
	v_mfma_f32_16x16x32_bf16 v[38:41], v[144:147], v[200:203], v[38:41]
	v_mfma_f32_16x16x32_bf16 v[34:37], v[152:155], v[200:203], v[34:37]
	s_setprio 0
	s_setprio 1
	v_mfma_f32_16x16x32_bf16 v[30:33], v[156:159], v[172:175], v[30:33]
	v_mfma_f32_16x16x32_bf16 v[26:29], v[164:167], v[172:175], v[26:29]
	v_mfma_f32_16x16x32_bf16 v[22:25], v[156:159], v[180:183], v[22:25]
	v_mfma_f32_16x16x32_bf16 v[18:21], v[164:167], v[180:183], v[18:21]
	v_mfma_f32_16x16x32_bf16 v[14:17], v[156:159], v[188:191], v[14:17]
	v_mfma_f32_16x16x32_bf16 v[10:13], v[164:167], v[188:191], v[10:13]
	v_mfma_f32_16x16x32_bf16 v[6:9], v[156:159], v[196:199], v[6:9]
	v_mfma_f32_16x16x32_bf16 v[2:5], v[164:167], v[196:199], v[2:5]
	v_mfma_f32_16x16x32_bf16 v[30:33], v[160:163], v[176:179], v[30:33]
	v_mfma_f32_16x16x32_bf16 v[26:29], v[168:171], v[176:179], v[26:29]
	v_mfma_f32_16x16x32_bf16 v[22:25], v[160:163], v[184:187], v[22:25]
	v_mfma_f32_16x16x32_bf16 v[18:21], v[168:171], v[184:187], v[18:21]
	v_mfma_f32_16x16x32_bf16 v[14:17], v[160:163], v[192:195], v[14:17]
	v_mfma_f32_16x16x32_bf16 v[10:13], v[168:171], v[192:195], v[10:13]
	v_mfma_f32_16x16x32_bf16 v[6:9], v[160:163], v[200:203], v[6:9]
	v_mfma_f32_16x16x32_bf16 v[2:5], v[168:171], v[200:203], v[2:5]
	s_barrier
	s_setprio 0
	s_movk_i32 s24, 0x100
	s_andn2_b64 vcc, exec, s[36:37]
	s_mov_b64 s[38:39], -1
	s_mov_b64 s[36:37], 0
	s_cbranch_vccz .LBB0_622
	s_and_b64 vcc, exec, s[10:11]
	s_cbranch_vccz .LBB0_625
	s_barrier

; #define PG8_STAGE(bufoff, gbase, voff) do { _Pragma("unroll") for (int _i = 0; _i < 2; ++_i) \
;         __builtin_amdgcn_global_load_lds((const unsigned*)((const char*)(gbase) + (voff)[_i]), (LAS unsigned*)(lds + (bufoff) + ldsw + _i * 8192), 16, 0, 0); } while (0)
; #define PG8_LDA(dst, b, h) do { _Pragma("unroll") for (int m = 0; m < 4; ++m) _Pragma("unroll") for (int k = 0; k < 2; ++k) dst[m][k] = *(const LAS bf16x8*)(lds + PG8_SA(b, h) + aoff + m * 2048 + k * 1024); } while (0)
; #define PG8_LDB(dst, b, h) do { _Pragma("unroll") for (int n = 0; n < 2; ++n) _Pragma("unroll") for (int k = 0; k < 2; ++k) dst[n][k] = *(const LAS bf16x8*)(lds + PG8_SB(b, h) + boff + n * 2048 + k * 1024); } while (0)
; #define PG8_WAIT_V(n) asm volatile("s_waitcnt vmcnt(" #n ")" ::: "memory")
; template <class Epi, class Sched, bool ALIGN_EPI, bool LAST_FUSED = false, bool PERM = false, bool CARRY = false>
; __device__ __forceinline__ void gemm_phase(LAS unsigned char* lds, const int tid, const int K, const int lda, const int ldb, const Sched& S, const Epi& E) {
;     ...
;         const bool has_next = S.next(KD_IDX(ui + 1), nxt);
;         const char* nA = has_next ? nxt.a : cA; const char* nB = has_next ? nxt.b : cB; const int nt = cur.nt;
; #pragma unroll 1
;         for (int t = 0; t < nt; t += 2) {
;             const bool last = (t == nt - 2);
;             const char* a1 = cA + (size_t)(t + 1) * kstep;
;             const char* a2 = last ? nA : cA + (size_t)(t + 2) * kstep; const char* b2 = last ? nB : cB + (size_t)(t + 2) * kstep;
;             const char* a3 = a2 + kstep; const char* b3 = b2 + kstep;
;             PG8_LDB(B0, 0, 0); PG8_LDB(B1, 0, 1); PG8_SCHED; PG8_LDA(At, 0, 0); PG8_STAGE(PG8_SA(1, 1), a1 + hstepA, voffA);
;             PG8_WAIT_V(8); PG8_WAIT_L(0); PG8_BAR; PG8_MMA(0, 0, At, B0); PG8_MMA(0, 1, At, B1); PG8_BAR; PG8_SCHED;
;             PG8_LDA(At, 0, 1); PG8_STAGE(PG8_SB(0, 0), b2, voffB); PG8_STAGE(PG8_SB(0, 1), b2 + hstepB, voffB); PG8_STAGE(PG8_SA(0, 0), a2, voffA);
;             PG8_WAIT_V(8); PG8_WAIT_L(0); PG8_BAR; PG8_MMA(1, 0, At, B0); PG8_MMA(1, 1, At, B1); PG8_BAR; PG8_SCHED;
;             PG8_LDB(B0, 1, 0); PG8_LDB(B1, 1, 1); PG8_SCHED; PG8_LDA(At, 1, 0); PG8_STAGE(PG8_SA(0, 1), a2 + hstepA, voffA);
;             PG8_WAIT_V(8); PG8_WAIT_L(0); PG8_BAR; PG8_MMA(0, 0, At, B0); PG8_MMA(0, 1, At, B1); PG8_BAR; PG8_SCHED;
.LBB0_705:
	s_add_u32 s30, s26, 0x100
	s_addc_u32 s31, s27, 0
	s_add_i32 s54, 0, 0x10000
	s_cmp_eq_u32 s53, 8
	s_cselect_b32 s39, s15, s31
	s_cselect_b32 s38, s14, s30
	v_add_u32_e32 v140, s54, v144
	s_cselect_b32 s37, s17, s52
	s_cselect_b32 s36, s16, s13
	s_add_i32 s55, 0, 0x14000
	ds_read_b128 v[146:149], v140
	ds_read_b128 v[150:153], v140 offset:1024
	ds_read_b128 v[154:157], v140 offset:2048
	ds_read_b128 v[158:161], v140 offset:3072
	v_add_u32_e32 v140, s55, v144
	ds_read_b128 v[162:165], v140
	ds_read_b128 v[166:169], v140 offset:1024
	ds_read_b128 v[170:173], v140 offset:2048
	ds_read_b128 v[174:177], v140 offset:3072
	v_lshl_add_u64 v[140:141], s[26:27], 0, v[136:137]
	s_add_i32 m0, s19, 0xc000
	ds_read_b128 v[178:181], v145
	ds_read_b128 v[182:185], v145 offset:1024
	ds_read_b128 v[186:189], v145 offset:2048
	ds_read_b128 v[190:193], v145 offset:3072
	ds_read_b128 v[194:197], v145 offset:4096
	ds_read_b128 v[198:201], v145 offset:5120
	ds_read_b128 v[202:205], v145 offset:6144
	ds_read_b128 v[206:209], v145 offset:7168
	global_load_lds_dwordx4 v[140:141], off
	v_lshl_add_u64 v[140:141], s[26:27], 0, v[138:139]
	s_add_i32 m0, s19, 0xe000
	s_nop 0
	global_load_lds_dwordx4 v[140:141], off
	s_waitcnt vmcnt(8)
	s_waitcnt lgkmcnt(0)
	s_barrier
	s_setprio 1
	v_mfma_f32_16x16x32_bf16 v[126:129], v[146:149], v[178:181], v[126:129]
	v_mfma_f32_16x16x32_bf16 v[122:125], v[154:157], v[178:181], v[122:125]
	v_mfma_f32_16x16x32_bf16 v[118:121], v[146:149], v[186:189], v[118:121]
	v_mfma_f32_16x16x32_bf16 v[110:113], v[154:157], v[186:189], v[110:113]
	v_mfma_f32_16x16x32_bf16 v[102:105], v[146:149], v[194:197], v[102:105]
	v_mfma_f32_16x16x32_bf16 v[94:97], v[154:157], v[194:197], v[94:97]
	v_mfma_f32_16x16x32_bf16 v[86:89], v[146:149], v[202:205], v[86:89]
	v_mfma_f32_16x16x32_bf16 v[78:81], v[154:157], v[202:205], v[78:81]
	v_mfma_f32_16x16x32_bf16 v[126:129], v[150:153], v[182:185], v[126:129]
	v_mfma_f32_16x16x32_bf16 v[122:125], v[158:161], v[182:185], v[122:125]
	v_mfma_f32_16x16x32_bf16 v[118:121], v[150:153], v[190:193], v[118:121]
	v_mfma_f32_16x16x32_bf16 v[110:113], v[158:161], v[190:193], v[110:113]
	v_mfma_f32_16x16x32_bf16 v[102:105], v[150:153], v[198:201], v[102:105]
	v_mfma_f32_16x16x32_bf16 v[94:97], v[158:161], v[198:201], v[94:97]
	v_mfma_f32_16x16x32_bf16 v[86:89], v[150:153], v[206:209], v[86:89]
	v_mfma_f32_16x16x32_bf16 v[78:81], v[158:161], v[206:209], v[78:81]
	s_setprio 0
	s_setprio 1
	v_mfma_f32_16x16x32_bf16 v[114:117], v[162:165], v[178:181], v[114:117]
	v_mfma_f32_16x16x32_bf16 v[106:109], v[170:173], v[178:181], v[106:109]
	v_mfma_f32_16x16x32_bf16 v[98:101], v[162:165], v[186:189], v[98:101]
	v_mfma_f32_16x16x32_bf16 v[90:93], v[170:173], v[186:189], v[90:93]
	v_mfma_f32_16x16x32_bf16 v[82:85], v[162:165], v[194:197], v[82:85]
	v_mfma_f32_16x16x32_bf16 v[74:77], v[170:173], v[194:197], v[74:77]
	v_mfma_f32_16x16x32_bf16 v[70:73], v[162:165], v[202:205], v[70:73]
	v_mfma_f32_16x16x32_bf16 v[66:69], v[170:173], v[202:205], v[66:69]
	v_mfma_f32_16x16x32_bf16 v[114:117], v[166:169], v[182:185], v[114:117]
	v_mfma_f32_16x16x32_bf16 v[106:109], v[174:177], v[182:185], v[106:109]
	v_mfma_f32_16x16x32_bf16 v[98:101], v[166:169], v[190:193], v[98:101]
	v_mfma_f32_16x16x32_bf16 v[90:93], v[174:177], v[190:193], v[90:93]
	v_mfma_f32_16x16x32_bf16 v[82:85], v[166:169], v[198:201], v[82:85]
	v_mfma_f32_16x16x32_bf16 v[74:77], v[174:177], v[198:201], v[74:77]
	v_mfma_f32_16x16x32_bf16 v[70:73], v[166:169], v[206:209], v[70:73]
	v_mfma_f32_16x16x32_bf16 v[66:69], v[174:177], v[206:209], v[66:69]
	s_barrier
	s_setprio 0
	s_add_i32 s26, s54, s40
	v_lshl_add_u64 v[140:141], s[36:37], 0, v[0:1]
	s_mov_b32 m0, s26
	ds_read_b128 v[178:181], v145 offset:16384
	ds_read_b128 v[182:185], v145 offset:17408
	ds_read_b128 v[186:189], v145 offset:18432
	ds_read_b128 v[190:193], v145 offset:19456
	ds_read_b128 v[194:197], v145 offset:20480
	ds_read_b128 v[198:201], v145 offset:21504
	ds_read_b128 v[202:205], v145 offset:22528
	ds_read_b128 v[206:209], v145 offset:23552
	global_load_lds_dwordx4 v[140:141], off
	s_add_i32 m0, s26, 0x2000
	s_add_u32 s26, s36, 0x30000
	v_lshl_add_u64 v[210:211], s[36:37], 0, v[130:131]
	s_addc_u32 s27, s37, 0
	s_add_i32 s54, s55, s40
	global_load_lds_dwordx4 v[210:211], off
	v_lshl_add_u64 v[212:213], s[26:27], 0, v[0:1]
	s_mov_b32 m0, s54
	v_lshl_add_u64 v[214:215], s[38:39], 0, v[132:133]
	global_load_lds_dwordx4 v[212:213], off
	v_lshl_add_u64 v[212:213], s[26:27], 0, v[130:131]
	s_add_i32 m0, s54, 0x2000
	s_nop 0
	global_load_lds_dwordx4 v[212:213], off
	v_lshl_add_u64 v[212:213], s[38:39], 0, v[134:135]
	s_mov_b32 m0, s19
	s_nop 0
	global_load_lds_dwordx4 v[212:213], off
	s_mov_b32 m0, s42
	s_nop 0
	global_load_lds_dwordx4 v[214:215], off
	s_waitcnt vmcnt(8)
	s_waitcnt lgkmcnt(0)
	s_barrier
; #define PG8_STAGE(bufoff, gbase, voff) do { _Pragma("unroll") for (int _i = 0; _i < 2; ++_i) \
;         __builtin_amdgcn_global_load_lds((const unsigned*)((const char*)(gbase) + (voff)[_i]), (LAS unsigned*)(lds + (bufoff) + ldsw + _i * 8192), 16, 0, 0); } while (0)
; #define PG8_LDA(dst, b, h) do { _Pragma("unroll") for (int m = 0; m < 4; ++m) _Pragma("unroll") for (int k = 0; k < 2; ++k) dst[m][k] = *(const LAS bf16x8*)(lds + PG8_SA(b, h) + aoff + m * 2048 + k * 1024); } while (0)
; #define PG8_LDB(dst, b, h) do { _Pragma("unroll") for (int n = 0; n < 2; ++n) _Pragma("unroll") for (int k = 0; k < 2; ++k) dst[n][k] = *(const LAS bf16x8*)(lds + PG8_SB(b, h) + boff + n * 2048 + k * 1024); } while (0)
; #define PG8_MMA(ai, bj, At, Bt) do { __builtin_amdgcn_s_setprio(1); _Pragma("unroll") for (int m = 0; m < 4; ++m) _Pragma("unroll") for (int n = 0; n < 2; ++n) _Pragma("unroll") for (int k = 0; k < 2; ++k) \
;         acc[ai][bj][m][n] = __builtin_amdgcn_mfma_f32_16x16x32_bf16(Bt[n][k], At[m][k], acc[ai][bj][m][n], 0, 0, 0); __builtin_amdgcn_s_setprio(0); } while (0)
; #define PG8_WAIT_V(n) asm volatile("s_waitcnt vmcnt(" #n ")" ::: "memory")
; #define PG8_WAIT_L(n) asm volatile("s_waitcnt lgkmcnt(" #n ")" ::: "memory")
; #define PG8_BAR __builtin_amdgcn_s_barrier()
; #define PG8_SCHED __builtin_amdgcn_sched_barrier(0)
; template <class Epi, class Sched, bool ALIGN_EPI, bool LAST_FUSED = false, bool PERM = false, bool CARRY = false>
; __device__ __forceinline__ void gemm_phase(LAS unsigned char* lds, const int tid, const int K, const int lda, const int ldb, const Sched& S, const Epi& E) {
;     ...
;             PG8_WAIT_V(8); PG8_WAIT_L(0); PG8_BAR; PG8_MMA(1, 0, At, B0); PG8_MMA(1, 1, At, B1); PG8_BAR; PG8_SCHED;
;             PG8_LDB(B0, 1, 0); PG8_LDB(B1, 1, 1); PG8_SCHED; PG8_LDA(At, 1, 0); PG8_STAGE(PG8_SA(0, 1), a2 + hstepA, voffA);
;             PG8_WAIT_V(8); PG8_WAIT_L(0); PG8_BAR; PG8_MMA(0, 0, At, B0); PG8_MMA(0, 1, At, B1); PG8_BAR; PG8_SCHED;
;             PG8_LDA(At, 1, 1); PG8_STAGE(PG8_SB(1, 0), b3, voffB); PG8_STAGE(PG8_SB(1, 1), b3 + hstepB, voffB); PG8_STAGE(PG8_SA(1, 0), a3, voffA);
;             PG8_WAIT_V(8); PG8_WAIT_L(0); PG8_BAR; PG8_MMA(1, 0, At, B0); PG8_MMA(1, 1, At, B1); PG8_BAR; PG8_SCHED;
	s_setprio 1
	v_mfma_f32_16x16x32_bf16 v[62:65], v[146:149], v[178:181], v[62:65]
	v_mfma_f32_16x16x32_bf16 v[58:61], v[154:157], v[178:181], v[58:61]
	v_mfma_f32_16x16x32_bf16 v[54:57], v[146:149], v[186:189], v[54:57]
	v_mfma_f32_16x16x32_bf16 v[46:49], v[154:157], v[186:189], v[46:49]
	v_mfma_f32_16x16x32_bf16 v[38:41], v[146:149], v[194:197], v[38:41]
	v_mfma_f32_16x16x32_bf16 v[30:33], v[154:157], v[194:197], v[30:33]
	v_mfma_f32_16x16x32_bf16 v[22:25], v[146:149], v[202:205], v[22:25]
	v_mfma_f32_16x16x32_bf16 v[14:17], v[154:157], v[202:205], v[14:17]
	v_mfma_f32_16x16x32_bf16 v[62:65], v[150:153], v[182:185], v[62:65]
	v_mfma_f32_16x16x32_bf16 v[58:61], v[158:161], v[182:185], v[58:61]
	v_mfma_f32_16x16x32_bf16 v[54:57], v[150:153], v[190:193], v[54:57]
	v_mfma_f32_16x16x32_bf16 v[46:49], v[158:161], v[190:193], v[46:49]
	v_mfma_f32_16x16x32_bf16 v[38:41], v[150:153], v[198:201], v[38:41]
	v_mfma_f32_16x16x32_bf16 v[30:33], v[158:161], v[198:201], v[30:33]
	v_mfma_f32_16x16x32_bf16 v[22:25], v[150:153], v[206:209], v[22:25]
	v_mfma_f32_16x16x32_bf16 v[14:17], v[158:161], v[206:209], v[14:17]
	s_setprio 0
	s_setprio 1
	v_mfma_f32_16x16x32_bf16 v[50:53], v[162:165], v[178:181], v[50:53]
	v_mfma_f32_16x16x32_bf16 v[42:45], v[170:173], v[178:181], v[42:45]
	v_mfma_f32_16x16x32_bf16 v[34:37], v[162:165], v[186:189], v[34:37]
	v_mfma_f32_16x16x32_bf16 v[26:29], v[170:173], v[186:189], v[26:29]
	v_mfma_f32_16x16x32_bf16 v[18:21], v[162:165], v[194:197], v[18:21]
	v_mfma_f32_16x16x32_bf16 v[10:13], v[170:173], v[194:197], v[10:13]
	v_mfma_f32_16x16x32_bf16 v[6:9], v[162:165], v[202:205], v[6:9]
	v_mfma_f32_16x16x32_bf16 v[2:5], v[170:173], v[202:205], v[2:5]
	v_mfma_f32_16x16x32_bf16 v[50:53], v[166:169], v[182:185], v[50:53]
	v_mfma_f32_16x16x32_bf16 v[42:45], v[174:177], v[182:185], v[42:45]
	v_mfma_f32_16x16x32_bf16 v[34:37], v[166:169], v[190:193], v[34:37]
	v_mfma_f32_16x16x32_bf16 v[26:29], v[174:177], v[190:193], v[26:29]
	v_mfma_f32_16x16x32_bf16 v[18:21], v[166:169], v[198:201], v[18:21]
	v_mfma_f32_16x16x32_bf16 v[10:13], v[174:177], v[198:201], v[10:13]
	v_mfma_f32_16x16x32_bf16 v[6:9], v[166:169], v[206:209], v[6:9]
	v_mfma_f32_16x16x32_bf16 v[2:5], v[174:177], v[206:209], v[2:5]
	s_barrier
	s_setprio 0
	s_add_i32 s54, 0, 0x18000
	s_add_i32 s55, 0, 0x1c000
	v_add_u32_e32 v158, s54, v144
	v_add_u32_e32 v174, s55, v144
	ds_read_b128 v[146:149], v158
	ds_read_b128 v[150:153], v158 offset:1024
	ds_read_b128 v[154:157], v158 offset:2048
	ds_read_b128 v[158:161], v158 offset:3072
	ds_read_b128 v[162:165], v174
	ds_read_b128 v[166:169], v174 offset:1024
	ds_read_b128 v[170:173], v174 offset:2048
	ds_read_b128 v[174:177], v174 offset:3072
	s_add_u32 s26, s38, 0x180000
	s_addc_u32 s27, s39, 0
	s_mov_b32 m0, s43
	v_lshl_add_u64 v[216:217], s[26:27], 0, v[134:135]
	ds_read_b128 v[178:181], v145 offset:32768
	ds_read_b128 v[182:185], v145 offset:33792
	ds_read_b128 v[186:189], v145 offset:34816
	ds_read_b128 v[190:193], v145 offset:35840
	ds_read_b128 v[194:197], v145 offset:36864
	ds_read_b128 v[198:201], v145 offset:37888
	ds_read_b128 v[202:205], v145 offset:38912
	ds_read_b128 v[206:209], v145 offset:39936
	global_load_lds_dwordx4 v[216:217], off
	v_lshl_add_u64 v[216:217], s[26:27], 0, v[132:133]
	s_mov_b32 m0, s44
	s_nop 0
	global_load_lds_dwordx4 v[216:217], off
	s_waitcnt vmcnt(8)
	s_waitcnt lgkmcnt(0)
	s_barrier
	s_setprio 1
	v_mfma_f32_16x16x32_bf16 v[126:129], v[146:149], v[178:181], v[126:129]
	v_mfma_f32_16x16x32_bf16 v[122:125], v[154:157], v[178:181], v[122:125]
	v_mfma_f32_16x16x32_bf16 v[118:121], v[146:149], v[186:189], v[118:121]
	v_mfma_f32_16x16x32_bf16 v[110:113], v[154:157], v[186:189], v[110:113]
	v_mfma_f32_16x16x32_bf16 v[102:105], v[146:149], v[194:197], v[102:105]
	v_mfma_f32_16x16x32_bf16 v[94:97], v[154:157], v[194:197], v[94:97]
	v_mfma_f32_16x16x32_bf16 v[86:89], v[146:149], v[202:205], v[86:89]
	v_mfma_f32_16x16x32_bf16 v[78:81], v[154:157], v[202:205], v[78:81]
	v_mfma_f32_16x16x32_bf16 v[126:129], v[150:153], v[182:185], v[126:129]
	v_mfma_f32_16x16x32_bf16 v[122:125], v[158:161], v[182:185], v[122:125]
	v_mfma_f32_16x16x32_bf16 v[118:121], v[150:153], v[190:193], v[118:121]
	v_mfma_f32_16x16x32_bf16 v[110:113], v[158:161], v[190:193], v[110:113]
	v_mfma_f32_16x16x32_bf16 v[102:105], v[150:153], v[198:201], v[102:105]
	v_mfma_f32_16x16x32_bf16 v[94:97], v[158:161], v[198:201], v[94:97]
	v_mfma_f32_16x16x32_bf16 v[86:89], v[150:153], v[206:209], v[86:89]
	v_mfma_f32_16x16x32_bf16 v[78:81], v[158:161], v[206:209], v[78:81]
	s_setprio 0
	s_setprio 1
	v_mfma_f32_16x16x32_bf16 v[114:117], v[162:165], v[178:181], v[114:117]
	v_mfma_f32_16x16x32_bf16 v[106:109], v[170:173], v[178:181], v[106:109]
	v_mfma_f32_16x16x32_bf16 v[98:101], v[162:165], v[186:189], v[98:101]
	v_mfma_f32_16x16x32_bf16 v[90:93], v[170:173], v[186:189], v[90:93]
	v_mfma_f32_16x16x32_bf16 v[82:85], v[162:165], v[194:197], v[82:85]
	v_mfma_f32_16x16x32_bf16 v[74:77], v[170:173], v[194:197], v[74:77]
	v_mfma_f32_16x16x32_bf16 v[70:73], v[162:165], v[202:205], v[70:73]
	v_mfma_f32_16x16x32_bf16 v[66:69], v[170:173], v[202:205], v[66:69]
	v_mfma_f32_16x16x32_bf16 v[114:117], v[166:169], v[182:185], v[114:117]
	v_mfma_f32_16x16x32_bf16 v[106:109], v[174:177], v[182:185], v[106:109]
	v_mfma_f32_16x16x32_bf16 v[98:101], v[166:169], v[190:193], v[98:101]
	v_mfma_f32_16x16x32_bf16 v[90:93], v[174:177], v[190:193], v[90:93]
	v_mfma_f32_16x16x32_bf16 v[82:85], v[166:169], v[198:201], v[82:85]
	v_mfma_f32_16x16x32_bf16 v[74:77], v[174:177], v[198:201], v[74:77]
	v_mfma_f32_16x16x32_bf16 v[70:73], v[166:169], v[206:209], v[70:73]
	v_mfma_f32_16x16x32_bf16 v[66:69], v[174:177], v[206:209], v[66:69]
	s_barrier
; #define PG8_STAGE(bufoff, gbase, voff) do { _Pragma("unroll") for (int _i = 0; _i < 2; ++_i) \
;         __builtin_amdgcn_global_load_lds((const unsigned*)((const char*)(gbase) + (voff)[_i]), (LAS unsigned*)(lds + (bufoff) + ldsw + _i * 8192), 16, 0, 0); } while (0)
; #define PG8_LDA(dst, b, h) do { _Pragma("unroll") for (int m = 0; m < 4; ++m) _Pragma("unroll") for (int k = 0; k < 2; ++k) dst[m][k] = *(const LAS bf16x8*)(lds + PG8_SA(b, h) + aoff + m * 2048 + k * 1024); } while (0)
; #define PG8_MMA(ai, bj, At, Bt) do { __builtin_amdgcn_s_setprio(1); _Pragma("unroll") for (int m = 0; m < 4; ++m) _Pragma("unroll") for (int n = 0; n < 2; ++n) _Pragma("unroll") for (int k = 0; k < 2; ++k) \
;         acc[ai][bj][m][n] = __builtin_amdgcn_mfma_f32_16x16x32_bf16(Bt[n][k], At[m][k], acc[ai][bj][m][n], 0, 0, 0); __builtin_amdgcn_s_setprio(0); } while (0)
; #define PG8_WAIT_V(n) asm volatile("s_waitcnt vmcnt(" #n ")" ::: "memory")
; #define PG8_WAIT_L(n) asm volatile("s_waitcnt lgkmcnt(" #n ")" ::: "memory")
; #define PG8_BAR __builtin_amdgcn_s_barrier()
; #define PG8_SCHED __builtin_amdgcn_sched_barrier(0)
; template <class Epi, class Sched, bool ALIGN_EPI, bool LAST_FUSED = false, bool PERM = false, bool CARRY = false>
; __device__ __forceinline__ void gemm_phase(LAS unsigned char* lds, const int tid, const int K, const int lda, const int ldb, const Sched& S, const Epi& E) {
;     ...
;             PG8_LDA(At, 1, 1); PG8_STAGE(PG8_SB(1, 0), b3, voffB); PG8_STAGE(PG8_SB(1, 1), b3 + hstepB, voffB); PG8_STAGE(PG8_SA(1, 0), a3, voffA);
;             PG8_WAIT_V(8); PG8_WAIT_L(0); PG8_BAR; PG8_MMA(1, 0, At, B0); PG8_MMA(1, 1, At, B1); PG8_BAR; PG8_SCHED;
;         }
;         if constexpr (ALIGN_EPI) { if (wr == 0) PG8_BAR; }
	s_setprio 0
	s_add_i32 s26, s54, s40
	v_lshl_add_u64 v[140:141], v[140:141], 0, s[68:69]
	s_mov_b32 m0, s26
	ds_read_b128 v[178:181], v145 offset:49152
	ds_read_b128 v[182:185], v145 offset:50176
	ds_read_b128 v[186:189], v145 offset:51200
	ds_read_b128 v[190:193], v145 offset:52224
	ds_read_b128 v[194:197], v145 offset:53248
	ds_read_b128 v[198:201], v145 offset:54272
	ds_read_b128 v[202:205], v145 offset:55296
	ds_read_b128 v[206:209], v145 offset:56320
	global_load_lds_dwordx4 v[140:141], off
	s_add_i32 m0, s26, 0x2000
	s_add_u32 s26, s36, 0x30080
	v_lshl_add_u64 v[140:141], v[210:211], 0, s[68:69]
	s_addc_u32 s27, s37, 0
	s_add_i32 s36, s55, s40
	global_load_lds_dwordx4 v[140:141], off
	v_lshl_add_u64 v[140:141], s[26:27], 0, v[0:1]
	s_mov_b32 m0, s36
	s_nop 0
	global_load_lds_dwordx4 v[140:141], off
	v_lshl_add_u64 v[140:141], s[26:27], 0, v[130:131]
	s_add_i32 m0, s36, 0x2000
	s_nop 0
	global_load_lds_dwordx4 v[140:141], off
	v_lshl_add_u64 v[140:141], v[212:213], 0, s[68:69]
	s_mov_b32 m0, s46
	s_nop 0
	global_load_lds_dwordx4 v[140:141], off
	v_lshl_add_u64 v[140:141], v[214:215], 0, s[68:69]
	s_mov_b32 m0, s47
	s_nop 0
	global_load_lds_dwordx4 v[140:141], off
	s_waitcnt vmcnt(8)
	s_waitcnt lgkmcnt(0)
	s_barrier
	s_setprio 1
	v_mfma_f32_16x16x32_bf16 v[62:65], v[146:149], v[178:181], v[62:65]
	v_mfma_f32_16x16x32_bf16 v[58:61], v[154:157], v[178:181], v[58:61]
	v_mfma_f32_16x16x32_bf16 v[54:57], v[146:149], v[186:189], v[54:57]
	v_mfma_f32_16x16x32_bf16 v[46:49], v[154:157], v[186:189], v[46:49]
	v_mfma_f32_16x16x32_bf16 v[38:41], v[146:149], v[194:197], v[38:41]
	v_mfma_f32_16x16x32_bf16 v[30:33], v[154:157], v[194:197], v[30:33]
	v_mfma_f32_16x16x32_bf16 v[22:25], v[146:149], v[202:205], v[22:25]
	v_mfma_f32_16x16x32_bf16 v[14:17], v[154:157], v[202:205], v[14:17]
	v_mfma_f32_16x16x32_bf16 v[62:65], v[150:153], v[182:185], v[62:65]
	v_mfma_f32_16x16x32_bf16 v[58:61], v[158:161], v[182:185], v[58:61]
	v_mfma_f32_16x16x32_bf16 v[54:57], v[150:153], v[190:193], v[54:57]
	v_mfma_f32_16x16x32_bf16 v[46:49], v[158:161], v[190:193], v[46:49]
	v_mfma_f32_16x16x32_bf16 v[38:41], v[150:153], v[198:201], v[38:41]
	v_mfma_f32_16x16x32_bf16 v[30:33], v[158:161], v[198:201], v[30:33]
	v_mfma_f32_16x16x32_bf16 v[22:25], v[150:153], v[206:209], v[22:25]
	v_mfma_f32_16x16x32_bf16 v[14:17], v[158:161], v[206:209], v[14:17]
	s_setprio 0
	s_setprio 1
	v_mfma_f32_16x16x32_bf16 v[50:53], v[162:165], v[178:181], v[50:53]
	v_mfma_f32_16x16x32_bf16 v[42:45], v[170:173], v[178:181], v[42:45]
	v_mfma_f32_16x16x32_bf16 v[34:37], v[162:165], v[186:189], v[34:37]
	v_mfma_f32_16x16x32_bf16 v[26:29], v[170:173], v[186:189], v[26:29]
	v_mfma_f32_16x16x32_bf16 v[18:21], v[162:165], v[194:197], v[18:21]
	v_mfma_f32_16x16x32_bf16 v[10:13], v[170:173], v[194:197], v[10:13]
	v_mfma_f32_16x16x32_bf16 v[6:9], v[162:165], v[202:205], v[6:9]
	v_mfma_f32_16x16x32_bf16 v[2:5], v[170:173], v[202:205], v[2:5]
	v_mfma_f32_16x16x32_bf16 v[50:53], v[166:169], v[182:185], v[50:53]
	v_mfma_f32_16x16x32_bf16 v[42:45], v[174:177], v[182:185], v[42:45]
	v_mfma_f32_16x16x32_bf16 v[34:37], v[166:169], v[190:193], v[34:37]
	v_mfma_f32_16x16x32_bf16 v[26:29], v[174:177], v[190:193], v[26:29]
	v_mfma_f32_16x16x32_bf16 v[18:21], v[166:169], v[198:201], v[18:21]
	v_mfma_f32_16x16x32_bf16 v[10:13], v[174:177], v[198:201], v[10:13]
	v_mfma_f32_16x16x32_bf16 v[6:9], v[166:169], v[206:209], v[6:9]
	v_mfma_f32_16x16x32_bf16 v[2:5], v[174:177], v[206:209], v[2:5]
	s_barrier
	s_setprio 0
	s_add_i32 s53, s53, 2
	s_add_u32 s13, s13, 0x100
	s_addc_u32 s52, s52, 0
	s_cmp_gt_u32 s53, 9
	s_mov_b64 s[26:27], s[30:31]
	s_cbranch_scc0 .LBB0_705
	s_and_b64 vcc, exec, s[10:11]
	s_cbranch_vccz .LBB0_708
	s_barrier

; #define PG8_STAGE(bufoff, gbase, voff) do { _Pragma("unroll") for (int _i = 0; _i < 2; ++_i) \
;         __builtin_amdgcn_global_load_lds((const unsigned*)((const char*)(gbase) + (voff)[_i]), (LAS unsigned*)(lds + (bufoff) + ldsw + _i * 8192), 16, 0, 0); } while (0)
; #define PG8_LDA(dst, b, h) do { _Pragma("unroll") for (int m = 0; m < 4; ++m) _Pragma("unroll") for (int k = 0; k < 2; ++k) dst[m][k] = *(const LAS bf16x8*)(lds + PG8_SA(b, h) + aoff + m * 2048 + k * 1024); } while (0)
; #define PG8_LDB(dst, b, h) do { _Pragma("unroll") for (int n = 0; n < 2; ++n) _Pragma("unroll") for (int k = 0; k < 2; ++k) dst[n][k] = *(const LAS bf16x8*)(lds + PG8_SB(b, h) + boff + n * 2048 + k * 1024); } while (0)
; #define PG8_WAIT_V(n) asm volatile("s_waitcnt vmcnt(" #n ")" ::: "memory")
; #define PG8_WAIT_L(n) asm volatile("s_waitcnt lgkmcnt(" #n ")" ::: "memory")
; #define PG8_BAR __builtin_amdgcn_s_barrier()
; #define PG8_SCHED __builtin_amdgcn_sched_barrier(0)
; template <class Epi, class Sched, bool ALIGN_EPI, bool LAST_FUSED = false, bool PERM = false, bool CARRY = false>
; __device__ __forceinline__ void gemm_phase(LAS unsigned char* lds, const int tid, const int K, const int lda, const int ldb, const Sched& S, const Epi& E) {
;     ...
;         const bool has_next = S.next(KD_IDX(ui + 1), nxt);
;         const char* nA = has_next ? nxt.a : cA; const char* nB = has_next ? nxt.b : cB; const int nt = cur.nt;
; #pragma unroll 1
;         for (int t = 0; t < nt; t += 2) {
;             const bool last = (t == nt - 2);
;             const char* a1 = cA + (size_t)(t + 1) * kstep;
;             const char* a2 = last ? nA : cA + (size_t)(t + 2) * kstep; const char* b2 = last ? nB : cB + (size_t)(t + 2) * kstep;
;             const char* a3 = a2 + kstep; const char* b3 = b2 + kstep;
;             PG8_LDB(B0, 0, 0); PG8_LDB(B1, 0, 1); PG8_SCHED; PG8_LDA(At, 0, 0); PG8_STAGE(PG8_SA(1, 1), a1 + hstepA, voffA);
;             PG8_WAIT_V(8); PG8_WAIT_L(0); PG8_BAR; PG8_MMA(0, 0, At, B0); PG8_MMA(0, 1, At, B1); PG8_BAR; PG8_SCHED;
;             PG8_LDA(At, 0, 1); PG8_STAGE(PG8_SB(0, 0), b2, voffB); PG8_STAGE(PG8_SB(0, 1), b2 + hstepB, voffB); PG8_STAGE(PG8_SA(0, 0), a2, voffA);
;             PG8_WAIT_V(8); PG8_WAIT_L(0); PG8_BAR; PG8_MMA(1, 0, At, B0); PG8_MMA(1, 1, At, B1); PG8_BAR; PG8_SCHED;
.LBB0_838:
	s_add_u32 s6, s4, 0xfff80080
	s_addc_u32 s7, s5, -1
	s_add_i32 s29, 0, 0x10000
	s_cmp_eq_u32 s28, 28
	s_cselect_b32 s37, s43, s7
	s_cselect_b32 s36, s42, s6
	v_add_u32_e32 v140, s29, v146
	s_cselect_b32 s7, s71, s23
	s_cselect_b32 s6, s70, s22
	s_add_i32 s31, 0, 0x14000
	ds_read_b128 v[136:139], v140
	ds_read_b128 v[148:151], v140 offset:1024
	ds_read_b128 v[152:155], v140 offset:2048
	ds_read_b128 v[156:159], v140 offset:3072
	v_add_u32_e32 v140, s31, v146
	ds_read_b128 v[160:163], v140
	ds_read_b128 v[164:167], v140 offset:1024
	ds_read_b128 v[168:171], v140 offset:2048
	ds_read_b128 v[172:175], v140 offset:3072
	v_lshl_add_u64 v[140:141], s[4:5], 0, v[132:133]
	s_add_i32 m0, s50, 0xc000
	ds_read_b128 v[176:179], v147
	ds_read_b128 v[180:183], v147 offset:1024
	ds_read_b128 v[184:187], v147 offset:2048
	ds_read_b128 v[188:191], v147 offset:3072
	ds_read_b128 v[192:195], v147 offset:4096
	ds_read_b128 v[196:199], v147 offset:5120
	ds_read_b128 v[200:203], v147 offset:6144
	ds_read_b128 v[204:207], v147 offset:7168
	global_load_lds_dwordx4 v[140:141], off
	v_lshl_add_u64 v[140:141], s[4:5], 0, v[134:135]
	s_add_i32 m0, s50, 0xe000
	s_nop 0
	global_load_lds_dwordx4 v[140:141], off
	s_waitcnt vmcnt(8)
	s_waitcnt lgkmcnt(0)
	s_barrier
	s_setprio 1
	v_mfma_f32_16x16x32_bf16 v[126:129], v[136:139], v[176:179], v[126:129]
	v_mfma_f32_16x16x32_bf16 v[122:125], v[152:155], v[176:179], v[122:125]
	v_mfma_f32_16x16x32_bf16 v[110:113], v[136:139], v[184:187], v[110:113]
	v_mfma_f32_16x16x32_bf16 v[106:109], v[152:155], v[184:187], v[106:109]
	v_mfma_f32_16x16x32_bf16 v[94:97], v[136:139], v[192:195], v[94:97]
	v_mfma_f32_16x16x32_bf16 v[90:93], v[152:155], v[192:195], v[90:93]
	v_mfma_f32_16x16x32_bf16 v[78:81], v[136:139], v[200:203], v[78:81]
	v_mfma_f32_16x16x32_bf16 v[74:77], v[152:155], v[200:203], v[74:77]
	v_mfma_f32_16x16x32_bf16 v[126:129], v[148:151], v[180:183], v[126:129]
	v_mfma_f32_16x16x32_bf16 v[122:125], v[156:159], v[180:183], v[122:125]
	v_mfma_f32_16x16x32_bf16 v[110:113], v[148:151], v[188:191], v[110:113]
	v_mfma_f32_16x16x32_bf16 v[106:109], v[156:159], v[188:191], v[106:109]
	v_mfma_f32_16x16x32_bf16 v[94:97], v[148:151], v[196:199], v[94:97]
	v_mfma_f32_16x16x32_bf16 v[90:93], v[156:159], v[196:199], v[90:93]
	v_mfma_f32_16x16x32_bf16 v[78:81], v[148:151], v[204:207], v[78:81]
	v_mfma_f32_16x16x32_bf16 v[74:77], v[156:159], v[204:207], v[74:77]
	s_setprio 0
	s_setprio 1
	v_mfma_f32_16x16x32_bf16 v[118:121], v[160:163], v[176:179], v[118:121]
	v_mfma_f32_16x16x32_bf16 v[114:117], v[168:171], v[176:179], v[114:117]
	v_mfma_f32_16x16x32_bf16 v[102:105], v[160:163], v[184:187], v[102:105]
	v_mfma_f32_16x16x32_bf16 v[98:101], v[168:171], v[184:187], v[98:101]
	v_mfma_f32_16x16x32_bf16 v[86:89], v[160:163], v[192:195], v[86:89]
	v_mfma_f32_16x16x32_bf16 v[82:85], v[168:171], v[192:195], v[82:85]
	v_mfma_f32_16x16x32_bf16 v[70:73], v[160:163], v[200:203], v[70:73]
	v_mfma_f32_16x16x32_bf16 v[66:69], v[168:171], v[200:203], v[66:69]
	v_mfma_f32_16x16x32_bf16 v[118:121], v[164:167], v[180:183], v[118:121]
	v_mfma_f32_16x16x32_bf16 v[114:117], v[172:175], v[180:183], v[114:117]
	v_mfma_f32_16x16x32_bf16 v[102:105], v[164:167], v[188:191], v[102:105]
	v_mfma_f32_16x16x32_bf16 v[98:101], v[172:175], v[188:191], v[98:101]
	v_mfma_f32_16x16x32_bf16 v[86:89], v[164:167], v[196:199], v[86:89]
	v_mfma_f32_16x16x32_bf16 v[82:85], v[172:175], v[196:199], v[82:85]
	v_mfma_f32_16x16x32_bf16 v[70:73], v[164:167], v[204:207], v[70:73]
	v_mfma_f32_16x16x32_bf16 v[66:69], v[172:175], v[204:207], v[66:69]
	s_barrier
	s_setprio 0
	s_add_i32 s29, s29, s49
	v_lshl_add_u64 v[140:141], s[6:7], 0, v[0:1]
	s_mov_b32 m0, s29
	ds_read_b128 v[176:179], v147 offset:16384
	ds_read_b128 v[180:183], v147 offset:17408
	ds_read_b128 v[184:187], v147 offset:18432
	ds_read_b128 v[188:191], v147 offset:19456
	ds_read_b128 v[192:195], v147 offset:20480
	ds_read_b128 v[196:199], v147 offset:21504
	ds_read_b128 v[200:203], v147 offset:22528
	ds_read_b128 v[204:207], v147 offset:23552
	global_load_lds_dwordx4 v[140:141], off
	s_add_i32 m0, s29, 0x2000
	s_add_u32 s44, s6, 0x80000
	v_lshl_add_u64 v[208:209], s[6:7], 0, v[130:131]
	s_addc_u32 s45, s7, 0
	s_add_i32 s29, s31, s49
	global_load_lds_dwordx4 v[208:209], off
	v_lshl_add_u64 v[210:211], s[44:45], 0, v[0:1]
	s_mov_b32 m0, s29
	v_lshl_add_u64 v[212:213], s[36:37], 0, v[130:131]
	global_load_lds_dwordx4 v[210:211], off
	v_lshl_add_u64 v[210:211], s[44:45], 0, v[130:131]
	s_add_i32 m0, s29, 0x2000
	s_nop 0
	global_load_lds_dwordx4 v[210:211], off
	v_lshl_add_u64 v[210:211], s[36:37], 0, v[0:1]
	s_mov_b32 m0, s50
	s_nop 0
	global_load_lds_dwordx4 v[210:211], off
	s_mov_b32 m0, s51
	s_nop 0
	global_load_lds_dwordx4 v[212:213], off
	s_waitcnt vmcnt(8)
	s_waitcnt lgkmcnt(0)
	s_barrier
; #define PG8_STAGE(bufoff, gbase, voff) do { _Pragma("unroll") for (int _i = 0; _i < 2; ++_i) \
;         __builtin_amdgcn_global_load_lds((const unsigned*)((const char*)(gbase) + (voff)[_i]), (LAS unsigned*)(lds + (bufoff) + ldsw + _i * 8192), 16, 0, 0); } while (0)
; #define PG8_LDA(dst, b, h) do { _Pragma("unroll") for (int m = 0; m < 4; ++m) _Pragma("unroll") for (int k = 0; k < 2; ++k) dst[m][k] = *(const LAS bf16x8*)(lds + PG8_SA(b, h) + aoff + m * 2048 + k * 1024); } while (0)
; #define PG8_LDB(dst, b, h) do { _Pragma("unroll") for (int n = 0; n < 2; ++n) _Pragma("unroll") for (int k = 0; k < 2; ++k) dst[n][k] = *(const LAS bf16x8*)(lds + PG8_SB(b, h) + boff + n * 2048 + k * 1024); } while (0)
; #define PG8_MMA(ai, bj, At, Bt) do { __builtin_amdgcn_s_setprio(1); _Pragma("unroll") for (int m = 0; m < 4; ++m) _Pragma("unroll") for (int n = 0; n < 2; ++n) _Pragma("unroll") for (int k = 0; k < 2; ++k) \
;         acc[ai][bj][m][n] = __builtin_amdgcn_mfma_f32_16x16x32_bf16(Bt[n][k], At[m][k], acc[ai][bj][m][n], 0, 0, 0); __builtin_amdgcn_s_setprio(0); } while (0)
; #define PG8_WAIT_V(n) asm volatile("s_waitcnt vmcnt(" #n ")" ::: "memory")
; #define PG8_WAIT_L(n) asm volatile("s_waitcnt lgkmcnt(" #n ")" ::: "memory")
; #define PG8_BAR __builtin_amdgcn_s_barrier()
; #define PG8_SCHED __builtin_amdgcn_sched_barrier(0)
; template <class Epi, class Sched, bool ALIGN_EPI, bool LAST_FUSED = false, bool PERM = false, bool CARRY = false>
; __device__ __forceinline__ void gemm_phase(LAS unsigned char* lds, const int tid, const int K, const int lda, const int ldb, const Sched& S, const Epi& E) {
;     ...
;             PG8_WAIT_V(8); PG8_WAIT_L(0); PG8_BAR; PG8_MMA(1, 0, At, B0); PG8_MMA(1, 1, At, B1); PG8_BAR; PG8_SCHED;
;             PG8_LDB(B0, 1, 0); PG8_LDB(B1, 1, 1); PG8_SCHED; PG8_LDA(At, 1, 0); PG8_STAGE(PG8_SA(0, 1), a2 + hstepA, voffA);
;             PG8_WAIT_V(8); PG8_WAIT_L(0); PG8_BAR; PG8_MMA(0, 0, At, B0); PG8_MMA(0, 1, At, B1); PG8_BAR; PG8_SCHED;
;             PG8_LDA(At, 1, 1); PG8_STAGE(PG8_SB(1, 0), b3, voffB); PG8_STAGE(PG8_SB(1, 1), b3 + hstepB, voffB); PG8_STAGE(PG8_SA(1, 0), a3, voffA);
;             PG8_WAIT_V(8); PG8_WAIT_L(0); PG8_BAR; PG8_MMA(1, 0, At, B0); PG8_MMA(1, 1, At, B1); PG8_BAR; PG8_SCHED;
	s_setprio 1
	v_mfma_f32_16x16x32_bf16 v[62:65], v[136:139], v[176:179], v[62:65]
	v_mfma_f32_16x16x32_bf16 v[58:61], v[152:155], v[176:179], v[58:61]
	v_mfma_f32_16x16x32_bf16 v[46:49], v[136:139], v[184:187], v[46:49]
	v_mfma_f32_16x16x32_bf16 v[42:45], v[152:155], v[184:187], v[42:45]
	v_mfma_f32_16x16x32_bf16 v[30:33], v[136:139], v[192:195], v[30:33]
	v_mfma_f32_16x16x32_bf16 v[26:29], v[152:155], v[192:195], v[26:29]
	v_mfma_f32_16x16x32_bf16 v[14:17], v[136:139], v[200:203], v[14:17]
	v_mfma_f32_16x16x32_bf16 v[10:13], v[152:155], v[200:203], v[10:13]
	v_mfma_f32_16x16x32_bf16 v[62:65], v[148:151], v[180:183], v[62:65]
	v_mfma_f32_16x16x32_bf16 v[58:61], v[156:159], v[180:183], v[58:61]
	v_mfma_f32_16x16x32_bf16 v[46:49], v[148:151], v[188:191], v[46:49]
	v_mfma_f32_16x16x32_bf16 v[42:45], v[156:159], v[188:191], v[42:45]
	v_mfma_f32_16x16x32_bf16 v[30:33], v[148:151], v[196:199], v[30:33]
	v_mfma_f32_16x16x32_bf16 v[26:29], v[156:159], v[196:199], v[26:29]
	v_mfma_f32_16x16x32_bf16 v[14:17], v[148:151], v[204:207], v[14:17]
	v_mfma_f32_16x16x32_bf16 v[10:13], v[156:159], v[204:207], v[10:13]
	s_setprio 0
	s_setprio 1
	v_mfma_f32_16x16x32_bf16 v[54:57], v[160:163], v[176:179], v[54:57]
	v_mfma_f32_16x16x32_bf16 v[50:53], v[168:171], v[176:179], v[50:53]
	v_mfma_f32_16x16x32_bf16 v[38:41], v[160:163], v[184:187], v[38:41]
	v_mfma_f32_16x16x32_bf16 v[34:37], v[168:171], v[184:187], v[34:37]
	v_mfma_f32_16x16x32_bf16 v[22:25], v[160:163], v[192:195], v[22:25]
	v_mfma_f32_16x16x32_bf16 v[18:21], v[168:171], v[192:195], v[18:21]
	v_mfma_f32_16x16x32_bf16 v[6:9], v[160:163], v[200:203], v[6:9]
	v_mfma_f32_16x16x32_bf16 v[2:5], v[168:171], v[200:203], v[2:5]
	v_mfma_f32_16x16x32_bf16 v[54:57], v[164:167], v[180:183], v[54:57]
	v_mfma_f32_16x16x32_bf16 v[50:53], v[172:175], v[180:183], v[50:53]
	v_mfma_f32_16x16x32_bf16 v[38:41], v[164:167], v[188:191], v[38:41]
	v_mfma_f32_16x16x32_bf16 v[34:37], v[172:175], v[188:191], v[34:37]
	v_mfma_f32_16x16x32_bf16 v[22:25], v[164:167], v[196:199], v[22:25]
	v_mfma_f32_16x16x32_bf16 v[18:21], v[172:175], v[196:199], v[18:21]
	v_mfma_f32_16x16x32_bf16 v[6:9], v[164:167], v[204:207], v[6:9]
	v_mfma_f32_16x16x32_bf16 v[2:5], v[172:175], v[204:207], v[2:5]
	s_barrier
	s_setprio 0
	s_add_i32 s29, 0, 0x18000
	s_add_i32 s31, 0, 0x1c000
	v_add_u32_e32 v156, s29, v146
	v_add_u32_e32 v172, s31, v146
	ds_read_b128 v[136:139], v156
	ds_read_b128 v[148:151], v156 offset:1024
	ds_read_b128 v[152:155], v156 offset:2048
	ds_read_b128 v[156:159], v156 offset:3072
	ds_read_b128 v[160:163], v172
	ds_read_b128 v[164:167], v172 offset:1024
	ds_read_b128 v[168:171], v172 offset:2048
	ds_read_b128 v[172:175], v172 offset:3072
	s_add_u32 s36, s36, 0x80000
	s_addc_u32 s37, s37, 0
	s_mov_b32 m0, s52
	v_lshl_add_u64 v[214:215], s[36:37], 0, v[0:1]
	ds_read_b128 v[176:179], v147 offset:32768
	ds_read_b128 v[180:183], v147 offset:33792
	ds_read_b128 v[184:187], v147 offset:34816
	ds_read_b128 v[188:191], v147 offset:35840
	ds_read_b128 v[192:195], v147 offset:36864
	ds_read_b128 v[196:199], v147 offset:37888
	ds_read_b128 v[200:203], v147 offset:38912
	ds_read_b128 v[204:207], v147 offset:39936
	global_load_lds_dwordx4 v[214:215], off
	v_lshl_add_u64 v[214:215], s[36:37], 0, v[130:131]
	s_mov_b32 m0, s53
	s_nop 0
	global_load_lds_dwordx4 v[214:215], off
	s_waitcnt vmcnt(8)
	s_waitcnt lgkmcnt(0)
	s_barrier
	s_setprio 1
	v_mfma_f32_16x16x32_bf16 v[126:129], v[136:139], v[176:179], v[126:129]
	v_mfma_f32_16x16x32_bf16 v[122:125], v[152:155], v[176:179], v[122:125]
	v_mfma_f32_16x16x32_bf16 v[110:113], v[136:139], v[184:187], v[110:113]
	v_mfma_f32_16x16x32_bf16 v[106:109], v[152:155], v[184:187], v[106:109]
	v_mfma_f32_16x16x32_bf16 v[94:97], v[136:139], v[192:195], v[94:97]
	v_mfma_f32_16x16x32_bf16 v[90:93], v[152:155], v[192:195], v[90:93]
	v_mfma_f32_16x16x32_bf16 v[78:81], v[136:139], v[200:203], v[78:81]
	v_mfma_f32_16x16x32_bf16 v[74:77], v[152:155], v[200:203], v[74:77]
	v_mfma_f32_16x16x32_bf16 v[126:129], v[148:151], v[180:183], v[126:129]
	v_mfma_f32_16x16x32_bf16 v[122:125], v[156:159], v[180:183], v[122:125]
	v_mfma_f32_16x16x32_bf16 v[110:113], v[148:151], v[188:191], v[110:113]
	v_mfma_f32_16x16x32_bf16 v[106:109], v[156:159], v[188:191], v[106:109]
	v_mfma_f32_16x16x32_bf16 v[94:97], v[148:151], v[196:199], v[94:97]
	v_mfma_f32_16x16x32_bf16 v[90:93], v[156:159], v[196:199], v[90:93]
	v_mfma_f32_16x16x32_bf16 v[78:81], v[148:151], v[204:207], v[78:81]
	v_mfma_f32_16x16x32_bf16 v[74:77], v[156:159], v[204:207], v[74:77]
	s_setprio 0
	s_setprio 1
	v_mfma_f32_16x16x32_bf16 v[118:121], v[160:163], v[176:179], v[118:121]
	v_mfma_f32_16x16x32_bf16 v[114:117], v[168:171], v[176:179], v[114:117]
	v_mfma_f32_16x16x32_bf16 v[102:105], v[160:163], v[184:187], v[102:105]
	v_mfma_f32_16x16x32_bf16 v[98:101], v[168:171], v[184:187], v[98:101]
	v_mfma_f32_16x16x32_bf16 v[86:89], v[160:163], v[192:195], v[86:89]
	v_mfma_f32_16x16x32_bf16 v[82:85], v[168:171], v[192:195], v[82:85]
	v_mfma_f32_16x16x32_bf16 v[70:73], v[160:163], v[200:203], v[70:73]
	v_mfma_f32_16x16x32_bf16 v[66:69], v[168:171], v[200:203], v[66:69]
	v_mfma_f32_16x16x32_bf16 v[118:121], v[164:167], v[180:183], v[118:121]
	v_mfma_f32_16x16x32_bf16 v[114:117], v[172:175], v[180:183], v[114:117]
	v_mfma_f32_16x16x32_bf16 v[102:105], v[164:167], v[188:191], v[102:105]
	v_mfma_f32_16x16x32_bf16 v[98:101], v[172:175], v[188:191], v[98:101]
	v_mfma_f32_16x16x32_bf16 v[86:89], v[164:167], v[196:199], v[86:89]
	v_mfma_f32_16x16x32_bf16 v[82:85], v[172:175], v[196:199], v[82:85]
	v_mfma_f32_16x16x32_bf16 v[70:73], v[164:167], v[204:207], v[70:73]
	v_mfma_f32_16x16x32_bf16 v[66:69], v[172:175], v[204:207], v[66:69]
	s_barrier
; #define PG8_STAGE(bufoff, gbase, voff) do { _Pragma("unroll") for (int _i = 0; _i < 2; ++_i) \
;         __builtin_amdgcn_global_load_lds((const unsigned*)((const char*)(gbase) + (voff)[_i]), (LAS unsigned*)(lds + (bufoff) + ldsw + _i * 8192), 16, 0, 0); } while (0)
; #define PG8_LDA(dst, b, h) do { _Pragma("unroll") for (int m = 0; m < 4; ++m) _Pragma("unroll") for (int k = 0; k < 2; ++k) dst[m][k] = *(const LAS bf16x8*)(lds + PG8_SA(b, h) + aoff + m * 2048 + k * 1024); } while (0)
; #define PG8_MMA(ai, bj, At, Bt) do { __builtin_amdgcn_s_setprio(1); _Pragma("unroll") for (int m = 0; m < 4; ++m) _Pragma("unroll") for (int n = 0; n < 2; ++n) _Pragma("unroll") for (int k = 0; k < 2; ++k) \
;         acc[ai][bj][m][n] = __builtin_amdgcn_mfma_f32_16x16x32_bf16(Bt[n][k], At[m][k], acc[ai][bj][m][n], 0, 0, 0); __builtin_amdgcn_s_setprio(0); } while (0)
; #define PG8_WAIT_V(n) asm volatile("s_waitcnt vmcnt(" #n ")" ::: "memory")
; #define PG8_WAIT_L(n) asm volatile("s_waitcnt lgkmcnt(" #n ")" ::: "memory")
; #define PG8_BAR __builtin_amdgcn_s_barrier()
; #define PG8_SCHED __builtin_amdgcn_sched_barrier(0)
; template <class Epi, class Sched, bool ALIGN_EPI, bool LAST_FUSED = false, bool PERM = false, bool CARRY = false>
; __device__ __forceinline__ void gemm_phase(LAS unsigned char* lds, const int tid, const int K, const int lda, const int ldb, const Sched& S, const Epi& E) {
;     ...
;             PG8_LDA(At, 1, 1); PG8_STAGE(PG8_SB(1, 0), b3, voffB); PG8_STAGE(PG8_SB(1, 1), b3 + hstepB, voffB); PG8_STAGE(PG8_SA(1, 0), a3, voffA);
;             PG8_WAIT_V(8); PG8_WAIT_L(0); PG8_BAR; PG8_MMA(1, 0, At, B0); PG8_MMA(1, 1, At, B1); PG8_BAR; PG8_SCHED;
;         }
;         if constexpr (ALIGN_EPI) { if (wr == 0) PG8_BAR; }
	s_setprio 0
	s_add_i32 s29, s29, s49
	v_lshl_add_u64 v[140:141], v[140:141], 0, s[68:69]
	s_mov_b32 m0, s29
	ds_read_b128 v[176:179], v147 offset:49152
	ds_read_b128 v[180:183], v147 offset:50176
	ds_read_b128 v[184:187], v147 offset:51200
	ds_read_b128 v[188:191], v147 offset:52224
	ds_read_b128 v[192:195], v147 offset:53248
	ds_read_b128 v[196:199], v147 offset:54272
	ds_read_b128 v[200:203], v147 offset:55296
	ds_read_b128 v[204:207], v147 offset:56320
	global_load_lds_dwordx4 v[140:141], off
	s_add_i32 m0, s29, 0x2000
	s_add_u32 s6, s6, 0x80080
	v_lshl_add_u64 v[140:141], v[208:209], 0, s[68:69]
	s_addc_u32 s7, s7, 0
	s_add_i32 s29, s31, s49
	global_load_lds_dwordx4 v[140:141], off
	v_lshl_add_u64 v[140:141], s[6:7], 0, v[0:1]
	s_mov_b32 m0, s29
	s_nop 0
	global_load_lds_dwordx4 v[140:141], off
	v_lshl_add_u64 v[140:141], s[6:7], 0, v[130:131]
	s_add_i32 m0, s29, 0x2000
	s_nop 0
	global_load_lds_dwordx4 v[140:141], off
	v_lshl_add_u64 v[140:141], v[210:211], 0, s[68:69]
	s_mov_b32 m0, s55
	s_nop 0
	global_load_lds_dwordx4 v[140:141], off
	v_lshl_add_u64 v[140:141], v[212:213], 0, s[68:69]
	s_mov_b32 m0, s56
	s_nop 0
	global_load_lds_dwordx4 v[140:141], off
	s_waitcnt vmcnt(8)
	s_waitcnt lgkmcnt(0)
	s_barrier
	s_setprio 1
	v_mfma_f32_16x16x32_bf16 v[62:65], v[136:139], v[176:179], v[62:65]
	v_mfma_f32_16x16x32_bf16 v[58:61], v[152:155], v[176:179], v[58:61]
	v_mfma_f32_16x16x32_bf16 v[46:49], v[136:139], v[184:187], v[46:49]
	v_mfma_f32_16x16x32_bf16 v[42:45], v[152:155], v[184:187], v[42:45]
	v_mfma_f32_16x16x32_bf16 v[30:33], v[136:139], v[192:195], v[30:33]
	v_mfma_f32_16x16x32_bf16 v[26:29], v[152:155], v[192:195], v[26:29]
	v_mfma_f32_16x16x32_bf16 v[14:17], v[136:139], v[200:203], v[14:17]
	v_mfma_f32_16x16x32_bf16 v[10:13], v[152:155], v[200:203], v[10:13]
	v_mfma_f32_16x16x32_bf16 v[62:65], v[148:151], v[180:183], v[62:65]
	v_mfma_f32_16x16x32_bf16 v[58:61], v[156:159], v[180:183], v[58:61]
	v_mfma_f32_16x16x32_bf16 v[46:49], v[148:151], v[188:191], v[46:49]
	v_mfma_f32_16x16x32_bf16 v[42:45], v[156:159], v[188:191], v[42:45]
	v_mfma_f32_16x16x32_bf16 v[30:33], v[148:151], v[196:199], v[30:33]
	v_mfma_f32_16x16x32_bf16 v[26:29], v[156:159], v[196:199], v[26:29]
	v_mfma_f32_16x16x32_bf16 v[14:17], v[148:151], v[204:207], v[14:17]
	v_mfma_f32_16x16x32_bf16 v[10:13], v[156:159], v[204:207], v[10:13]
	s_setprio 0
	s_setprio 1
	v_mfma_f32_16x16x32_bf16 v[54:57], v[160:163], v[176:179], v[54:57]
	v_mfma_f32_16x16x32_bf16 v[50:53], v[168:171], v[176:179], v[50:53]
	v_mfma_f32_16x16x32_bf16 v[38:41], v[160:163], v[184:187], v[38:41]
	v_mfma_f32_16x16x32_bf16 v[34:37], v[168:171], v[184:187], v[34:37]
	v_mfma_f32_16x16x32_bf16 v[22:25], v[160:163], v[192:195], v[22:25]
	v_mfma_f32_16x16x32_bf16 v[18:21], v[168:171], v[192:195], v[18:21]
	v_mfma_f32_16x16x32_bf16 v[6:9], v[160:163], v[200:203], v[6:9]
	v_mfma_f32_16x16x32_bf16 v[2:5], v[168:171], v[200:203], v[2:5]
	v_mfma_f32_16x16x32_bf16 v[54:57], v[164:167], v[180:183], v[54:57]
	v_mfma_f32_16x16x32_bf16 v[50:53], v[172:175], v[180:183], v[50:53]
	v_mfma_f32_16x16x32_bf16 v[38:41], v[164:167], v[188:191], v[38:41]
	v_mfma_f32_16x16x32_bf16 v[34:37], v[172:175], v[188:191], v[34:37]
	v_mfma_f32_16x16x32_bf16 v[22:25], v[164:167], v[196:199], v[22:25]
	v_mfma_f32_16x16x32_bf16 v[18:21], v[172:175], v[196:199], v[18:21]
	v_mfma_f32_16x16x32_bf16 v[6:9], v[164:167], v[204:207], v[6:9]
	v_mfma_f32_16x16x32_bf16 v[2:5], v[172:175], v[204:207], v[2:5]
	s_barrier
	s_setprio 0
	s_add_i32 s28, s28, 2
	s_add_u32 s4, s4, 0x100
	s_addc_u32 s5, s5, 0
	s_add_u32 s22, s22, 0x100
	s_addc_u32 s23, s23, 0
	s_cmp_gt_u32 s28, 29
	s_cbranch_scc0 .LBB0_838
	s_and_b64 vcc, exec, s[26:27]
	s_cbranch_vccz .LBB0_841
	s_barrier

; #define PG8_STAGE(bufoff, gbase, voff) do { _Pragma("unroll") for (int _i = 0; _i < 2; ++_i) \
;         __builtin_amdgcn_global_load_lds((const unsigned*)((const char*)(gbase) + (voff)[_i]), (LAS unsigned*)(lds + (bufoff) + ldsw + _i * 8192), 16, 0, 0); } while (0)
; #define PG8_LDA(dst, b, h) do { _Pragma("unroll") for (int m = 0; m < 4; ++m) _Pragma("unroll") for (int k = 0; k < 2; ++k) dst[m][k] = *(const LAS bf16x8*)(lds + PG8_SA(b, h) + aoff + m * 2048 + k * 1024); } while (0)
; #define PG8_LDB(dst, b, h) do { _Pragma("unroll") for (int n = 0; n < 2; ++n) _Pragma("unroll") for (int k = 0; k < 2; ++k) dst[n][k] = *(const LAS bf16x8*)(lds + PG8_SB(b, h) + boff + n * 2048 + k * 1024); } while (0)
; #define PG8_WAIT_V(n) asm volatile("s_waitcnt vmcnt(" #n ")" ::: "memory")
; #define PG8_WAIT_L(n) asm volatile("s_waitcnt lgkmcnt(" #n ")" ::: "memory")
; #define PG8_BAR __builtin_amdgcn_s_barrier()
; #define PG8_SCHED __builtin_amdgcn_sched_barrier(0)
; template <class Epi, class Sched, bool ALIGN_EPI, bool LAST_FUSED = false, bool PERM = false, bool CARRY = false>
; __device__ __forceinline__ void gemm_phase(LAS unsigned char* lds, const int tid, const int K, const int lda, const int ldb, const Sched& S, const Epi& E) {
;     ...
;         const bool has_next = S.next(KD_IDX(ui + 1), nxt);
;         const char* nA = has_next ? nxt.a : cA; const char* nB = has_next ? nxt.b : cB; const int nt = cur.nt;
; #pragma unroll 1
;         for (int t = 0; t < nt; t += 2) {
;             const bool last = (t == nt - 2);
;             const char* a1 = cA + (size_t)(t + 1) * kstep;
;             const char* a2 = last ? nA : cA + (size_t)(t + 2) * kstep; const char* b2 = last ? nB : cB + (size_t)(t + 2) * kstep;
;             const char* a3 = a2 + kstep; const char* b3 = b2 + kstep;
;             PG8_LDB(B0, 0, 0); PG8_LDB(B1, 0, 1); PG8_SCHED; PG8_LDA(At, 0, 0); PG8_STAGE(PG8_SA(1, 1), a1 + hstepA, voffA);
;             PG8_WAIT_V(8); PG8_WAIT_L(0); PG8_BAR; PG8_MMA(0, 0, At, B0); PG8_MMA(0, 1, At, B1); PG8_BAR; PG8_SCHED;
;             PG8_LDA(At, 0, 1); PG8_STAGE(PG8_SB(0, 0), b2, voffB); PG8_STAGE(PG8_SB(0, 1), b2 + hstepB, voffB); PG8_STAGE(PG8_SA(0, 0), a2, voffA);
;             PG8_WAIT_V(8); PG8_WAIT_L(0); PG8_BAR; PG8_MMA(1, 0, At, B0); PG8_MMA(1, 1, At, B1); PG8_BAR; PG8_SCHED;
.LBB0_1077:
	s_add_u32 s23, s26, 0xfff80080
	s_addc_u32 s28, s27, -1
	s_add_i32 s29, 0, 0x10000
	s_cmp_eq_u32 s15, 28
	s_cselect_b32 s37, s17, s28
	s_cselect_b32 s36, s16, s23
	s_cselect_b32 s31, s19, s13
	s_cselect_b32 s30, s18, s5
	s_add_i32 s23, 0, 0x14000
	v_add_u32_e32 v152, s29, v142
	v_add_u32_e32 v168, s23, v142
	ds_read_b128 v[136:139], v152
	ds_read_b128 v[144:147], v152 offset:1024
	ds_read_b128 v[148:151], v152 offset:2048
	ds_read_b128 v[152:155], v152 offset:3072
	ds_read_b128 v[156:159], v168
	ds_read_b128 v[160:163], v168 offset:1024
	ds_read_b128 v[164:167], v168 offset:2048
	ds_read_b128 v[168:171], v168 offset:3072
	v_lshl_add_u64 v[204:205], s[26:27], 0, v[132:133]
	s_add_i32 m0, s46, 0xc000
	ds_read_b128 v[172:175], v143
	ds_read_b128 v[176:179], v143 offset:1024
	ds_read_b128 v[180:183], v143 offset:2048
	ds_read_b128 v[184:187], v143 offset:3072
	ds_read_b128 v[188:191], v143 offset:4096
	ds_read_b128 v[192:195], v143 offset:5120
	ds_read_b128 v[196:199], v143 offset:6144
	ds_read_b128 v[200:203], v143 offset:7168
	global_load_lds_dwordx4 v[204:205], off
	v_lshl_add_u64 v[204:205], s[26:27], 0, v[134:135]
	s_add_i32 m0, s46, 0xe000
	s_nop 0
	global_load_lds_dwordx4 v[204:205], off
	s_waitcnt vmcnt(8)
	s_waitcnt lgkmcnt(0)
	s_barrier
	s_setprio 1
	v_mfma_f32_16x16x32_bf16 v[126:129], v[136:139], v[172:175], v[126:129]
	v_mfma_f32_16x16x32_bf16 v[122:125], v[148:151], v[172:175], v[122:125]
	v_mfma_f32_16x16x32_bf16 v[110:113], v[136:139], v[180:183], v[110:113]
	v_mfma_f32_16x16x32_bf16 v[106:109], v[148:151], v[180:183], v[106:109]
	v_mfma_f32_16x16x32_bf16 v[94:97], v[136:139], v[188:191], v[94:97]
	v_mfma_f32_16x16x32_bf16 v[90:93], v[148:151], v[188:191], v[90:93]
	v_mfma_f32_16x16x32_bf16 v[78:81], v[136:139], v[196:199], v[78:81]
	v_mfma_f32_16x16x32_bf16 v[74:77], v[148:151], v[196:199], v[74:77]
	v_mfma_f32_16x16x32_bf16 v[126:129], v[144:147], v[176:179], v[126:129]
	v_mfma_f32_16x16x32_bf16 v[122:125], v[152:155], v[176:179], v[122:125]
	v_mfma_f32_16x16x32_bf16 v[110:113], v[144:147], v[184:187], v[110:113]
	v_mfma_f32_16x16x32_bf16 v[106:109], v[152:155], v[184:187], v[106:109]
	v_mfma_f32_16x16x32_bf16 v[94:97], v[144:147], v[192:195], v[94:97]
	v_mfma_f32_16x16x32_bf16 v[90:93], v[152:155], v[192:195], v[90:93]
	v_mfma_f32_16x16x32_bf16 v[78:81], v[144:147], v[200:203], v[78:81]
	v_mfma_f32_16x16x32_bf16 v[74:77], v[152:155], v[200:203], v[74:77]
	s_setprio 0
	s_setprio 1
	v_mfma_f32_16x16x32_bf16 v[118:121], v[156:159], v[172:175], v[118:121]
	v_mfma_f32_16x16x32_bf16 v[114:117], v[164:167], v[172:175], v[114:117]
	v_mfma_f32_16x16x32_bf16 v[102:105], v[156:159], v[180:183], v[102:105]
	v_mfma_f32_16x16x32_bf16 v[98:101], v[164:167], v[180:183], v[98:101]
	v_mfma_f32_16x16x32_bf16 v[86:89], v[156:159], v[188:191], v[86:89]
	v_mfma_f32_16x16x32_bf16 v[82:85], v[164:167], v[188:191], v[82:85]
	v_mfma_f32_16x16x32_bf16 v[70:73], v[156:159], v[196:199], v[70:73]
	v_mfma_f32_16x16x32_bf16 v[66:69], v[164:167], v[196:199], v[66:69]
	v_mfma_f32_16x16x32_bf16 v[118:121], v[160:163], v[176:179], v[118:121]
	v_mfma_f32_16x16x32_bf16 v[114:117], v[168:171], v[176:179], v[114:117]
	v_mfma_f32_16x16x32_bf16 v[102:105], v[160:163], v[184:187], v[102:105]
	v_mfma_f32_16x16x32_bf16 v[98:101], v[168:171], v[184:187], v[98:101]
	v_mfma_f32_16x16x32_bf16 v[86:89], v[160:163], v[192:195], v[86:89]
	v_mfma_f32_16x16x32_bf16 v[82:85], v[168:171], v[192:195], v[82:85]
	v_mfma_f32_16x16x32_bf16 v[70:73], v[160:163], v[200:203], v[70:73]
	v_mfma_f32_16x16x32_bf16 v[66:69], v[168:171], v[200:203], v[66:69]
	s_barrier
	s_setprio 0
	s_add_i32 s28, s29, s43
	v_lshl_add_u64 v[204:205], s[30:31], 0, v[0:1]
	s_mov_b32 m0, s28
	ds_read_b128 v[172:175], v143 offset:16384
	ds_read_b128 v[176:179], v143 offset:17408
	ds_read_b128 v[180:183], v143 offset:18432
	ds_read_b128 v[184:187], v143 offset:19456
	ds_read_b128 v[188:191], v143 offset:20480
	ds_read_b128 v[192:195], v143 offset:21504
	ds_read_b128 v[196:199], v143 offset:22528
	ds_read_b128 v[200:203], v143 offset:23552
	global_load_lds_dwordx4 v[204:205], off
	s_add_i32 m0, s28, 0x2000
	s_add_u32 s28, s30, 0x80000
	v_lshl_add_u64 v[206:207], s[30:31], 0, v[130:131]
	s_addc_u32 s29, s31, 0
	s_add_i32 s23, s23, s43
	global_load_lds_dwordx4 v[206:207], off
	v_lshl_add_u64 v[208:209], s[28:29], 0, v[0:1]
	s_mov_b32 m0, s23
	v_lshl_add_u64 v[210:211], s[36:37], 0, v[130:131]
	global_load_lds_dwordx4 v[208:209], off
	v_lshl_add_u64 v[208:209], s[28:29], 0, v[130:131]
	s_add_i32 m0, s23, 0x2000
	s_nop 0
	global_load_lds_dwordx4 v[208:209], off
	v_lshl_add_u64 v[208:209], s[36:37], 0, v[0:1]
	s_mov_b32 m0, s46
	s_nop 0
	global_load_lds_dwordx4 v[208:209], off
	s_mov_b32 m0, s47
	s_nop 0
	global_load_lds_dwordx4 v[210:211], off
	s_waitcnt vmcnt(8)
	s_waitcnt lgkmcnt(0)
	s_barrier
; #define PG8_STAGE(bufoff, gbase, voff) do { _Pragma("unroll") for (int _i = 0; _i < 2; ++_i) \
;         __builtin_amdgcn_global_load_lds((const unsigned*)((const char*)(gbase) + (voff)[_i]), (LAS unsigned*)(lds + (bufoff) + ldsw + _i * 8192), 16, 0, 0); } while (0)
; #define PG8_LDA(dst, b, h) do { _Pragma("unroll") for (int m = 0; m < 4; ++m) _Pragma("unroll") for (int k = 0; k < 2; ++k) dst[m][k] = *(const LAS bf16x8*)(lds + PG8_SA(b, h) + aoff + m * 2048 + k * 1024); } while (0)
; #define PG8_LDB(dst, b, h) do { _Pragma("unroll") for (int n = 0; n < 2; ++n) _Pragma("unroll") for (int k = 0; k < 2; ++k) dst[n][k] = *(const LAS bf16x8*)(lds + PG8_SB(b, h) + boff + n * 2048 + k * 1024); } while (0)
; #define PG8_MMA(ai, bj, At, Bt) do { __builtin_amdgcn_s_setprio(1); _Pragma("unroll") for (int m = 0; m < 4; ++m) _Pragma("unroll") for (int n = 0; n < 2; ++n) _Pragma("unroll") for (int k = 0; k < 2; ++k) \
;         acc[ai][bj][m][n] = __builtin_amdgcn_mfma_f32_16x16x32_bf16(Bt[n][k], At[m][k], acc[ai][bj][m][n], 0, 0, 0); __builtin_amdgcn_s_setprio(0); } while (0)
; #define PG8_WAIT_V(n) asm volatile("s_waitcnt vmcnt(" #n ")" ::: "memory")
; #define PG8_WAIT_L(n) asm volatile("s_waitcnt lgkmcnt(" #n ")" ::: "memory")
; #define PG8_BAR __builtin_amdgcn_s_barrier()
; #define PG8_SCHED __builtin_amdgcn_sched_barrier(0)
; template <class Epi, class Sched, bool ALIGN_EPI, bool LAST_FUSED = false, bool PERM = false, bool CARRY = false>
; __device__ __forceinline__ void gemm_phase(LAS unsigned char* lds, const int tid, const int K, const int lda, const int ldb, const Sched& S, const Epi& E) {
;     ...
;             PG8_WAIT_V(8); PG8_WAIT_L(0); PG8_BAR; PG8_MMA(1, 0, At, B0); PG8_MMA(1, 1, At, B1); PG8_BAR; PG8_SCHED;
;             PG8_LDB(B0, 1, 0); PG8_LDB(B1, 1, 1); PG8_SCHED; PG8_LDA(At, 1, 0); PG8_STAGE(PG8_SA(0, 1), a2 + hstepA, voffA);
;             PG8_WAIT_V(8); PG8_WAIT_L(0); PG8_BAR; PG8_MMA(0, 0, At, B0); PG8_MMA(0, 1, At, B1); PG8_BAR; PG8_SCHED;
;             PG8_LDA(At, 1, 1); PG8_STAGE(PG8_SB(1, 0), b3, voffB); PG8_STAGE(PG8_SB(1, 1), b3 + hstepB, voffB); PG8_STAGE(PG8_SA(1, 0), a3, voffA);
;             PG8_WAIT_V(8); PG8_WAIT_L(0); PG8_BAR; PG8_MMA(1, 0, At, B0); PG8_MMA(1, 1, At, B1); PG8_BAR; PG8_SCHED;
	s_setprio 1
	v_mfma_f32_16x16x32_bf16 v[62:65], v[136:139], v[172:175], v[62:65]
	v_mfma_f32_16x16x32_bf16 v[58:61], v[148:151], v[172:175], v[58:61]
	v_mfma_f32_16x16x32_bf16 v[46:49], v[136:139], v[180:183], v[46:49]
	v_mfma_f32_16x16x32_bf16 v[42:45], v[148:151], v[180:183], v[42:45]
	v_mfma_f32_16x16x32_bf16 v[30:33], v[136:139], v[188:191], v[30:33]
	v_mfma_f32_16x16x32_bf16 v[26:29], v[148:151], v[188:191], v[26:29]
	v_mfma_f32_16x16x32_bf16 v[14:17], v[136:139], v[196:199], v[14:17]
	v_mfma_f32_16x16x32_bf16 v[10:13], v[148:151], v[196:199], v[10:13]
	v_mfma_f32_16x16x32_bf16 v[62:65], v[144:147], v[176:179], v[62:65]
	v_mfma_f32_16x16x32_bf16 v[58:61], v[152:155], v[176:179], v[58:61]
	v_mfma_f32_16x16x32_bf16 v[46:49], v[144:147], v[184:187], v[46:49]
	v_mfma_f32_16x16x32_bf16 v[42:45], v[152:155], v[184:187], v[42:45]
	v_mfma_f32_16x16x32_bf16 v[30:33], v[144:147], v[192:195], v[30:33]
	v_mfma_f32_16x16x32_bf16 v[26:29], v[152:155], v[192:195], v[26:29]
	v_mfma_f32_16x16x32_bf16 v[14:17], v[144:147], v[200:203], v[14:17]
	v_mfma_f32_16x16x32_bf16 v[10:13], v[152:155], v[200:203], v[10:13]
	s_setprio 0
	s_setprio 1
	v_mfma_f32_16x16x32_bf16 v[54:57], v[156:159], v[172:175], v[54:57]
	v_mfma_f32_16x16x32_bf16 v[50:53], v[164:167], v[172:175], v[50:53]
	v_mfma_f32_16x16x32_bf16 v[38:41], v[156:159], v[180:183], v[38:41]
	v_mfma_f32_16x16x32_bf16 v[34:37], v[164:167], v[180:183], v[34:37]
	v_mfma_f32_16x16x32_bf16 v[22:25], v[156:159], v[188:191], v[22:25]
	v_mfma_f32_16x16x32_bf16 v[18:21], v[164:167], v[188:191], v[18:21]
	v_mfma_f32_16x16x32_bf16 v[6:9], v[156:159], v[196:199], v[6:9]
	v_mfma_f32_16x16x32_bf16 v[2:5], v[164:167], v[196:199], v[2:5]
	v_mfma_f32_16x16x32_bf16 v[54:57], v[160:163], v[176:179], v[54:57]
	v_mfma_f32_16x16x32_bf16 v[50:53], v[168:171], v[176:179], v[50:53]
	v_mfma_f32_16x16x32_bf16 v[38:41], v[160:163], v[184:187], v[38:41]
	v_mfma_f32_16x16x32_bf16 v[34:37], v[168:171], v[184:187], v[34:37]
	v_mfma_f32_16x16x32_bf16 v[22:25], v[160:163], v[192:195], v[22:25]
	v_mfma_f32_16x16x32_bf16 v[18:21], v[168:171], v[192:195], v[18:21]
	v_mfma_f32_16x16x32_bf16 v[6:9], v[160:163], v[200:203], v[6:9]
	v_mfma_f32_16x16x32_bf16 v[2:5], v[168:171], v[200:203], v[2:5]
	s_barrier
	s_setprio 0
	s_add_i32 s23, 0, 0x18000
	s_add_i32 s35, 0, 0x1c000
	v_add_u32_e32 v152, s23, v142
	v_add_u32_e32 v168, s35, v142
	ds_read_b128 v[136:139], v152
	ds_read_b128 v[144:147], v152 offset:1024
	ds_read_b128 v[148:151], v152 offset:2048
	ds_read_b128 v[152:155], v152 offset:3072
	ds_read_b128 v[156:159], v168
	ds_read_b128 v[160:163], v168 offset:1024
	ds_read_b128 v[164:167], v168 offset:2048
	ds_read_b128 v[168:171], v168 offset:3072
	s_add_u32 s28, s36, 0x80000
	s_addc_u32 s29, s37, 0
	s_mov_b32 m0, s48
	v_lshl_add_u64 v[212:213], s[28:29], 0, v[0:1]
	ds_read_b128 v[172:175], v143 offset:32768
	ds_read_b128 v[176:179], v143 offset:33792
	ds_read_b128 v[180:183], v143 offset:34816
	ds_read_b128 v[184:187], v143 offset:35840
	ds_read_b128 v[188:191], v143 offset:36864
	ds_read_b128 v[192:195], v143 offset:37888
	ds_read_b128 v[196:199], v143 offset:38912
	ds_read_b128 v[200:203], v143 offset:39936
	global_load_lds_dwordx4 v[212:213], off
	v_lshl_add_u64 v[212:213], s[28:29], 0, v[130:131]
	s_mov_b32 m0, s49
	s_nop 0
	global_load_lds_dwordx4 v[212:213], off
	s_waitcnt vmcnt(8)
	s_waitcnt lgkmcnt(0)
	s_barrier
	s_setprio 1
	v_mfma_f32_16x16x32_bf16 v[126:129], v[136:139], v[172:175], v[126:129]
	v_mfma_f32_16x16x32_bf16 v[122:125], v[148:151], v[172:175], v[122:125]
	v_mfma_f32_16x16x32_bf16 v[110:113], v[136:139], v[180:183], v[110:113]
	v_mfma_f32_16x16x32_bf16 v[106:109], v[148:151], v[180:183], v[106:109]
	v_mfma_f32_16x16x32_bf16 v[94:97], v[136:139], v[188:191], v[94:97]
	v_mfma_f32_16x16x32_bf16 v[90:93], v[148:151], v[188:191], v[90:93]
	v_mfma_f32_16x16x32_bf16 v[78:81], v[136:139], v[196:199], v[78:81]
	v_mfma_f32_16x16x32_bf16 v[74:77], v[148:151], v[196:199], v[74:77]
	v_mfma_f32_16x16x32_bf16 v[126:129], v[144:147], v[176:179], v[126:129]
	v_mfma_f32_16x16x32_bf16 v[122:125], v[152:155], v[176:179], v[122:125]
	v_mfma_f32_16x16x32_bf16 v[110:113], v[144:147], v[184:187], v[110:113]
	v_mfma_f32_16x16x32_bf16 v[106:109], v[152:155], v[184:187], v[106:109]
	v_mfma_f32_16x16x32_bf16 v[94:97], v[144:147], v[192:195], v[94:97]
	v_mfma_f32_16x16x32_bf16 v[90:93], v[152:155], v[192:195], v[90:93]
	v_mfma_f32_16x16x32_bf16 v[78:81], v[144:147], v[200:203], v[78:81]
	v_mfma_f32_16x16x32_bf16 v[74:77], v[152:155], v[200:203], v[74:77]
	s_setprio 0
	s_setprio 1
	v_mfma_f32_16x16x32_bf16 v[118:121], v[156:159], v[172:175], v[118:121]
	v_mfma_f32_16x16x32_bf16 v[114:117], v[164:167], v[172:175], v[114:117]
	v_mfma_f32_16x16x32_bf16 v[102:105], v[156:159], v[180:183], v[102:105]
	v_mfma_f32_16x16x32_bf16 v[98:101], v[164:167], v[180:183], v[98:101]
	v_mfma_f32_16x16x32_bf16 v[86:89], v[156:159], v[188:191], v[86:89]
	v_mfma_f32_16x16x32_bf16 v[82:85], v[164:167], v[188:191], v[82:85]
	v_mfma_f32_16x16x32_bf16 v[70:73], v[156:159], v[196:199], v[70:73]
	v_mfma_f32_16x16x32_bf16 v[66:69], v[164:167], v[196:199], v[66:69]
	v_mfma_f32_16x16x32_bf16 v[118:121], v[160:163], v[176:179], v[118:121]
	v_mfma_f32_16x16x32_bf16 v[114:117], v[168:171], v[176:179], v[114:117]
	v_mfma_f32_16x16x32_bf16 v[102:105], v[160:163], v[184:187], v[102:105]
	v_mfma_f32_16x16x32_bf16 v[98:101], v[168:171], v[184:187], v[98:101]
	v_mfma_f32_16x16x32_bf16 v[86:89], v[160:163], v[192:195], v[86:89]
	v_mfma_f32_16x16x32_bf16 v[82:85], v[168:171], v[192:195], v[82:85]
	v_mfma_f32_16x16x32_bf16 v[70:73], v[160:163], v[200:203], v[70:73]
	v_mfma_f32_16x16x32_bf16 v[66:69], v[168:171], v[200:203], v[66:69]
	s_barrier
; #define PG8_STAGE(bufoff, gbase, voff) do { _Pragma("unroll") for (int _i = 0; _i < 2; ++_i) \
;         __builtin_amdgcn_global_load_lds((const unsigned*)((const char*)(gbase) + (voff)[_i]), (LAS unsigned*)(lds + (bufoff) + ldsw + _i * 8192), 16, 0, 0); } while (0)
; #define PG8_LDA(dst, b, h) do { _Pragma("unroll") for (int m = 0; m < 4; ++m) _Pragma("unroll") for (int k = 0; k < 2; ++k) dst[m][k] = *(const LAS bf16x8*)(lds + PG8_SA(b, h) + aoff + m * 2048 + k * 1024); } while (0)
; #define PG8_MMA(ai, bj, At, Bt) do { __builtin_amdgcn_s_setprio(1); _Pragma("unroll") for (int m = 0; m < 4; ++m) _Pragma("unroll") for (int n = 0; n < 2; ++n) _Pragma("unroll") for (int k = 0; k < 2; ++k) \
;         acc[ai][bj][m][n] = __builtin_amdgcn_mfma_f32_16x16x32_bf16(Bt[n][k], At[m][k], acc[ai][bj][m][n], 0, 0, 0); __builtin_amdgcn_s_setprio(0); } while (0)
; #define PG8_WAIT_V(n) asm volatile("s_waitcnt vmcnt(" #n ")" ::: "memory")
; #define PG8_WAIT_L(n) asm volatile("s_waitcnt lgkmcnt(" #n ")" ::: "memory")
; #define PG8_BAR __builtin_amdgcn_s_barrier()
; #define PG8_SCHED __builtin_amdgcn_sched_barrier(0)
; template <class Epi, class Sched, bool ALIGN_EPI, bool LAST_FUSED = false, bool PERM = false, bool CARRY = false>
; __device__ __forceinline__ void gemm_phase(LAS unsigned char* lds, const int tid, const int K, const int lda, const int ldb, const Sched& S, const Epi& E) {
;     ...
;             PG8_LDA(At, 1, 1); PG8_STAGE(PG8_SB(1, 0), b3, voffB); PG8_STAGE(PG8_SB(1, 1), b3 + hstepB, voffB); PG8_STAGE(PG8_SA(1, 0), a3, voffA);
;             PG8_WAIT_V(8); PG8_WAIT_L(0); PG8_BAR; PG8_MMA(1, 0, At, B0); PG8_MMA(1, 1, At, B1); PG8_BAR; PG8_SCHED;
;         }
;         if constexpr (ALIGN_EPI) { if (wr == 0) PG8_BAR; }
	s_setprio 0
	s_add_i32 s23, s23, s43
	v_lshl_add_u64 v[204:205], v[204:205], 0, s[68:69]
	s_mov_b32 m0, s23
	ds_read_b128 v[172:175], v143 offset:49152
	ds_read_b128 v[176:179], v143 offset:50176
	ds_read_b128 v[180:183], v143 offset:51200
	ds_read_b128 v[184:187], v143 offset:52224
	ds_read_b128 v[188:191], v143 offset:53248
	ds_read_b128 v[192:195], v143 offset:54272
	ds_read_b128 v[196:199], v143 offset:55296
	ds_read_b128 v[200:203], v143 offset:56320
	global_load_lds_dwordx4 v[204:205], off
	s_add_i32 m0, s23, 0x2000
	s_add_u32 s28, s30, 0x80080
	v_lshl_add_u64 v[204:205], v[206:207], 0, s[68:69]
	s_addc_u32 s29, s31, 0
	s_add_i32 s23, s35, s43
	global_load_lds_dwordx4 v[204:205], off
	v_lshl_add_u64 v[204:205], s[28:29], 0, v[0:1]
	s_mov_b32 m0, s23
	s_nop 0
	global_load_lds_dwordx4 v[204:205], off
	v_lshl_add_u64 v[204:205], s[28:29], 0, v[130:131]
	s_add_i32 m0, s23, 0x2000
	s_nop 0
	global_load_lds_dwordx4 v[204:205], off
	v_lshl_add_u64 v[204:205], v[208:209], 0, s[68:69]
	s_mov_b32 m0, s51
	s_nop 0
	global_load_lds_dwordx4 v[204:205], off
	v_lshl_add_u64 v[204:205], v[210:211], 0, s[68:69]
	s_mov_b32 m0, s52
	s_nop 0
	global_load_lds_dwordx4 v[204:205], off
	s_waitcnt vmcnt(8)
	s_waitcnt lgkmcnt(0)
	s_barrier
	s_setprio 1
	v_mfma_f32_16x16x32_bf16 v[62:65], v[136:139], v[172:175], v[62:65]
	v_mfma_f32_16x16x32_bf16 v[58:61], v[148:151], v[172:175], v[58:61]
	v_mfma_f32_16x16x32_bf16 v[46:49], v[136:139], v[180:183], v[46:49]
	v_mfma_f32_16x16x32_bf16 v[42:45], v[148:151], v[180:183], v[42:45]
	v_mfma_f32_16x16x32_bf16 v[30:33], v[136:139], v[188:191], v[30:33]
	v_mfma_f32_16x16x32_bf16 v[26:29], v[148:151], v[188:191], v[26:29]
	v_mfma_f32_16x16x32_bf16 v[14:17], v[136:139], v[196:199], v[14:17]
	v_mfma_f32_16x16x32_bf16 v[10:13], v[148:151], v[196:199], v[10:13]
	v_mfma_f32_16x16x32_bf16 v[62:65], v[144:147], v[176:179], v[62:65]
	v_mfma_f32_16x16x32_bf16 v[58:61], v[152:155], v[176:179], v[58:61]
	v_mfma_f32_16x16x32_bf16 v[46:49], v[144:147], v[184:187], v[46:49]
	v_mfma_f32_16x16x32_bf16 v[42:45], v[152:155], v[184:187], v[42:45]
	v_mfma_f32_16x16x32_bf16 v[30:33], v[144:147], v[192:195], v[30:33]
	v_mfma_f32_16x16x32_bf16 v[26:29], v[152:155], v[192:195], v[26:29]
	v_mfma_f32_16x16x32_bf16 v[14:17], v[144:147], v[200:203], v[14:17]
	v_mfma_f32_16x16x32_bf16 v[10:13], v[152:155], v[200:203], v[10:13]
	s_setprio 0
	s_setprio 1
	v_mfma_f32_16x16x32_bf16 v[54:57], v[156:159], v[172:175], v[54:57]
	v_mfma_f32_16x16x32_bf16 v[50:53], v[164:167], v[172:175], v[50:53]
	v_mfma_f32_16x16x32_bf16 v[38:41], v[156:159], v[180:183], v[38:41]
	v_mfma_f32_16x16x32_bf16 v[34:37], v[164:167], v[180:183], v[34:37]
	v_mfma_f32_16x16x32_bf16 v[22:25], v[156:159], v[188:191], v[22:25]
	v_mfma_f32_16x16x32_bf16 v[18:21], v[164:167], v[188:191], v[18:21]
	v_mfma_f32_16x16x32_bf16 v[6:9], v[156:159], v[196:199], v[6:9]
	v_mfma_f32_16x16x32_bf16 v[2:5], v[164:167], v[196:199], v[2:5]
	v_mfma_f32_16x16x32_bf16 v[54:57], v[160:163], v[176:179], v[54:57]
	v_mfma_f32_16x16x32_bf16 v[50:53], v[168:171], v[176:179], v[50:53]
	v_mfma_f32_16x16x32_bf16 v[38:41], v[160:163], v[184:187], v[38:41]
	v_mfma_f32_16x16x32_bf16 v[34:37], v[168:171], v[184:187], v[34:37]
	v_mfma_f32_16x16x32_bf16 v[22:25], v[160:163], v[192:195], v[22:25]
	v_mfma_f32_16x16x32_bf16 v[18:21], v[168:171], v[192:195], v[18:21]
	v_mfma_f32_16x16x32_bf16 v[6:9], v[160:163], v[200:203], v[6:9]
	v_mfma_f32_16x16x32_bf16 v[2:5], v[168:171], v[200:203], v[2:5]
	s_barrier
	s_setprio 0
	s_add_i32 s15, s15, 2
	s_add_u32 s26, s26, 0x100
	s_addc_u32 s27, s27, 0
	s_add_u32 s5, s5, 0x100
	s_addc_u32 s13, s13, 0
	s_cmp_gt_u32 s15, 29
	s_cbranch_scc0 .LBB0_1077
	s_and_b64 vcc, exec, s[10:11]
	s_cbranch_vccz .LBB0_1080
	s_barrier

; #define PG8_STAGE(bufoff, gbase, voff) do { _Pragma("unroll") for (int _i = 0; _i < 2; ++_i) \
;         __builtin_amdgcn_global_load_lds((const unsigned*)((const char*)(gbase) + (voff)[_i]), (LAS unsigned*)(lds + (bufoff) + ldsw + _i * 8192), 16, 0, 0); } while (0)
; #define PG8_LDA(dst, b, h) do { _Pragma("unroll") for (int m = 0; m < 4; ++m) _Pragma("unroll") for (int k = 0; k < 2; ++k) dst[m][k] = *(const LAS bf16x8*)(lds + PG8_SA(b, h) + aoff + m * 2048 + k * 1024); } while (0)
; #define PG8_LDB(dst, b, h) do { _Pragma("unroll") for (int n = 0; n < 2; ++n) _Pragma("unroll") for (int k = 0; k < 2; ++k) dst[n][k] = *(const LAS bf16x8*)(lds + PG8_SB(b, h) + boff + n * 2048 + k * 1024); } while (0)
; #define PG8_WAIT_V(n) asm volatile("s_waitcnt vmcnt(" #n ")" ::: "memory")
; template <class Epi, class Sched, bool ALIGN_EPI, bool LAST_FUSED = false, bool PERM = false, bool CARRY = false>
; __device__ __forceinline__ void gemm_phase(LAS unsigned char* lds, const int tid, const int K, const int lda, const int ldb, const Sched& S, const Epi& E) {
;     ...
;         const bool has_next = S.next(KD_IDX(ui + 1), nxt);
;         const char* nA = has_next ? nxt.a : cA; const char* nB = has_next ? nxt.b : cB; const int nt = cur.nt;
; #pragma unroll 1
;         for (int t = 0; t < nt; t += 2) {
;             const bool last = (t == nt - 2);
;             const char* a1 = cA + (size_t)(t + 1) * kstep;
;             const char* a2 = last ? nA : cA + (size_t)(t + 2) * kstep; const char* b2 = last ? nB : cB + (size_t)(t + 2) * kstep;
;             const char* a3 = a2 + kstep; const char* b3 = b2 + kstep;
;             PG8_LDB(B0, 0, 0); PG8_LDB(B1, 0, 1); PG8_SCHED; PG8_LDA(At, 0, 0); PG8_STAGE(PG8_SA(1, 1), a1 + hstepA, voffA);
;             PG8_WAIT_V(8); PG8_WAIT_L(0); PG8_BAR; PG8_MMA(0, 0, At, B0); PG8_MMA(0, 1, At, B1); PG8_BAR; PG8_SCHED;
;             PG8_LDA(At, 0, 1); PG8_STAGE(PG8_SB(0, 0), b2, voffB); PG8_STAGE(PG8_SB(0, 1), b2 + hstepB, voffB); PG8_STAGE(PG8_SA(0, 0), a2, voffA);
;             PG8_WAIT_V(8); PG8_WAIT_L(0); PG8_BAR; PG8_MMA(1, 0, At, B0); PG8_MMA(1, 1, At, B1); PG8_BAR; PG8_SCHED;
;             PG8_LDB(B0, 1, 0); PG8_LDB(B1, 1, 1); PG8_SCHED; PG8_LDA(At, 1, 0); PG8_STAGE(PG8_SA(0, 1), a2 + hstepA, voffA);
;             PG8_WAIT_V(8); PG8_WAIT_L(0); PG8_BAR; PG8_MMA(0, 0, At, B0); PG8_MMA(0, 1, At, B1); PG8_BAR; PG8_SCHED;
.LBB0_1367:
	s_add_u32 s19, s38, s17
	s_addc_u32 s23, s39, 0
	s_add_u32 s35, s19, 0x100
	s_addc_u32 s37, s23, 0
	s_and_b64 s[28:29], s[46:47], exec
	s_cselect_b32 s51, s27, s37
	s_cselect_b32 s50, s26, s35
	s_add_u32 s17, s40, s17
	s_addc_u32 s28, s41, 0
	s_add_u32 s17, s17, 0x100
	s_addc_u32 s35, s28, 0
	s_add_i32 s45, 0, 0x10000
	s_and_b64 s[28:29], s[46:47], exec
	s_cselect_b32 s55, s31, s35
	s_cselect_b32 s54, s30, s17
	s_add_i32 s47, 0, 0x14000
	s_add_u32 s52, s19, 0x80080
	s_addc_u32 s53, s23, 0
	s_add_i32 s44, s45, s61
	s_add_i32 m0, s63, 0xc000
	s_add_i32 s79, s63, 0xe000
	s_add_i32 s29, s44, 0x2000
	s_add_u32 s58, s54, 0x10000
	v_add_u32_e32 v46, s45, v216
	v_add_u32_e32 v164, s47, v216
	s_addc_u32 s59, s55, 0
	s_add_i32 s37, s47, s61
	ds_read_b128 v[26:29], v46
	ds_read_b128 v[34:37], v46 offset:1024
	ds_read_b128 v[38:41], v46 offset:2048
	ds_read_b128 v[46:49], v46 offset:3072
	ds_read_b128 v[54:57], v164
	ds_read_b128 v[58:61], v164 offset:1024
	ds_read_b128 v[160:163], v164 offset:2048
	ds_read_b128 v[164:167], v164 offset:3072
	s_add_i32 s35, s37, 0x2000
	s_add_i32 s28, 0, 0x18000
	s_add_i32 s23, 0, 0x1c000
	s_add_u32 s48, s50, 0x80000
	s_addc_u32 s49, s51, 0
	s_add_i32 s19, s28, s61
	s_add_i32 s17, s19, 0x2000
	s_add_u32 s46, s54, 0x10080
	s_addc_u32 s47, s55, 0
	s_add_i32 s78, s23, s61
	s_add_i32 s45, s78, 0x2000
	v_lshl_add_u64 v[200:201], s[52:53], 0, v[158:159]
	ds_read_b128 v[168:171], v217
	ds_read_b128 v[172:175], v217 offset:1024
	ds_read_b128 v[176:179], v217 offset:2048
	ds_read_b128 v[180:183], v217 offset:3072
	ds_read_b128 v[184:187], v217 offset:4096
	ds_read_b128 v[188:191], v217 offset:5120
	ds_read_b128 v[192:195], v217 offset:6144
	ds_read_b128 v[196:199], v217 offset:7168
	global_load_lds_dwordx4 v[200:201], off
	v_lshl_add_u64 v[200:201], s[52:53], 0, v[156:157]
	s_mov_b32 m0, s79
	s_nop 0
	global_load_lds_dwordx4 v[200:201], off
	s_waitcnt vmcnt(8)
	s_waitcnt lgkmcnt(0)
	s_barrier
	s_setprio 1
	v_mfma_f32_16x16x32_bf16 v[150:153], v[26:29], v[168:171], v[150:153]
	v_mfma_f32_16x16x32_bf16 v[142:145], v[38:41], v[168:171], v[142:145]
	v_mfma_f32_16x16x32_bf16 v[134:137], v[26:29], v[176:179], v[134:137]
	v_mfma_f32_16x16x32_bf16 v[126:129], v[38:41], v[176:179], v[126:129]
	v_mfma_f32_16x16x32_bf16 v[118:121], v[26:29], v[184:187], v[118:121]
	v_mfma_f32_16x16x32_bf16 v[110:113], v[38:41], v[184:187], v[110:113]
	v_mfma_f32_16x16x32_bf16 v[102:105], v[26:29], v[192:195], v[102:105]
	v_mfma_f32_16x16x32_bf16 v[94:97], v[38:41], v[192:195], v[94:97]
	v_mfma_f32_16x16x32_bf16 v[150:153], v[34:37], v[172:175], v[150:153]
	v_mfma_f32_16x16x32_bf16 v[142:145], v[46:49], v[172:175], v[142:145]
	v_mfma_f32_16x16x32_bf16 v[134:137], v[34:37], v[180:183], v[134:137]
	v_mfma_f32_16x16x32_bf16 v[126:129], v[46:49], v[180:183], v[126:129]
	v_mfma_f32_16x16x32_bf16 v[118:121], v[34:37], v[188:191], v[118:121]
	v_mfma_f32_16x16x32_bf16 v[110:113], v[46:49], v[188:191], v[110:113]
	v_mfma_f32_16x16x32_bf16 v[102:105], v[34:37], v[196:199], v[102:105]
	v_mfma_f32_16x16x32_bf16 v[94:97], v[46:49], v[196:199], v[94:97]
	s_setprio 0
	s_setprio 1
	v_mfma_f32_16x16x32_bf16 v[146:149], v[54:57], v[168:171], v[146:149]
	v_mfma_f32_16x16x32_bf16 v[138:141], v[160:163], v[168:171], v[138:141]
	v_mfma_f32_16x16x32_bf16 v[130:133], v[54:57], v[176:179], v[130:133]
	v_mfma_f32_16x16x32_bf16 v[122:125], v[160:163], v[176:179], v[122:125]
	v_mfma_f32_16x16x32_bf16 v[114:117], v[54:57], v[184:187], v[114:117]
	v_mfma_f32_16x16x32_bf16 v[106:109], v[160:163], v[184:187], v[106:109]
	v_mfma_f32_16x16x32_bf16 v[98:101], v[54:57], v[192:195], v[98:101]
	v_mfma_f32_16x16x32_bf16 v[90:93], v[160:163], v[192:195], v[90:93]
	v_mfma_f32_16x16x32_bf16 v[146:149], v[58:61], v[172:175], v[146:149]
	v_mfma_f32_16x16x32_bf16 v[138:141], v[164:167], v[172:175], v[138:141]
	v_mfma_f32_16x16x32_bf16 v[130:133], v[58:61], v[180:183], v[130:133]
	v_mfma_f32_16x16x32_bf16 v[122:125], v[164:167], v[180:183], v[122:125]
	v_mfma_f32_16x16x32_bf16 v[114:117], v[58:61], v[188:191], v[114:117]
	v_mfma_f32_16x16x32_bf16 v[106:109], v[164:167], v[188:191], v[106:109]
	v_mfma_f32_16x16x32_bf16 v[98:101], v[58:61], v[196:199], v[98:101]
	v_mfma_f32_16x16x32_bf16 v[90:93], v[164:167], v[196:199], v[90:93]
	s_barrier
	s_setprio 0
	s_mov_b32 m0, s44
	v_lshl_add_u64 v[204:205], s[54:55], 0, v[0:1]
	ds_read_b128 v[168:171], v217 offset:16384
	ds_read_b128 v[172:175], v217 offset:17408
	ds_read_b128 v[176:179], v217 offset:18432
	ds_read_b128 v[180:183], v217 offset:19456
	ds_read_b128 v[184:187], v217 offset:20480
	ds_read_b128 v[188:191], v217 offset:21504
	ds_read_b128 v[192:195], v217 offset:22528
	ds_read_b128 v[196:199], v217 offset:23552
	global_load_lds_dwordx4 v[204:205], off
	v_lshl_add_u64 v[206:207], s[54:55], 0, v[154:155]
	s_mov_b32 m0, s29
	v_lshl_add_u64 v[200:201], s[58:59], 0, v[0:1]
	global_load_lds_dwordx4 v[206:207], off
	s_mov_b32 m0, s37
	v_lshl_add_u64 v[208:209], s[50:51], 0, v[158:159]
	global_load_lds_dwordx4 v[200:201], off
	v_lshl_add_u64 v[200:201], s[58:59], 0, v[154:155]
	s_mov_b32 m0, s35
	v_lshl_add_u64 v[210:211], s[50:51], 0, v[156:157]
	global_load_lds_dwordx4 v[200:201], off
	s_mov_b32 m0, s63
	s_nop 0
	global_load_lds_dwordx4 v[208:209], off
	s_mov_b32 m0, s64
	s_nop 0
	global_load_lds_dwordx4 v[210:211], off
	s_waitcnt vmcnt(8)
	s_waitcnt lgkmcnt(0)
	s_barrier
; #define PG8_STAGE(bufoff, gbase, voff) do { _Pragma("unroll") for (int _i = 0; _i < 2; ++_i) \
;         __builtin_amdgcn_global_load_lds((const unsigned*)((const char*)(gbase) + (voff)[_i]), (LAS unsigned*)(lds + (bufoff) + ldsw + _i * 8192), 16, 0, 0); } while (0)
; #define PG8_LDA(dst, b, h) do { _Pragma("unroll") for (int m = 0; m < 4; ++m) _Pragma("unroll") for (int k = 0; k < 2; ++k) dst[m][k] = *(const LAS bf16x8*)(lds + PG8_SA(b, h) + aoff + m * 2048 + k * 1024); } while (0)
; #define PG8_LDB(dst, b, h) do { _Pragma("unroll") for (int n = 0; n < 2; ++n) _Pragma("unroll") for (int k = 0; k < 2; ++k) dst[n][k] = *(const LAS bf16x8*)(lds + PG8_SB(b, h) + boff + n * 2048 + k * 1024); } while (0)
; #define PG8_MMA(ai, bj, At, Bt) do { __builtin_amdgcn_s_setprio(1); _Pragma("unroll") for (int m = 0; m < 4; ++m) _Pragma("unroll") for (int n = 0; n < 2; ++n) _Pragma("unroll") for (int k = 0; k < 2; ++k) \
;         acc[ai][bj][m][n] = __builtin_amdgcn_mfma_f32_16x16x32_bf16(Bt[n][k], At[m][k], acc[ai][bj][m][n], 0, 0, 0); __builtin_amdgcn_s_setprio(0); } while (0)
; #define PG8_WAIT_V(n) asm volatile("s_waitcnt vmcnt(" #n ")" ::: "memory")
; #define PG8_WAIT_L(n) asm volatile("s_waitcnt lgkmcnt(" #n ")" ::: "memory")
; #define PG8_BAR __builtin_amdgcn_s_barrier()
; #define PG8_SCHED __builtin_amdgcn_sched_barrier(0)
; template <class Epi, class Sched, bool ALIGN_EPI, bool LAST_FUSED = false, bool PERM = false, bool CARRY = false>
; __device__ __forceinline__ void gemm_phase(LAS unsigned char* lds, const int tid, const int K, const int lda, const int ldb, const Sched& S, const Epi& E) {
;     ...
;             PG8_WAIT_V(8); PG8_WAIT_L(0); PG8_BAR; PG8_MMA(1, 0, At, B0); PG8_MMA(1, 1, At, B1); PG8_BAR; PG8_SCHED;
;             PG8_LDB(B0, 1, 0); PG8_LDB(B1, 1, 1); PG8_SCHED; PG8_LDA(At, 1, 0); PG8_STAGE(PG8_SA(0, 1), a2 + hstepA, voffA);
;             PG8_WAIT_V(8); PG8_WAIT_L(0); PG8_BAR; PG8_MMA(0, 0, At, B0); PG8_MMA(0, 1, At, B1); PG8_BAR; PG8_SCHED;
;             PG8_LDA(At, 1, 1); PG8_STAGE(PG8_SB(1, 0), b3, voffB); PG8_STAGE(PG8_SB(1, 1), b3 + hstepB, voffB); PG8_STAGE(PG8_SA(1, 0), a3, voffA);
;             PG8_WAIT_V(8); PG8_WAIT_L(0); PG8_BAR; PG8_MMA(1, 0, At, B0); PG8_MMA(1, 1, At, B1); PG8_BAR; PG8_SCHED;
	s_setprio 1
	v_mfma_f32_16x16x32_bf16 v[86:89], v[26:29], v[168:171], v[86:89]
	v_mfma_f32_16x16x32_bf16 v[78:81], v[38:41], v[168:171], v[78:81]
	v_mfma_f32_16x16x32_bf16 v[70:73], v[26:29], v[176:179], v[70:73]
	v_mfma_f32_16x16x32_bf16 v[62:65], v[38:41], v[176:179], v[62:65]
	v_mfma_f32_16x16x32_bf16 v[42:45], v[26:29], v[184:187], v[42:45]
	v_mfma_f32_16x16x32_bf16 v[22:25], v[38:41], v[184:187], v[22:25]
	v_mfma_f32_16x16x32_bf16 v[14:17], v[26:29], v[192:195], v[14:17]
	v_mfma_f32_16x16x32_bf16 v[6:9], v[38:41], v[192:195], v[6:9]
	v_mfma_f32_16x16x32_bf16 v[86:89], v[34:37], v[172:175], v[86:89]
	v_mfma_f32_16x16x32_bf16 v[78:81], v[46:49], v[172:175], v[78:81]
	v_mfma_f32_16x16x32_bf16 v[70:73], v[34:37], v[180:183], v[70:73]
	v_mfma_f32_16x16x32_bf16 v[62:65], v[46:49], v[180:183], v[62:65]
	v_mfma_f32_16x16x32_bf16 v[42:45], v[34:37], v[188:191], v[42:45]
	v_mfma_f32_16x16x32_bf16 v[22:25], v[46:49], v[188:191], v[22:25]
	v_mfma_f32_16x16x32_bf16 v[14:17], v[34:37], v[196:199], v[14:17]
	v_mfma_f32_16x16x32_bf16 v[6:9], v[46:49], v[196:199], v[6:9]
	s_setprio 0
	s_setprio 1
	v_mfma_f32_16x16x32_bf16 v[30:33], v[54:57], v[184:187], v[30:33]
	v_mfma_f32_16x16x32_bf16 v[18:21], v[160:163], v[184:187], v[18:21]
	v_mfma_f32_16x16x32_bf16 v[10:13], v[54:57], v[192:195], v[10:13]
	v_mfma_f32_16x16x32_bf16 v[2:5], v[160:163], v[192:195], v[2:5]
	v_mfma_f32_16x16x32_bf16 v[26:29], v[54:57], v[168:171], v[82:85]
	v_mfma_f32_16x16x32_bf16 v[34:37], v[160:163], v[168:171], v[74:77]
	v_mfma_f32_16x16x32_bf16 v[38:41], v[54:57], v[176:179], v[66:69]
	v_mfma_f32_16x16x32_bf16 v[46:49], v[160:163], v[176:179], v[50:53]
	v_mfma_f32_16x16x32_bf16 v[30:33], v[58:61], v[188:191], v[30:33]
	v_mfma_f32_16x16x32_bf16 v[18:21], v[164:167], v[188:191], v[18:21]
	v_mfma_f32_16x16x32_bf16 v[10:13], v[58:61], v[196:199], v[10:13]
	v_mfma_f32_16x16x32_bf16 v[2:5], v[164:167], v[196:199], v[2:5]
	v_mfma_f32_16x16x32_bf16 v[26:29], v[58:61], v[172:175], v[26:29]
	v_mfma_f32_16x16x32_bf16 v[34:37], v[164:167], v[172:175], v[34:37]
	v_mfma_f32_16x16x32_bf16 v[38:41], v[58:61], v[180:183], v[38:41]
	v_mfma_f32_16x16x32_bf16 v[46:49], v[164:167], v[180:183], v[46:49]
	s_barrier
	s_setprio 0
	v_add_u32_e32 v66, s28, v216
	v_add_u32_e32 v74, s23, v216
	ds_read_b128 v[50:53], v66
	ds_read_b128 v[54:57], v66 offset:1024
	ds_read_b128 v[58:61], v66 offset:2048
	ds_read_b128 v[66:69], v66 offset:3072
	ds_read_b128 v[160:163], v74
	ds_read_b128 v[164:167], v74 offset:1024
	ds_read_b128 v[168:171], v74 offset:2048
	ds_read_b128 v[172:175], v74 offset:3072
	s_mov_b32 m0, s65
	v_lshl_add_u64 v[200:201], s[48:49], 0, v[158:159]
	ds_read_b128 v[74:77], v217 offset:32768
	ds_read_b128 v[82:85], v217 offset:33792
	ds_read_b128 v[176:179], v217 offset:34816
	ds_read_b128 v[180:183], v217 offset:35840
	ds_read_b128 v[184:187], v217 offset:36864
	ds_read_b128 v[188:191], v217 offset:37888
	ds_read_b128 v[192:195], v217 offset:38912
	ds_read_b128 v[196:199], v217 offset:39936
	global_load_lds_dwordx4 v[200:201], off
	v_lshl_add_u64 v[200:201], s[48:49], 0, v[156:157]
	s_mov_b32 m0, s66
	s_nop 0
	global_load_lds_dwordx4 v[200:201], off
	s_waitcnt vmcnt(8)
	s_waitcnt lgkmcnt(0)
	s_barrier
	s_setprio 1
	v_mfma_f32_16x16x32_bf16 v[150:153], v[50:53], v[74:77], v[150:153]
	v_mfma_f32_16x16x32_bf16 v[142:145], v[58:61], v[74:77], v[142:145]
	v_mfma_f32_16x16x32_bf16 v[134:137], v[50:53], v[176:179], v[134:137]
	v_mfma_f32_16x16x32_bf16 v[126:129], v[58:61], v[176:179], v[126:129]
	v_mfma_f32_16x16x32_bf16 v[118:121], v[50:53], v[184:187], v[118:121]
	v_mfma_f32_16x16x32_bf16 v[110:113], v[58:61], v[184:187], v[110:113]
	v_mfma_f32_16x16x32_bf16 v[102:105], v[50:53], v[192:195], v[102:105]
	v_mfma_f32_16x16x32_bf16 v[94:97], v[58:61], v[192:195], v[94:97]
	v_mfma_f32_16x16x32_bf16 v[150:153], v[54:57], v[82:85], v[150:153]
	v_mfma_f32_16x16x32_bf16 v[142:145], v[66:69], v[82:85], v[142:145]
	v_mfma_f32_16x16x32_bf16 v[134:137], v[54:57], v[180:183], v[134:137]
	v_mfma_f32_16x16x32_bf16 v[126:129], v[66:69], v[180:183], v[126:129]
	v_mfma_f32_16x16x32_bf16 v[118:121], v[54:57], v[188:191], v[118:121]
	v_mfma_f32_16x16x32_bf16 v[110:113], v[66:69], v[188:191], v[110:113]
	v_mfma_f32_16x16x32_bf16 v[102:105], v[54:57], v[196:199], v[102:105]
	v_mfma_f32_16x16x32_bf16 v[94:97], v[66:69], v[196:199], v[94:97]
	s_setprio 0
	s_setprio 1
	v_mfma_f32_16x16x32_bf16 v[146:149], v[160:163], v[74:77], v[146:149]
	v_mfma_f32_16x16x32_bf16 v[74:77], v[168:171], v[74:77], v[138:141]
	v_mfma_f32_16x16x32_bf16 v[138:141], v[172:175], v[82:85], v[74:77]
	v_mfma_f32_16x16x32_bf16 v[74:77], v[160:163], v[176:179], v[130:133]
	v_mfma_f32_16x16x32_bf16 v[130:133], v[164:167], v[180:183], v[74:77]
	v_mfma_f32_16x16x32_bf16 v[74:77], v[168:171], v[176:179], v[122:125]
	v_mfma_f32_16x16x32_bf16 v[122:125], v[172:175], v[180:183], v[74:77]
	v_mfma_f32_16x16x32_bf16 v[74:77], v[160:163], v[184:187], v[114:117]
	v_mfma_f32_16x16x32_bf16 v[114:117], v[164:167], v[188:191], v[74:77]
	v_mfma_f32_16x16x32_bf16 v[74:77], v[168:171], v[184:187], v[106:109]
	v_mfma_f32_16x16x32_bf16 v[106:109], v[172:175], v[188:191], v[74:77]
	v_mfma_f32_16x16x32_bf16 v[74:77], v[160:163], v[192:195], v[98:101]
	v_mfma_f32_16x16x32_bf16 v[98:101], v[164:167], v[196:199], v[74:77]
	v_mfma_f32_16x16x32_bf16 v[74:77], v[168:171], v[192:195], v[90:93]
	v_mfma_f32_16x16x32_bf16 v[146:149], v[164:167], v[82:85], v[146:149]
	v_mfma_f32_16x16x32_bf16 v[90:93], v[172:175], v[196:199], v[74:77]
	s_barrier
; #define PG8_STAGE(bufoff, gbase, voff) do { _Pragma("unroll") for (int _i = 0; _i < 2; ++_i) \
;         __builtin_amdgcn_global_load_lds((const unsigned*)((const char*)(gbase) + (voff)[_i]), (LAS unsigned*)(lds + (bufoff) + ldsw + _i * 8192), 16, 0, 0); } while (0)
; #define PG8_LDA(dst, b, h) do { _Pragma("unroll") for (int m = 0; m < 4; ++m) _Pragma("unroll") for (int k = 0; k < 2; ++k) dst[m][k] = *(const LAS bf16x8*)(lds + PG8_SA(b, h) + aoff + m * 2048 + k * 1024); } while (0)
; #define PG8_MMA(ai, bj, At, Bt) do { __builtin_amdgcn_s_setprio(1); _Pragma("unroll") for (int m = 0; m < 4; ++m) _Pragma("unroll") for (int n = 0; n < 2; ++n) _Pragma("unroll") for (int k = 0; k < 2; ++k) \
;         acc[ai][bj][m][n] = __builtin_amdgcn_mfma_f32_16x16x32_bf16(Bt[n][k], At[m][k], acc[ai][bj][m][n], 0, 0, 0); __builtin_amdgcn_s_setprio(0); } while (0)
; #define PG8_WAIT_V(n) asm volatile("s_waitcnt vmcnt(" #n ")" ::: "memory")
; #define PG8_WAIT_L(n) asm volatile("s_waitcnt lgkmcnt(" #n ")" ::: "memory")
; #define PG8_BAR __builtin_amdgcn_s_barrier()
; #define PG8_SCHED __builtin_amdgcn_sched_barrier(0)
; template <class Epi, class Sched, bool ALIGN_EPI, bool LAST_FUSED = false, bool PERM = false, bool CARRY = false>
; __device__ __forceinline__ void gemm_phase(LAS unsigned char* lds, const int tid, const int K, const int lda, const int ldb, const Sched& S, const Epi& E) {
;     ...
;             PG8_LDA(At, 1, 1); PG8_STAGE(PG8_SB(1, 0), b3, voffB); PG8_STAGE(PG8_SB(1, 1), b3 + hstepB, voffB); PG8_STAGE(PG8_SA(1, 0), a3, voffA);
;             PG8_WAIT_V(8); PG8_WAIT_L(0); PG8_BAR; PG8_MMA(1, 0, At, B0); PG8_MMA(1, 1, At, B1); PG8_BAR; PG8_SCHED;
;         }
	s_setprio 0
	s_mov_b32 m0, s19
	v_lshl_add_u64 v[82:83], v[204:205], 0, s[68:69]
	s_nop 1
	ds_read_b128 v[74:77], v217 offset:49152
	ds_read_b128 v[176:179], v217 offset:50176
	ds_read_b128 v[180:183], v217 offset:51200
	ds_read_b128 v[184:187], v217 offset:52224
	ds_read_b128 v[188:191], v217 offset:53248
	ds_read_b128 v[192:195], v217 offset:54272
	ds_read_b128 v[196:199], v217 offset:55296
	ds_read_b128 v[200:203], v217 offset:56320
	global_load_lds_dwordx4 v[82:83], off
	v_lshl_add_u64 v[82:83], v[206:207], 0, s[68:69]
	s_mov_b32 m0, s17
	s_nop 0
	global_load_lds_dwordx4 v[82:83], off
	v_lshl_add_u64 v[82:83], s[46:47], 0, v[0:1]
	s_mov_b32 m0, s78
	s_nop 0
	global_load_lds_dwordx4 v[82:83], off
	v_lshl_add_u64 v[82:83], s[46:47], 0, v[154:155]
	s_mov_b32 m0, s45
	s_nop 0
	global_load_lds_dwordx4 v[82:83], off
	v_lshl_add_u64 v[82:83], v[208:209], 0, s[68:69]
	s_mov_b32 m0, s74
	s_nop 0
	global_load_lds_dwordx4 v[82:83], off
	v_lshl_add_u64 v[82:83], v[210:211], 0, s[68:69]
	s_mov_b32 m0, s75
	s_nop 0
	global_load_lds_dwordx4 v[82:83], off
	s_waitcnt vmcnt(8)
	s_waitcnt lgkmcnt(0)
	s_barrier
	s_setprio 1
	v_mfma_f32_16x16x32_bf16 v[82:85], v[50:53], v[74:77], v[86:89]
	v_mfma_f32_16x16x32_bf16 v[78:81], v[58:61], v[74:77], v[78:81]
	v_mfma_f32_16x16x32_bf16 v[70:73], v[50:53], v[180:183], v[70:73]
	v_mfma_f32_16x16x32_bf16 v[62:65], v[58:61], v[180:183], v[62:65]
	v_mfma_f32_16x16x32_bf16 v[42:45], v[50:53], v[188:191], v[42:45]
	v_mfma_f32_16x16x32_bf16 v[22:25], v[58:61], v[188:191], v[22:25]
	v_mfma_f32_16x16x32_bf16 v[14:17], v[50:53], v[196:199], v[14:17]
	v_mfma_f32_16x16x32_bf16 v[6:9], v[58:61], v[196:199], v[6:9]
	v_mfma_f32_16x16x32_bf16 v[86:89], v[54:57], v[176:179], v[82:85]
	v_mfma_f32_16x16x32_bf16 v[78:81], v[66:69], v[176:179], v[78:81]
	v_mfma_f32_16x16x32_bf16 v[70:73], v[54:57], v[184:187], v[70:73]
	v_mfma_f32_16x16x32_bf16 v[62:65], v[66:69], v[184:187], v[62:65]
	v_mfma_f32_16x16x32_bf16 v[42:45], v[54:57], v[192:195], v[42:45]
	v_mfma_f32_16x16x32_bf16 v[22:25], v[66:69], v[192:195], v[22:25]
	v_mfma_f32_16x16x32_bf16 v[14:17], v[54:57], v[200:203], v[14:17]
	v_mfma_f32_16x16x32_bf16 v[6:9], v[66:69], v[200:203], v[6:9]
	s_setprio 0
	s_setprio 1
	v_mfma_f32_16x16x32_bf16 v[26:29], v[160:163], v[74:77], v[26:29]
	v_mfma_f32_16x16x32_bf16 v[82:85], v[164:167], v[176:179], v[26:29]
	v_mfma_f32_16x16x32_bf16 v[26:29], v[168:171], v[74:77], v[34:37]
	v_mfma_f32_16x16x32_bf16 v[74:77], v[172:175], v[176:179], v[26:29]
	v_mfma_f32_16x16x32_bf16 v[26:29], v[160:163], v[180:183], v[38:41]
	v_mfma_f32_16x16x32_bf16 v[66:69], v[164:167], v[184:187], v[26:29]
	v_mfma_f32_16x16x32_bf16 v[26:29], v[168:171], v[180:183], v[46:49]
	v_mfma_f32_16x16x32_bf16 v[50:53], v[172:175], v[184:187], v[26:29]
	v_mfma_f32_16x16x32_bf16 v[26:29], v[160:163], v[188:191], v[30:33]
	v_mfma_f32_16x16x32_bf16 v[18:21], v[168:171], v[188:191], v[18:21]
	v_mfma_f32_16x16x32_bf16 v[10:13], v[160:163], v[196:199], v[10:13]
	v_mfma_f32_16x16x32_bf16 v[2:5], v[168:171], v[196:199], v[2:5]
	v_mfma_f32_16x16x32_bf16 v[30:33], v[164:167], v[192:195], v[26:29]
	v_mfma_f32_16x16x32_bf16 v[18:21], v[172:175], v[192:195], v[18:21]
	v_mfma_f32_16x16x32_bf16 v[10:13], v[164:167], v[200:203], v[10:13]
	v_mfma_f32_16x16x32_bf16 v[2:5], v[172:175], v[200:203], v[2:5]
	s_barrier
	s_setprio 0
	s_movk_i32 s17, 0x100
	s_andn2_b64 vcc, exec, s[42:43]
	s_mov_b64 s[46:47], -1
	s_mov_b64 s[42:43], 0
	s_cbranch_vccz .LBB0_1367
	s_and_b64 vcc, exec, s[14:15]
	s_cbranch_vccz .LBB0_1370
	s_barrier

; #define PG8_STAGE(bufoff, gbase, voff) do { _Pragma("unroll") for (int _i = 0; _i < 2; ++_i) \
;         __builtin_amdgcn_global_load_lds((const unsigned*)((const char*)(gbase) + (voff)[_i]), (LAS unsigned*)(lds + (bufoff) + ldsw + _i * 8192), 16, 0, 0); } while (0)
; #define PG8_LDA(dst, b, h) do { _Pragma("unroll") for (int m = 0; m < 4; ++m) _Pragma("unroll") for (int k = 0; k < 2; ++k) dst[m][k] = *(const LAS bf16x8*)(lds + PG8_SA(b, h) + aoff + m * 2048 + k * 1024); } while (0)
; #define PG8_LDB(dst, b, h) do { _Pragma("unroll") for (int n = 0; n < 2; ++n) _Pragma("unroll") for (int k = 0; k < 2; ++k) dst[n][k] = *(const LAS bf16x8*)(lds + PG8_SB(b, h) + boff + n * 2048 + k * 1024); } while (0)
; #define PG8_WAIT_V(n) asm volatile("s_waitcnt vmcnt(" #n ")" ::: "memory")
; #define PG8_WAIT_L(n) asm volatile("s_waitcnt lgkmcnt(" #n ")" ::: "memory")
; #define PG8_BAR __builtin_amdgcn_s_barrier()
; #define PG8_SCHED __builtin_amdgcn_sched_barrier(0)
; template <class Epi, class Sched, bool ALIGN_EPI, bool LAST_FUSED = false, bool PERM = false, bool CARRY = false>
; __device__ __forceinline__ void gemm_phase(LAS unsigned char* lds, const int tid, const int K, const int lda, const int ldb, const Sched& S, const Epi& E) {
;     ...
;         const bool has_next = S.next(KD_IDX(ui + 1), nxt);
;         const char* nA = has_next ? nxt.a : cA; const char* nB = has_next ? nxt.b : cB; const int nt = cur.nt;
; #pragma unroll 1
;         for (int t = 0; t < nt; t += 2) {
;             const bool last = (t == nt - 2);
;             const char* a1 = cA + (size_t)(t + 1) * kstep;
;             const char* a2 = last ? nA : cA + (size_t)(t + 2) * kstep; const char* b2 = last ? nB : cB + (size_t)(t + 2) * kstep;
;             const char* a3 = a2 + kstep; const char* b3 = b2 + kstep;
;             PG8_LDB(B0, 0, 0); PG8_LDB(B1, 0, 1); PG8_SCHED; PG8_LDA(At, 0, 0); PG8_STAGE(PG8_SA(1, 1), a1 + hstepA, voffA);
;             PG8_WAIT_V(8); PG8_WAIT_L(0); PG8_BAR; PG8_MMA(0, 0, At, B0); PG8_MMA(0, 1, At, B1); PG8_BAR; PG8_SCHED;
;             PG8_LDA(At, 0, 1); PG8_STAGE(PG8_SB(0, 0), b2, voffB); PG8_STAGE(PG8_SB(0, 1), b2 + hstepB, voffB); PG8_STAGE(PG8_SA(0, 0), a2, voffA);
;             PG8_WAIT_V(8); PG8_WAIT_L(0); PG8_BAR; PG8_MMA(1, 0, At, B0); PG8_MMA(1, 1, At, B1); PG8_BAR; PG8_SCHED;
.LBB0_1585:
	s_add_u32 s52, s42, s48
	s_addc_u32 s53, s43, s49
	s_add_u32 s76, s40, s48
	s_addc_u32 s77, s41, s49
	s_add_i32 s96, 0, 0x10000
	s_cmp_eq_u32 s3, s95
	s_cselect_b32 s53, s24, s53
	s_cselect_b32 s52, s55, s52
	s_cselect_b32 s77, s93, s77
	s_cselect_b32 s76, s94, s76
	s_add_i32 vcc_lo, 0, 0x14000
	v_add_u32_e32 v156, s96, v140
	v_add_u32_e32 v172, vcc_lo, v140
	ds_read_b128 v[142:145], v156
	ds_read_b128 v[146:149], v156 offset:1024
	ds_read_b128 v[150:153], v156 offset:2048
	ds_read_b128 v[156:159], v156 offset:3072
	ds_read_b128 v[160:163], v172
	ds_read_b128 v[164:167], v172 offset:1024
	ds_read_b128 v[168:171], v172 offset:2048
	ds_read_b128 v[172:175], v172 offset:3072
	v_lshl_add_u64 v[208:209], s[42:43], 0, v[138:139]
	s_add_i32 m0, s35, 0xc000
	ds_read_b128 v[176:179], v141
	ds_read_b128 v[180:183], v141 offset:1024
	ds_read_b128 v[184:187], v141 offset:2048
	ds_read_b128 v[188:191], v141 offset:3072
	ds_read_b128 v[192:195], v141 offset:4096
	ds_read_b128 v[196:199], v141 offset:5120
	ds_read_b128 v[200:203], v141 offset:6144
	ds_read_b128 v[204:207], v141 offset:7168
	global_load_lds_dwordx4 v[208:209], off
	v_lshl_add_u64 v[208:209], s[42:43], 0, v[128:129]
	s_add_i32 m0, s35, 0xe000
	s_nop 0
	global_load_lds_dwordx4 v[208:209], off
	s_waitcnt vmcnt(8)
	s_waitcnt lgkmcnt(0)
	s_barrier
	s_setprio 1
	v_mfma_f32_16x16x32_bf16 v[62:65], v[142:145], v[176:179], v[62:65]
	v_mfma_f32_16x16x32_bf16 v[42:45], v[150:153], v[176:179], v[42:45]
	v_mfma_f32_16x16x32_bf16 v[18:21], v[142:145], v[184:187], v[18:21]
	v_mfma_f32_16x16x32_bf16 v[14:17], v[150:153], v[184:187], v[14:17]
	v_mfma_f32_16x16x32_bf16 v[38:41], v[142:145], v[192:195], v[38:41]
	v_mfma_f32_16x16x32_bf16 v[30:33], v[150:153], v[192:195], v[30:33]
	v_mfma_f32_16x16x32_bf16 v[58:61], v[142:145], v[200:203], v[58:61]
	v_mfma_f32_16x16x32_bf16 v[54:57], v[150:153], v[200:203], v[54:57]
	v_mfma_f32_16x16x32_bf16 v[62:65], v[146:149], v[180:183], v[62:65]
	v_mfma_f32_16x16x32_bf16 v[42:45], v[156:159], v[180:183], v[42:45]
	v_mfma_f32_16x16x32_bf16 v[18:21], v[146:149], v[188:191], v[18:21]
	v_mfma_f32_16x16x32_bf16 v[14:17], v[156:159], v[188:191], v[14:17]
	v_mfma_f32_16x16x32_bf16 v[38:41], v[146:149], v[196:199], v[38:41]
	v_mfma_f32_16x16x32_bf16 v[30:33], v[156:159], v[196:199], v[30:33]
	v_mfma_f32_16x16x32_bf16 v[58:61], v[146:149], v[204:207], v[58:61]
	v_mfma_f32_16x16x32_bf16 v[54:57], v[156:159], v[204:207], v[54:57]
	s_setprio 0
	s_setprio 1
	v_mfma_f32_16x16x32_bf16 v[34:37], v[160:163], v[176:179], v[34:37]
	v_mfma_f32_16x16x32_bf16 v[2:5], v[168:171], v[176:179], v[2:5]
	v_mfma_f32_16x16x32_bf16 v[10:13], v[160:163], v[184:187], v[10:13]
	v_mfma_f32_16x16x32_bf16 v[6:9], v[168:171], v[184:187], v[6:9]
	v_mfma_f32_16x16x32_bf16 v[26:29], v[160:163], v[192:195], v[26:29]
	v_mfma_f32_16x16x32_bf16 v[22:25], v[168:171], v[192:195], v[22:25]
	v_mfma_f32_16x16x32_bf16 v[50:53], v[160:163], v[200:203], v[50:53]
	v_mfma_f32_16x16x32_bf16 v[46:49], v[168:171], v[200:203], v[46:49]
	v_mfma_f32_16x16x32_bf16 v[34:37], v[164:167], v[180:183], v[34:37]
	v_mfma_f32_16x16x32_bf16 v[2:5], v[172:175], v[180:183], v[2:5]
	v_mfma_f32_16x16x32_bf16 v[10:13], v[164:167], v[188:191], v[10:13]
	v_mfma_f32_16x16x32_bf16 v[6:9], v[172:175], v[188:191], v[6:9]
	v_mfma_f32_16x16x32_bf16 v[26:29], v[164:167], v[196:199], v[26:29]
	v_mfma_f32_16x16x32_bf16 v[22:25], v[172:175], v[196:199], v[22:25]
	v_mfma_f32_16x16x32_bf16 v[50:53], v[164:167], v[204:207], v[50:53]
	v_mfma_f32_16x16x32_bf16 v[46:49], v[172:175], v[204:207], v[46:49]
	s_barrier
	s_setprio 0
	s_add_i32 s96, s96, s87
	v_lshl_add_u64 v[208:209], s[76:77], 0, v[0:1]
	s_mov_b32 m0, s96
	ds_read_b128 v[176:179], v141 offset:16384
	ds_read_b128 v[180:183], v141 offset:17408
	ds_read_b128 v[184:187], v141 offset:18432
	ds_read_b128 v[188:191], v141 offset:19456
	ds_read_b128 v[192:195], v141 offset:20480
	ds_read_b128 v[196:199], v141 offset:21504
	ds_read_b128 v[200:203], v141 offset:22528
	ds_read_b128 v[204:207], v141 offset:23552
	global_load_lds_dwordx4 v[208:209], off
	s_add_i32 m0, s96, 0x2000
	s_add_u32 s96, s76, 0x80000
	v_lshl_add_u64 v[210:211], s[76:77], 0, v[122:123]
	s_addc_u32 s97, s77, 0
	s_add_i32 vcc_lo, vcc_lo, s87
	global_load_lds_dwordx4 v[210:211], off
	v_lshl_add_u64 v[212:213], s[96:97], 0, v[0:1]
	s_mov_b32 m0, vcc_lo
	v_lshl_add_u64 v[214:215], s[52:53], 0, v[122:123]
	global_load_lds_dwordx4 v[212:213], off
	v_lshl_add_u64 v[212:213], s[96:97], 0, v[122:123]
	s_add_i32 m0, vcc_lo, 0x2000
	s_nop 0
	global_load_lds_dwordx4 v[212:213], off
	v_lshl_add_u64 v[212:213], s[52:53], 0, v[0:1]
	s_mov_b32 m0, s35
	s_nop 0
	global_load_lds_dwordx4 v[212:213], off
	s_mov_b32 m0, s28
	s_nop 0
	global_load_lds_dwordx4 v[214:215], off
	s_waitcnt vmcnt(8)
	s_waitcnt lgkmcnt(0)
	s_barrier
; #define PG8_STAGE(bufoff, gbase, voff) do { _Pragma("unroll") for (int _i = 0; _i < 2; ++_i) \
;         __builtin_amdgcn_global_load_lds((const unsigned*)((const char*)(gbase) + (voff)[_i]), (LAS unsigned*)(lds + (bufoff) + ldsw + _i * 8192), 16, 0, 0); } while (0)
; #define PG8_LDA(dst, b, h) do { _Pragma("unroll") for (int m = 0; m < 4; ++m) _Pragma("unroll") for (int k = 0; k < 2; ++k) dst[m][k] = *(const LAS bf16x8*)(lds + PG8_SA(b, h) + aoff + m * 2048 + k * 1024); } while (0)
; #define PG8_LDB(dst, b, h) do { _Pragma("unroll") for (int n = 0; n < 2; ++n) _Pragma("unroll") for (int k = 0; k < 2; ++k) dst[n][k] = *(const LAS bf16x8*)(lds + PG8_SB(b, h) + boff + n * 2048 + k * 1024); } while (0)
; #define PG8_MMA(ai, bj, At, Bt) do { __builtin_amdgcn_s_setprio(1); _Pragma("unroll") for (int m = 0; m < 4; ++m) _Pragma("unroll") for (int n = 0; n < 2; ++n) _Pragma("unroll") for (int k = 0; k < 2; ++k) \
;         acc[ai][bj][m][n] = __builtin_amdgcn_mfma_f32_16x16x32_bf16(Bt[n][k], At[m][k], acc[ai][bj][m][n], 0, 0, 0); __builtin_amdgcn_s_setprio(0); } while (0)
; #define PG8_WAIT_V(n) asm volatile("s_waitcnt vmcnt(" #n ")" ::: "memory")
; #define PG8_WAIT_L(n) asm volatile("s_waitcnt lgkmcnt(" #n ")" ::: "memory")
; #define PG8_BAR __builtin_amdgcn_s_barrier()
; #define PG8_SCHED __builtin_amdgcn_sched_barrier(0)
; template <class Epi, class Sched, bool ALIGN_EPI, bool LAST_FUSED = false, bool PERM = false, bool CARRY = false>
; __device__ __forceinline__ void gemm_phase(LAS unsigned char* lds, const int tid, const int K, const int lda, const int ldb, const Sched& S, const Epi& E) {
;     ...
;             PG8_WAIT_V(8); PG8_WAIT_L(0); PG8_BAR; PG8_MMA(1, 0, At, B0); PG8_MMA(1, 1, At, B1); PG8_BAR; PG8_SCHED;
;             PG8_LDB(B0, 1, 0); PG8_LDB(B1, 1, 1); PG8_SCHED; PG8_LDA(At, 1, 0); PG8_STAGE(PG8_SA(0, 1), a2 + hstepA, voffA);
;             PG8_WAIT_V(8); PG8_WAIT_L(0); PG8_BAR; PG8_MMA(0, 0, At, B0); PG8_MMA(0, 1, At, B1); PG8_BAR; PG8_SCHED;
;             PG8_LDA(At, 1, 1); PG8_STAGE(PG8_SB(1, 0), b3, voffB); PG8_STAGE(PG8_SB(1, 1), b3 + hstepB, voffB); PG8_STAGE(PG8_SA(1, 0), a3, voffA);
;             PG8_WAIT_V(8); PG8_WAIT_L(0); PG8_BAR; PG8_MMA(1, 0, At, B0); PG8_MMA(1, 1, At, B1); PG8_BAR; PG8_SCHED;
	s_setprio 1
	v_mfma_f32_16x16x32_bf16 v[78:81], v[142:145], v[176:179], v[78:81]
	v_mfma_f32_16x16x32_bf16 v[74:77], v[150:153], v[176:179], v[74:77]
	v_mfma_f32_16x16x32_bf16 v[98:101], v[142:145], v[184:187], v[98:101]
	v_mfma_f32_16x16x32_bf16 v[94:97], v[150:153], v[184:187], v[94:97]
	v_mfma_f32_16x16x32_bf16 v[118:121], v[142:145], v[192:195], v[118:121]
	v_mfma_f32_16x16x32_bf16 v[114:117], v[150:153], v[192:195], v[114:117]
	v_mfma_f32_16x16x32_bf16 v[134:137], v[142:145], v[200:203], v[134:137]
	v_mfma_f32_16x16x32_bf16 v[130:133], v[150:153], v[200:203], v[130:133]
	v_mfma_f32_16x16x32_bf16 v[78:81], v[146:149], v[180:183], v[78:81]
	v_mfma_f32_16x16x32_bf16 v[74:77], v[156:159], v[180:183], v[74:77]
	v_mfma_f32_16x16x32_bf16 v[98:101], v[146:149], v[188:191], v[98:101]
	v_mfma_f32_16x16x32_bf16 v[94:97], v[156:159], v[188:191], v[94:97]
	v_mfma_f32_16x16x32_bf16 v[118:121], v[146:149], v[196:199], v[118:121]
	v_mfma_f32_16x16x32_bf16 v[114:117], v[156:159], v[196:199], v[114:117]
	v_mfma_f32_16x16x32_bf16 v[134:137], v[146:149], v[204:207], v[134:137]
	v_mfma_f32_16x16x32_bf16 v[130:133], v[156:159], v[204:207], v[130:133]
	s_setprio 0
	s_setprio 1
	v_mfma_f32_16x16x32_bf16 v[70:73], v[160:163], v[176:179], v[70:73]
	v_mfma_f32_16x16x32_bf16 v[66:69], v[168:171], v[176:179], v[66:69]
	v_mfma_f32_16x16x32_bf16 v[90:93], v[160:163], v[184:187], v[90:93]
	v_mfma_f32_16x16x32_bf16 v[86:89], v[168:171], v[184:187], v[86:89]
	v_mfma_f32_16x16x32_bf16 v[110:113], v[160:163], v[192:195], v[110:113]
	v_mfma_f32_16x16x32_bf16 v[106:109], v[168:171], v[192:195], v[106:109]
	v_mfma_f32_16x16x32_bf16 v[102:105], v[160:163], v[200:203], v[102:105]
	v_mfma_f32_16x16x32_bf16 v[82:85], v[168:171], v[200:203], v[82:85]
	v_mfma_f32_16x16x32_bf16 v[70:73], v[164:167], v[180:183], v[70:73]
	v_mfma_f32_16x16x32_bf16 v[66:69], v[172:175], v[180:183], v[66:69]
	v_mfma_f32_16x16x32_bf16 v[90:93], v[164:167], v[188:191], v[90:93]
	v_mfma_f32_16x16x32_bf16 v[86:89], v[172:175], v[188:191], v[86:89]
	v_mfma_f32_16x16x32_bf16 v[110:113], v[164:167], v[196:199], v[110:113]
	v_mfma_f32_16x16x32_bf16 v[106:109], v[172:175], v[196:199], v[106:109]
	v_mfma_f32_16x16x32_bf16 v[102:105], v[164:167], v[204:207], v[102:105]
	v_mfma_f32_16x16x32_bf16 v[82:85], v[172:175], v[204:207], v[82:85]
	s_barrier
	s_setprio 0
	s_add_i32 s96, 0, 0x18000
	s_add_i32 s97, 0, 0x1c000
	v_add_u32_e32 v156, s96, v140
	v_add_u32_e32 v172, s97, v140
	ds_read_b128 v[142:145], v156
	ds_read_b128 v[146:149], v156 offset:1024
	ds_read_b128 v[150:153], v156 offset:2048
	ds_read_b128 v[156:159], v156 offset:3072
	ds_read_b128 v[160:163], v172
	ds_read_b128 v[164:167], v172 offset:1024
	ds_read_b128 v[168:171], v172 offset:2048
	ds_read_b128 v[172:175], v172 offset:3072
	s_add_u32 s52, s52, 0x80000
	s_addc_u32 s53, s53, 0
	s_mov_b32 m0, s29
	v_lshl_add_u64 v[216:217], s[52:53], 0, v[0:1]
	ds_read_b128 v[176:179], v141 offset:32768
	ds_read_b128 v[180:183], v141 offset:33792
	ds_read_b128 v[184:187], v141 offset:34816
	ds_read_b128 v[188:191], v141 offset:35840
	ds_read_b128 v[192:195], v141 offset:36864
	ds_read_b128 v[196:199], v141 offset:37888
	ds_read_b128 v[200:203], v141 offset:38912
	ds_read_b128 v[204:207], v141 offset:39936
	global_load_lds_dwordx4 v[216:217], off
	v_lshl_add_u64 v[216:217], s[52:53], 0, v[122:123]
	s_mov_b32 m0, s14
	s_nop 0
	global_load_lds_dwordx4 v[216:217], off
	s_waitcnt vmcnt(8)
	s_waitcnt lgkmcnt(0)
	s_barrier
	s_setprio 1
	v_mfma_f32_16x16x32_bf16 v[62:65], v[142:145], v[176:179], v[62:65]
	v_mfma_f32_16x16x32_bf16 v[42:45], v[150:153], v[176:179], v[42:45]
	v_mfma_f32_16x16x32_bf16 v[18:21], v[142:145], v[184:187], v[18:21]
	v_mfma_f32_16x16x32_bf16 v[14:17], v[150:153], v[184:187], v[14:17]
	v_mfma_f32_16x16x32_bf16 v[38:41], v[142:145], v[192:195], v[38:41]
	v_mfma_f32_16x16x32_bf16 v[30:33], v[150:153], v[192:195], v[30:33]
	v_mfma_f32_16x16x32_bf16 v[58:61], v[142:145], v[200:203], v[58:61]
	v_mfma_f32_16x16x32_bf16 v[54:57], v[150:153], v[200:203], v[54:57]
	v_mfma_f32_16x16x32_bf16 v[62:65], v[146:149], v[180:183], v[62:65]
	v_mfma_f32_16x16x32_bf16 v[42:45], v[156:159], v[180:183], v[42:45]
	v_mfma_f32_16x16x32_bf16 v[18:21], v[146:149], v[188:191], v[18:21]
	v_mfma_f32_16x16x32_bf16 v[14:17], v[156:159], v[188:191], v[14:17]
	v_mfma_f32_16x16x32_bf16 v[38:41], v[146:149], v[196:199], v[38:41]
	v_mfma_f32_16x16x32_bf16 v[30:33], v[156:159], v[196:199], v[30:33]
	v_mfma_f32_16x16x32_bf16 v[58:61], v[146:149], v[204:207], v[58:61]
	v_mfma_f32_16x16x32_bf16 v[54:57], v[156:159], v[204:207], v[54:57]
	s_setprio 0
	s_setprio 1
	v_mfma_f32_16x16x32_bf16 v[34:37], v[160:163], v[176:179], v[34:37]
	v_mfma_f32_16x16x32_bf16 v[2:5], v[168:171], v[176:179], v[2:5]
	v_mfma_f32_16x16x32_bf16 v[10:13], v[160:163], v[184:187], v[10:13]
	v_mfma_f32_16x16x32_bf16 v[6:9], v[168:171], v[184:187], v[6:9]
	v_mfma_f32_16x16x32_bf16 v[26:29], v[160:163], v[192:195], v[26:29]
	v_mfma_f32_16x16x32_bf16 v[22:25], v[168:171], v[192:195], v[22:25]
	v_mfma_f32_16x16x32_bf16 v[50:53], v[160:163], v[200:203], v[50:53]
	v_mfma_f32_16x16x32_bf16 v[46:49], v[168:171], v[200:203], v[46:49]
	v_mfma_f32_16x16x32_bf16 v[34:37], v[164:167], v[180:183], v[34:37]
	v_mfma_f32_16x16x32_bf16 v[2:5], v[172:175], v[180:183], v[2:5]
	v_mfma_f32_16x16x32_bf16 v[10:13], v[164:167], v[188:191], v[10:13]
	v_mfma_f32_16x16x32_bf16 v[6:9], v[172:175], v[188:191], v[6:9]
	v_mfma_f32_16x16x32_bf16 v[26:29], v[164:167], v[196:199], v[26:29]
	v_mfma_f32_16x16x32_bf16 v[22:25], v[172:175], v[196:199], v[22:25]
	v_mfma_f32_16x16x32_bf16 v[50:53], v[164:167], v[204:207], v[50:53]
	v_mfma_f32_16x16x32_bf16 v[46:49], v[172:175], v[204:207], v[46:49]
	s_barrier
; #define PG8_STAGE(bufoff, gbase, voff) do { _Pragma("unroll") for (int _i = 0; _i < 2; ++_i) \
;         __builtin_amdgcn_global_load_lds((const unsigned*)((const char*)(gbase) + (voff)[_i]), (LAS unsigned*)(lds + (bufoff) + ldsw + _i * 8192), 16, 0, 0); } while (0)
; #define PG8_LDA(dst, b, h) do { _Pragma("unroll") for (int m = 0; m < 4; ++m) _Pragma("unroll") for (int k = 0; k < 2; ++k) dst[m][k] = *(const LAS bf16x8*)(lds + PG8_SA(b, h) + aoff + m * 2048 + k * 1024); } while (0)
; #define PG8_LDB(dst, b, h) do { _Pragma("unroll") for (int n = 0; n < 2; ++n) _Pragma("unroll") for (int k = 0; k < 2; ++k) dst[n][k] = *(const LAS bf16x8*)(lds + PG8_SB(b, h) + boff + n * 2048 + k * 1024); } while (0)
; #define PG8_WAIT_V(n) asm volatile("s_waitcnt vmcnt(" #n ")" ::: "memory")
; #define PG8_WAIT_L(n) asm volatile("s_waitcnt lgkmcnt(" #n ")" ::: "memory")
; #define PG8_BAR __builtin_amdgcn_s_barrier()
; #define PG8_SCHED __builtin_amdgcn_sched_barrier(0)
; template <class Epi, class Sched, bool ALIGN_EPI, bool LAST_FUSED = false, bool PERM = false, bool CARRY = false>
; __device__ __forceinline__ void gemm_phase(LAS unsigned char* lds, const int tid, const int K, const int lda, const int ldb, const Sched& S, const Epi& E) {
;     ...
;             PG8_LDB(B0, 0, 0); PG8_LDB(B1, 0, 1); PG8_SCHED; PG8_LDA(At, 0, 0); PG8_STAGE(PG8_SA(1, 1), a1 + hstepA, voffA);
;             PG8_WAIT_V(8); PG8_WAIT_L(0); PG8_BAR; PG8_MMA(0, 0, At, B0); PG8_MMA(0, 1, At, B1); PG8_BAR; PG8_SCHED;
;             PG8_LDA(At, 0, 1); PG8_STAGE(PG8_SB(0, 0), b2, voffB); PG8_STAGE(PG8_SB(0, 1), b2 + hstepB, voffB); PG8_STAGE(PG8_SA(0, 0), a2, voffA);
;             PG8_WAIT_V(8); PG8_WAIT_L(0); PG8_BAR; PG8_MMA(1, 0, At, B0); PG8_MMA(1, 1, At, B1); PG8_BAR; PG8_SCHED;
;             PG8_LDB(B0, 1, 0); PG8_LDB(B1, 1, 1); PG8_SCHED; PG8_LDA(At, 1, 0); PG8_STAGE(PG8_SA(0, 1), a2 + hstepA, voffA);
;             PG8_WAIT_V(8); PG8_WAIT_L(0); PG8_BAR; PG8_MMA(0, 0, At, B0); PG8_MMA(0, 1, At, B1); PG8_BAR; PG8_SCHED;
;             PG8_LDA(At, 1, 1); PG8_STAGE(PG8_SB(1, 0), b3, voffB); PG8_STAGE(PG8_SB(1, 1), b3 + hstepB, voffB); PG8_STAGE(PG8_SA(1, 0), a3, voffA);
;             PG8_WAIT_V(8); PG8_WAIT_L(0); PG8_BAR; PG8_MMA(1, 0, At, B0); PG8_MMA(1, 1, At, B1); PG8_BAR; PG8_SCHED;
;         }
;         if constexpr (ALIGN_EPI) { if (wr == 0) PG8_BAR; }
	s_setprio 0
	s_add_i32 s52, s96, s87
	v_lshl_add_u64 v[208:209], v[208:209], 0, s[68:69]
	s_mov_b32 m0, s52
	ds_read_b128 v[176:179], v141 offset:49152
	ds_read_b128 v[180:183], v141 offset:50176
	ds_read_b128 v[184:187], v141 offset:51200
	ds_read_b128 v[188:191], v141 offset:52224
	ds_read_b128 v[192:195], v141 offset:53248
	ds_read_b128 v[196:199], v141 offset:54272
	ds_read_b128 v[200:203], v141 offset:55296
	ds_read_b128 v[204:207], v141 offset:56320
	global_load_lds_dwordx4 v[208:209], off
	s_add_i32 m0, s52, 0x2000
	s_add_u32 s52, s76, 0x80080
	v_lshl_add_u64 v[208:209], v[210:211], 0, s[68:69]
	s_addc_u32 s53, s77, 0
	s_add_i32 s76, s97, s87
	global_load_lds_dwordx4 v[208:209], off
	v_lshl_add_u64 v[208:209], s[52:53], 0, v[0:1]
	s_mov_b32 m0, s76
	s_nop 0
	global_load_lds_dwordx4 v[208:209], off
	v_lshl_add_u64 v[208:209], s[52:53], 0, v[122:123]
	s_add_i32 m0, s76, 0x2000
	s_nop 0
	global_load_lds_dwordx4 v[208:209], off
	v_lshl_add_u64 v[208:209], v[212:213], 0, s[68:69]
	s_mov_b32 m0, s85
	s_nop 0
	global_load_lds_dwordx4 v[208:209], off
	v_lshl_add_u64 v[208:209], v[214:215], 0, s[68:69]
	s_mov_b32 m0, s89
	s_nop 0
	global_load_lds_dwordx4 v[208:209], off
	s_waitcnt vmcnt(8)
	s_waitcnt lgkmcnt(0)
	s_barrier
	s_setprio 1
	v_mfma_f32_16x16x32_bf16 v[78:81], v[142:145], v[176:179], v[78:81]
	v_mfma_f32_16x16x32_bf16 v[74:77], v[150:153], v[176:179], v[74:77]
	v_mfma_f32_16x16x32_bf16 v[98:101], v[142:145], v[184:187], v[98:101]
	v_mfma_f32_16x16x32_bf16 v[94:97], v[150:153], v[184:187], v[94:97]
	v_mfma_f32_16x16x32_bf16 v[118:121], v[142:145], v[192:195], v[118:121]
	v_mfma_f32_16x16x32_bf16 v[114:117], v[150:153], v[192:195], v[114:117]
	v_mfma_f32_16x16x32_bf16 v[134:137], v[142:145], v[200:203], v[134:137]
	v_mfma_f32_16x16x32_bf16 v[130:133], v[150:153], v[200:203], v[130:133]
	v_mfma_f32_16x16x32_bf16 v[78:81], v[146:149], v[180:183], v[78:81]
	v_mfma_f32_16x16x32_bf16 v[74:77], v[156:159], v[180:183], v[74:77]
	v_mfma_f32_16x16x32_bf16 v[98:101], v[146:149], v[188:191], v[98:101]
	v_mfma_f32_16x16x32_bf16 v[94:97], v[156:159], v[188:191], v[94:97]
	v_mfma_f32_16x16x32_bf16 v[118:121], v[146:149], v[196:199], v[118:121]
	v_mfma_f32_16x16x32_bf16 v[114:117], v[156:159], v[196:199], v[114:117]
	v_mfma_f32_16x16x32_bf16 v[134:137], v[146:149], v[204:207], v[134:137]
	v_mfma_f32_16x16x32_bf16 v[130:133], v[156:159], v[204:207], v[130:133]
	s_setprio 0
	s_setprio 1
	v_mfma_f32_16x16x32_bf16 v[70:73], v[160:163], v[176:179], v[70:73]
	v_mfma_f32_16x16x32_bf16 v[66:69], v[168:171], v[176:179], v[66:69]
	v_mfma_f32_16x16x32_bf16 v[90:93], v[160:163], v[184:187], v[90:93]
	v_mfma_f32_16x16x32_bf16 v[86:89], v[168:171], v[184:187], v[86:89]
	v_mfma_f32_16x16x32_bf16 v[110:113], v[160:163], v[192:195], v[110:113]
	v_mfma_f32_16x16x32_bf16 v[106:109], v[168:171], v[192:195], v[106:109]
	v_mfma_f32_16x16x32_bf16 v[102:105], v[160:163], v[200:203], v[102:105]
	v_mfma_f32_16x16x32_bf16 v[82:85], v[168:171], v[200:203], v[82:85]
	v_mfma_f32_16x16x32_bf16 v[70:73], v[164:167], v[180:183], v[70:73]
	v_mfma_f32_16x16x32_bf16 v[66:69], v[172:175], v[180:183], v[66:69]
	v_mfma_f32_16x16x32_bf16 v[90:93], v[164:167], v[188:191], v[90:93]
	v_mfma_f32_16x16x32_bf16 v[86:89], v[172:175], v[188:191], v[86:89]
	v_mfma_f32_16x16x32_bf16 v[110:113], v[164:167], v[196:199], v[110:113]
	v_mfma_f32_16x16x32_bf16 v[106:109], v[172:175], v[196:199], v[106:109]
	v_mfma_f32_16x16x32_bf16 v[102:105], v[164:167], v[204:207], v[102:105]
	v_mfma_f32_16x16x32_bf16 v[82:85], v[172:175], v[204:207], v[82:85]
	s_barrier
	s_setprio 0
	s_add_i32 s52, s95, 2
	s_add_u32 s48, s48, 0x100
	s_addc_u32 s49, s49, 0
	v_lshl_add_u64 v[138:139], v[138:139], 0, s[72:73]
	v_lshl_add_u64 v[128:129], v[128:129], 0, s[72:73]
	s_cmp_ge_i32 s95, s3
	s_mov_b32 s95, s52
	s_cbranch_scc0 .LBB0_1585
	s_and_b64 vcc, exec, s[36:37]
	s_cbranch_vccz .LBB0_1588
	s_barrier

; #define PG8_STAGE(bufoff, gbase, voff) do { _Pragma("unroll") for (int _i = 0; _i < 2; ++_i) \
;         __builtin_amdgcn_global_load_lds((const unsigned*)((const char*)(gbase) + (voff)[_i]), (LAS unsigned*)(lds + (bufoff) + ldsw + _i * 8192), 16, 0, 0); } while (0)
; #define PG8_LDA(dst, b, h) do { _Pragma("unroll") for (int m = 0; m < 4; ++m) _Pragma("unroll") for (int k = 0; k < 2; ++k) dst[m][k] = *(const LAS bf16x8*)(lds + PG8_SA(b, h) + aoff + m * 2048 + k * 1024); } while (0)
; #define PG8_LDB(dst, b, h) do { _Pragma("unroll") for (int n = 0; n < 2; ++n) _Pragma("unroll") for (int k = 0; k < 2; ++k) dst[n][k] = *(const LAS bf16x8*)(lds + PG8_SB(b, h) + boff + n * 2048 + k * 1024); } while (0)
; template <class Epi, class Sched, bool ALIGN_EPI, bool LAST_FUSED = false, bool PERM = false, bool CARRY = false>
; __device__ __forceinline__ void gemm_phase(LAS unsigned char* lds, const int tid, const int K, const int lda, const int ldb, const Sched& S, const Epi& E) {
;     ...
;         for (int t = 0; t < nt; t += 2) {
;             const bool last = (t == nt - 2);
;             const char* a1 = cA + (size_t)(t + 1) * kstep;
;             const char* a2 = last ? nA : cA + (size_t)(t + 2) * kstep; const char* b2 = last ? nB : cB + (size_t)(t + 2) * kstep;
;             const char* a3 = a2 + kstep; const char* b3 = b2 + kstep;
;             PG8_LDB(B0, 0, 0); PG8_LDB(B1, 0, 1); PG8_SCHED; PG8_LDA(At, 0, 0); PG8_STAGE(PG8_SA(1, 1), a1 + hstepA, voffA);
;             PG8_WAIT_V(8); PG8_WAIT_L(0); PG8_BAR; PG8_MMA(0, 0, At, B0); PG8_MMA(0, 1, At, B1); PG8_BAR; PG8_SCHED;
;             PG8_LDA(At, 0, 1); PG8_STAGE(PG8_SB(0, 0), b2, voffB); PG8_STAGE(PG8_SB(0, 1), b2 + hstepB, voffB); PG8_STAGE(PG8_SA(0, 0), a2, voffA);
;             PG8_WAIT_V(8); PG8_WAIT_L(0); PG8_BAR; PG8_MMA(1, 0, At, B0); PG8_MMA(1, 1, At, B1); PG8_BAR; PG8_SCHED;
;             PG8_LDB(B0, 1, 0); PG8_LDB(B1, 1, 1); PG8_SCHED; PG8_LDA(At, 1, 0); PG8_STAGE(PG8_SA(0, 1), a2 + hstepA, voffA);
;             PG8_WAIT_V(8); PG8_WAIT_L(0); PG8_BAR; PG8_MMA(0, 0, At, B0); PG8_MMA(0, 1, At, B1); PG8_BAR; PG8_SCHED;
;             PG8_LDA(At, 1, 1); PG8_STAGE(PG8_SB(1, 0), b3, voffB); PG8_STAGE(PG8_SB(1, 1), b3 + hstepB, voffB); PG8_STAGE(PG8_SA(1, 0), a3, voffA);
;             PG8_WAIT_V(8); PG8_WAIT_L(0); PG8_BAR; PG8_MMA(1, 0, At, B0); PG8_MMA(1, 1, At, B1); PG8_BAR; PG8_SCHED;
.LBB0_1662:
	s_add_u32 s52, s38, s48
	s_addc_u32 s53, s39, s49
	s_add_u32 s66, s40, s48
	s_addc_u32 s67, s41, s49
	s_waitcnt lgkmcnt(0)
	s_add_i32 s90, 0, 0x10000
	s_cmp_eq_u32 s3, s89
	s_cselect_b32 s53, s24, s53
	s_cselect_b32 s52, s85, s52
	s_cselect_b32 s67, s86, s67
	s_cselect_b32 s66, s87, s66
	s_add_i32 s92, 0, 0x14000
	v_add_u32_e32 v156, s90, v140
	v_add_u32_e32 v172, s92, v140
	ds_read_b128 v[142:145], v156
	ds_read_b128 v[146:149], v156 offset:1024
	ds_read_b128 v[150:153], v156 offset:2048
	ds_read_b128 v[156:159], v156 offset:3072
	ds_read_b128 v[160:163], v172
	ds_read_b128 v[164:167], v172 offset:1024
	ds_read_b128 v[168:171], v172 offset:2048
	ds_read_b128 v[172:175], v172 offset:3072
	v_lshl_add_u64 v[208:209], s[38:39], 0, v[138:139]
	s_add_i32 m0, s35, 0xc000
	ds_read_b128 v[176:179], v141
	ds_read_b128 v[180:183], v141 offset:1024
	ds_read_b128 v[184:187], v141 offset:2048
	ds_read_b128 v[188:191], v141 offset:3072
	ds_read_b128 v[192:195], v141 offset:4096
	ds_read_b128 v[196:199], v141 offset:5120
	ds_read_b128 v[200:203], v141 offset:6144
	ds_read_b128 v[204:207], v141 offset:7168
	global_load_lds_dwordx4 v[208:209], off
	v_lshl_add_u64 v[208:209], s[38:39], 0, v[128:129]
	s_add_i32 m0, s35, 0xe000
	s_nop 0
	global_load_lds_dwordx4 v[208:209], off
	s_waitcnt vmcnt(8)
	s_waitcnt lgkmcnt(0)
	s_barrier
	s_setprio 1
	v_mfma_f32_16x16x32_bf16 v[62:65], v[142:145], v[176:179], v[62:65]
	v_mfma_f32_16x16x32_bf16 v[42:45], v[150:153], v[176:179], v[42:45]
	v_mfma_f32_16x16x32_bf16 v[18:21], v[142:145], v[184:187], v[18:21]
	v_mfma_f32_16x16x32_bf16 v[14:17], v[150:153], v[184:187], v[14:17]
	v_mfma_f32_16x16x32_bf16 v[38:41], v[142:145], v[192:195], v[38:41]
	v_mfma_f32_16x16x32_bf16 v[30:33], v[150:153], v[192:195], v[30:33]
	v_mfma_f32_16x16x32_bf16 v[58:61], v[142:145], v[200:203], v[58:61]
	v_mfma_f32_16x16x32_bf16 v[54:57], v[150:153], v[200:203], v[54:57]
	v_mfma_f32_16x16x32_bf16 v[62:65], v[146:149], v[180:183], v[62:65]
	v_mfma_f32_16x16x32_bf16 v[42:45], v[156:159], v[180:183], v[42:45]
	v_mfma_f32_16x16x32_bf16 v[18:21], v[146:149], v[188:191], v[18:21]
	v_mfma_f32_16x16x32_bf16 v[14:17], v[156:159], v[188:191], v[14:17]
	v_mfma_f32_16x16x32_bf16 v[38:41], v[146:149], v[196:199], v[38:41]
	v_mfma_f32_16x16x32_bf16 v[30:33], v[156:159], v[196:199], v[30:33]
	v_mfma_f32_16x16x32_bf16 v[58:61], v[146:149], v[204:207], v[58:61]
	v_mfma_f32_16x16x32_bf16 v[54:57], v[156:159], v[204:207], v[54:57]
	s_setprio 0
	s_setprio 1
	v_mfma_f32_16x16x32_bf16 v[34:37], v[160:163], v[176:179], v[34:37]
	v_mfma_f32_16x16x32_bf16 v[2:5], v[168:171], v[176:179], v[2:5]
	v_mfma_f32_16x16x32_bf16 v[10:13], v[160:163], v[184:187], v[10:13]
	v_mfma_f32_16x16x32_bf16 v[6:9], v[168:171], v[184:187], v[6:9]
	v_mfma_f32_16x16x32_bf16 v[26:29], v[160:163], v[192:195], v[26:29]
	v_mfma_f32_16x16x32_bf16 v[22:25], v[168:171], v[192:195], v[22:25]
	v_mfma_f32_16x16x32_bf16 v[50:53], v[160:163], v[200:203], v[50:53]
	v_mfma_f32_16x16x32_bf16 v[46:49], v[168:171], v[200:203], v[46:49]
	v_mfma_f32_16x16x32_bf16 v[34:37], v[164:167], v[180:183], v[34:37]
	v_mfma_f32_16x16x32_bf16 v[2:5], v[172:175], v[180:183], v[2:5]
	v_mfma_f32_16x16x32_bf16 v[10:13], v[164:167], v[188:191], v[10:13]
	v_mfma_f32_16x16x32_bf16 v[6:9], v[172:175], v[188:191], v[6:9]
	v_mfma_f32_16x16x32_bf16 v[26:29], v[164:167], v[196:199], v[26:29]
	v_mfma_f32_16x16x32_bf16 v[22:25], v[172:175], v[196:199], v[22:25]
	v_mfma_f32_16x16x32_bf16 v[50:53], v[164:167], v[204:207], v[50:53]
	v_mfma_f32_16x16x32_bf16 v[46:49], v[172:175], v[204:207], v[46:49]
	s_barrier
	s_setprio 0
	s_add_i32 s90, s90, s76
	v_lshl_add_u64 v[208:209], s[66:67], 0, v[0:1]
	s_mov_b32 m0, s90
	ds_read_b128 v[176:179], v141 offset:16384
	ds_read_b128 v[180:183], v141 offset:17408
	ds_read_b128 v[184:187], v141 offset:18432
	ds_read_b128 v[188:191], v141 offset:19456
	ds_read_b128 v[192:195], v141 offset:20480
	ds_read_b128 v[196:199], v141 offset:21504
	ds_read_b128 v[200:203], v141 offset:22528
	ds_read_b128 v[204:207], v141 offset:23552
	global_load_lds_dwordx4 v[208:209], off
	s_add_i32 m0, s90, 0x2000
	s_add_u32 s90, s66, 0x100000
	v_lshl_add_u64 v[210:211], s[66:67], 0, v[122:123]
	s_addc_u32 s91, s67, 0
	s_add_i32 s92, s92, s76
	global_load_lds_dwordx4 v[210:211], off
	v_lshl_add_u64 v[212:213], s[90:91], 0, v[0:1]
	s_mov_b32 m0, s92
	v_lshl_add_u64 v[214:215], s[52:53], 0, v[122:123]
	global_load_lds_dwordx4 v[212:213], off
	v_lshl_add_u64 v[212:213], s[90:91], 0, v[122:123]
	s_add_i32 m0, s92, 0x2000
	s_nop 0
	global_load_lds_dwordx4 v[212:213], off
	v_lshl_add_u64 v[212:213], s[52:53], 0, v[0:1]
	s_mov_b32 m0, s35
	s_nop 0
	global_load_lds_dwordx4 v[212:213], off
	s_mov_b32 m0, s28
	s_nop 0
	global_load_lds_dwordx4 v[214:215], off
	s_waitcnt vmcnt(8)
	s_waitcnt lgkmcnt(0)
	s_barrier
; #define PG8_STAGE(bufoff, gbase, voff) do { _Pragma("unroll") for (int _i = 0; _i < 2; ++_i) \
;         __builtin_amdgcn_global_load_lds((const unsigned*)((const char*)(gbase) + (voff)[_i]), (LAS unsigned*)(lds + (bufoff) + ldsw + _i * 8192), 16, 0, 0); } while (0)
; #define PG8_LDA(dst, b, h) do { _Pragma("unroll") for (int m = 0; m < 4; ++m) _Pragma("unroll") for (int k = 0; k < 2; ++k) dst[m][k] = *(const LAS bf16x8*)(lds + PG8_SA(b, h) + aoff + m * 2048 + k * 1024); } while (0)
; #define PG8_LDB(dst, b, h) do { _Pragma("unroll") for (int n = 0; n < 2; ++n) _Pragma("unroll") for (int k = 0; k < 2; ++k) dst[n][k] = *(const LAS bf16x8*)(lds + PG8_SB(b, h) + boff + n * 2048 + k * 1024); } while (0)
; #define PG8_MMA(ai, bj, At, Bt) do { __builtin_amdgcn_s_setprio(1); _Pragma("unroll") for (int m = 0; m < 4; ++m) _Pragma("unroll") for (int n = 0; n < 2; ++n) _Pragma("unroll") for (int k = 0; k < 2; ++k) \
;         acc[ai][bj][m][n] = __builtin_amdgcn_mfma_f32_16x16x32_bf16(Bt[n][k], At[m][k], acc[ai][bj][m][n], 0, 0, 0); __builtin_amdgcn_s_setprio(0); } while (0)
; #define PG8_WAIT_V(n) asm volatile("s_waitcnt vmcnt(" #n ")" ::: "memory")
; #define PG8_WAIT_L(n) asm volatile("s_waitcnt lgkmcnt(" #n ")" ::: "memory")
; #define PG8_BAR __builtin_amdgcn_s_barrier()
; #define PG8_SCHED __builtin_amdgcn_sched_barrier(0)
; template <class Epi, class Sched, bool ALIGN_EPI, bool LAST_FUSED = false, bool PERM = false, bool CARRY = false>
; __device__ __forceinline__ void gemm_phase(LAS unsigned char* lds, const int tid, const int K, const int lda, const int ldb, const Sched& S, const Epi& E) {
;     ...
;             PG8_WAIT_V(8); PG8_WAIT_L(0); PG8_BAR; PG8_MMA(1, 0, At, B0); PG8_MMA(1, 1, At, B1); PG8_BAR; PG8_SCHED;
;             PG8_LDB(B0, 1, 0); PG8_LDB(B1, 1, 1); PG8_SCHED; PG8_LDA(At, 1, 0); PG8_STAGE(PG8_SA(0, 1), a2 + hstepA, voffA);
;             PG8_WAIT_V(8); PG8_WAIT_L(0); PG8_BAR; PG8_MMA(0, 0, At, B0); PG8_MMA(0, 1, At, B1); PG8_BAR; PG8_SCHED;
;             PG8_LDA(At, 1, 1); PG8_STAGE(PG8_SB(1, 0), b3, voffB); PG8_STAGE(PG8_SB(1, 1), b3 + hstepB, voffB); PG8_STAGE(PG8_SA(1, 0), a3, voffA);
;             PG8_WAIT_V(8); PG8_WAIT_L(0); PG8_BAR; PG8_MMA(1, 0, At, B0); PG8_MMA(1, 1, At, B1); PG8_BAR; PG8_SCHED;
	s_setprio 1
	v_mfma_f32_16x16x32_bf16 v[78:81], v[142:145], v[176:179], v[78:81]
	v_mfma_f32_16x16x32_bf16 v[74:77], v[150:153], v[176:179], v[74:77]
	v_mfma_f32_16x16x32_bf16 v[98:101], v[142:145], v[184:187], v[98:101]
	v_mfma_f32_16x16x32_bf16 v[94:97], v[150:153], v[184:187], v[94:97]
	v_mfma_f32_16x16x32_bf16 v[118:121], v[142:145], v[192:195], v[118:121]
	v_mfma_f32_16x16x32_bf16 v[114:117], v[150:153], v[192:195], v[114:117]
	v_mfma_f32_16x16x32_bf16 v[134:137], v[142:145], v[200:203], v[134:137]
	v_mfma_f32_16x16x32_bf16 v[130:133], v[150:153], v[200:203], v[130:133]
	v_mfma_f32_16x16x32_bf16 v[78:81], v[146:149], v[180:183], v[78:81]
	v_mfma_f32_16x16x32_bf16 v[74:77], v[156:159], v[180:183], v[74:77]
	v_mfma_f32_16x16x32_bf16 v[98:101], v[146:149], v[188:191], v[98:101]
	v_mfma_f32_16x16x32_bf16 v[94:97], v[156:159], v[188:191], v[94:97]
	v_mfma_f32_16x16x32_bf16 v[118:121], v[146:149], v[196:199], v[118:121]
	v_mfma_f32_16x16x32_bf16 v[114:117], v[156:159], v[196:199], v[114:117]
	v_mfma_f32_16x16x32_bf16 v[134:137], v[146:149], v[204:207], v[134:137]
	v_mfma_f32_16x16x32_bf16 v[130:133], v[156:159], v[204:207], v[130:133]
	s_setprio 0
	s_setprio 1
	v_mfma_f32_16x16x32_bf16 v[70:73], v[160:163], v[176:179], v[70:73]
	v_mfma_f32_16x16x32_bf16 v[66:69], v[168:171], v[176:179], v[66:69]
	v_mfma_f32_16x16x32_bf16 v[90:93], v[160:163], v[184:187], v[90:93]
	v_mfma_f32_16x16x32_bf16 v[86:89], v[168:171], v[184:187], v[86:89]
	v_mfma_f32_16x16x32_bf16 v[110:113], v[160:163], v[192:195], v[110:113]
	v_mfma_f32_16x16x32_bf16 v[106:109], v[168:171], v[192:195], v[106:109]
	v_mfma_f32_16x16x32_bf16 v[102:105], v[160:163], v[200:203], v[102:105]
	v_mfma_f32_16x16x32_bf16 v[82:85], v[168:171], v[200:203], v[82:85]
	v_mfma_f32_16x16x32_bf16 v[70:73], v[164:167], v[180:183], v[70:73]
	v_mfma_f32_16x16x32_bf16 v[66:69], v[172:175], v[180:183], v[66:69]
	v_mfma_f32_16x16x32_bf16 v[90:93], v[164:167], v[188:191], v[90:93]
	v_mfma_f32_16x16x32_bf16 v[86:89], v[172:175], v[188:191], v[86:89]
	v_mfma_f32_16x16x32_bf16 v[110:113], v[164:167], v[196:199], v[110:113]
	v_mfma_f32_16x16x32_bf16 v[106:109], v[172:175], v[196:199], v[106:109]
	v_mfma_f32_16x16x32_bf16 v[102:105], v[164:167], v[204:207], v[102:105]
	v_mfma_f32_16x16x32_bf16 v[82:85], v[172:175], v[204:207], v[82:85]
	s_barrier
	s_setprio 0
	s_add_i32 s90, 0, 0x18000
	s_add_i32 s91, 0, 0x1c000
	v_add_u32_e32 v156, s90, v140
	v_add_u32_e32 v172, s91, v140
	ds_read_b128 v[142:145], v156
	ds_read_b128 v[146:149], v156 offset:1024
	ds_read_b128 v[150:153], v156 offset:2048
	ds_read_b128 v[156:159], v156 offset:3072
	ds_read_b128 v[160:163], v172
	ds_read_b128 v[164:167], v172 offset:1024
	ds_read_b128 v[168:171], v172 offset:2048
	ds_read_b128 v[172:175], v172 offset:3072
	s_add_u32 s52, s52, 0x100000
	s_addc_u32 s53, s53, 0
	s_mov_b32 m0, s29
	v_lshl_add_u64 v[216:217], s[52:53], 0, v[0:1]
	ds_read_b128 v[176:179], v141 offset:32768
	ds_read_b128 v[180:183], v141 offset:33792
	ds_read_b128 v[184:187], v141 offset:34816
	ds_read_b128 v[188:191], v141 offset:35840
	ds_read_b128 v[192:195], v141 offset:36864
	ds_read_b128 v[196:199], v141 offset:37888
	ds_read_b128 v[200:203], v141 offset:38912
	ds_read_b128 v[204:207], v141 offset:39936
	global_load_lds_dwordx4 v[216:217], off
	v_lshl_add_u64 v[216:217], s[52:53], 0, v[122:123]
	s_mov_b32 m0, s14
	s_nop 0
	global_load_lds_dwordx4 v[216:217], off
	s_waitcnt vmcnt(8)
	s_waitcnt lgkmcnt(0)
	s_barrier
	s_setprio 1
	v_mfma_f32_16x16x32_bf16 v[62:65], v[142:145], v[176:179], v[62:65]
	v_mfma_f32_16x16x32_bf16 v[42:45], v[150:153], v[176:179], v[42:45]
	v_mfma_f32_16x16x32_bf16 v[18:21], v[142:145], v[184:187], v[18:21]
	v_mfma_f32_16x16x32_bf16 v[14:17], v[150:153], v[184:187], v[14:17]
	v_mfma_f32_16x16x32_bf16 v[38:41], v[142:145], v[192:195], v[38:41]
	v_mfma_f32_16x16x32_bf16 v[30:33], v[150:153], v[192:195], v[30:33]
	v_mfma_f32_16x16x32_bf16 v[58:61], v[142:145], v[200:203], v[58:61]
	v_mfma_f32_16x16x32_bf16 v[54:57], v[150:153], v[200:203], v[54:57]
	v_mfma_f32_16x16x32_bf16 v[62:65], v[146:149], v[180:183], v[62:65]
	v_mfma_f32_16x16x32_bf16 v[42:45], v[156:159], v[180:183], v[42:45]
	v_mfma_f32_16x16x32_bf16 v[18:21], v[146:149], v[188:191], v[18:21]
	v_mfma_f32_16x16x32_bf16 v[14:17], v[156:159], v[188:191], v[14:17]
	v_mfma_f32_16x16x32_bf16 v[38:41], v[146:149], v[196:199], v[38:41]
	v_mfma_f32_16x16x32_bf16 v[30:33], v[156:159], v[196:199], v[30:33]
	v_mfma_f32_16x16x32_bf16 v[58:61], v[146:149], v[204:207], v[58:61]
	v_mfma_f32_16x16x32_bf16 v[54:57], v[156:159], v[204:207], v[54:57]
	s_setprio 0
	s_setprio 1
	v_mfma_f32_16x16x32_bf16 v[34:37], v[160:163], v[176:179], v[34:37]
	v_mfma_f32_16x16x32_bf16 v[2:5], v[168:171], v[176:179], v[2:5]
	v_mfma_f32_16x16x32_bf16 v[10:13], v[160:163], v[184:187], v[10:13]
	v_mfma_f32_16x16x32_bf16 v[6:9], v[168:171], v[184:187], v[6:9]
	v_mfma_f32_16x16x32_bf16 v[26:29], v[160:163], v[192:195], v[26:29]
	v_mfma_f32_16x16x32_bf16 v[22:25], v[168:171], v[192:195], v[22:25]
	v_mfma_f32_16x16x32_bf16 v[50:53], v[160:163], v[200:203], v[50:53]
	v_mfma_f32_16x16x32_bf16 v[46:49], v[168:171], v[200:203], v[46:49]
	v_mfma_f32_16x16x32_bf16 v[34:37], v[164:167], v[180:183], v[34:37]
	v_mfma_f32_16x16x32_bf16 v[2:5], v[172:175], v[180:183], v[2:5]
	v_mfma_f32_16x16x32_bf16 v[10:13], v[164:167], v[188:191], v[10:13]
	v_mfma_f32_16x16x32_bf16 v[6:9], v[172:175], v[188:191], v[6:9]
	v_mfma_f32_16x16x32_bf16 v[26:29], v[164:167], v[196:199], v[26:29]
	v_mfma_f32_16x16x32_bf16 v[22:25], v[172:175], v[196:199], v[22:25]
	v_mfma_f32_16x16x32_bf16 v[50:53], v[164:167], v[204:207], v[50:53]
	v_mfma_f32_16x16x32_bf16 v[46:49], v[172:175], v[204:207], v[46:49]
	s_barrier
; #define PG8_STAGE(bufoff, gbase, voff) do { _Pragma("unroll") for (int _i = 0; _i < 2; ++_i) \
;         __builtin_amdgcn_global_load_lds((const unsigned*)((const char*)(gbase) + (voff)[_i]), (LAS unsigned*)(lds + (bufoff) + ldsw + _i * 8192), 16, 0, 0); } while (0)
; #define PG8_LDA(dst, b, h) do { _Pragma("unroll") for (int m = 0; m < 4; ++m) _Pragma("unroll") for (int k = 0; k < 2; ++k) dst[m][k] = *(const LAS bf16x8*)(lds + PG8_SA(b, h) + aoff + m * 2048 + k * 1024); } while (0)
; #define PG8_LDB(dst, b, h) do { _Pragma("unroll") for (int n = 0; n < 2; ++n) _Pragma("unroll") for (int k = 0; k < 2; ++k) dst[n][k] = *(const LAS bf16x8*)(lds + PG8_SB(b, h) + boff + n * 2048 + k * 1024); } while (0)
; #define PG8_MMA(ai, bj, At, Bt) do { __builtin_amdgcn_s_setprio(1); _Pragma("unroll") for (int m = 0; m < 4; ++m) _Pragma("unroll") for (int n = 0; n < 2; ++n) _Pragma("unroll") for (int k = 0; k < 2; ++k) \
;         acc[ai][bj][m][n] = __builtin_amdgcn_mfma_f32_16x16x32_bf16(Bt[n][k], At[m][k], acc[ai][bj][m][n], 0, 0, 0); __builtin_amdgcn_s_setprio(0); } while (0)
; #define PG8_WAIT_V(n) asm volatile("s_waitcnt vmcnt(" #n ")" ::: "memory")
; #define PG8_WAIT_L(n) asm volatile("s_waitcnt lgkmcnt(" #n ")" ::: "memory")
; #define PG8_BAR __builtin_amdgcn_s_barrier()
; #define PG8_SCHED __builtin_amdgcn_sched_barrier(0)
; template <class Epi, class Sched, bool ALIGN_EPI, bool LAST_FUSED = false, bool PERM = false, bool CARRY = false>
; __device__ __forceinline__ void gemm_phase(LAS unsigned char* lds, const int tid, const int K, const int lda, const int ldb, const Sched& S, const Epi& E) {
;     ...
;             PG8_LDB(B0, 1, 0); PG8_LDB(B1, 1, 1); PG8_SCHED; PG8_LDA(At, 1, 0); PG8_STAGE(PG8_SA(0, 1), a2 + hstepA, voffA);
;             PG8_WAIT_V(8); PG8_WAIT_L(0); PG8_BAR; PG8_MMA(0, 0, At, B0); PG8_MMA(0, 1, At, B1); PG8_BAR; PG8_SCHED;
;             PG8_LDA(At, 1, 1); PG8_STAGE(PG8_SB(1, 0), b3, voffB); PG8_STAGE(PG8_SB(1, 1), b3 + hstepB, voffB); PG8_STAGE(PG8_SA(1, 0), a3, voffA);
;             PG8_WAIT_V(8); PG8_WAIT_L(0); PG8_BAR; PG8_MMA(1, 0, At, B0); PG8_MMA(1, 1, At, B1); PG8_BAR; PG8_SCHED;
;         }
;         if constexpr (ALIGN_EPI) { if (wr == 0) PG8_BAR; }
	s_setprio 0
	s_add_i32 s52, s90, s76
	v_lshl_add_u64 v[208:209], v[208:209], 0, s[68:69]
	s_mov_b32 m0, s52
	ds_read_b128 v[176:179], v141 offset:49152
	ds_read_b128 v[180:183], v141 offset:50176
	ds_read_b128 v[184:187], v141 offset:51200
	ds_read_b128 v[188:191], v141 offset:52224
	ds_read_b128 v[192:195], v141 offset:53248
	ds_read_b128 v[196:199], v141 offset:54272
	ds_read_b128 v[200:203], v141 offset:55296
	ds_read_b128 v[204:207], v141 offset:56320
	global_load_lds_dwordx4 v[208:209], off
	s_add_i32 m0, s52, 0x2000
	s_add_u32 s52, s66, 0x100080
	v_lshl_add_u64 v[208:209], v[210:211], 0, s[68:69]
	s_addc_u32 s53, s67, 0
	s_add_i32 s66, s91, s76
	global_load_lds_dwordx4 v[208:209], off
	v_lshl_add_u64 v[208:209], s[52:53], 0, v[0:1]
	s_mov_b32 m0, s66
	s_nop 0
	global_load_lds_dwordx4 v[208:209], off
	v_lshl_add_u64 v[208:209], s[52:53], 0, v[122:123]
	s_add_i32 m0, s66, 0x2000
	s_nop 0
	global_load_lds_dwordx4 v[208:209], off
	v_lshl_add_u64 v[208:209], v[212:213], 0, s[68:69]
	s_mov_b32 m0, s77
	s_nop 0
	global_load_lds_dwordx4 v[208:209], off
	v_lshl_add_u64 v[208:209], v[214:215], 0, s[68:69]
	s_mov_b32 m0, s79
	s_nop 0
	global_load_lds_dwordx4 v[208:209], off
	s_waitcnt vmcnt(8)
	s_waitcnt lgkmcnt(0)
	s_barrier
	s_setprio 1
	v_mfma_f32_16x16x32_bf16 v[78:81], v[142:145], v[176:179], v[78:81]
	v_mfma_f32_16x16x32_bf16 v[74:77], v[150:153], v[176:179], v[74:77]
	v_mfma_f32_16x16x32_bf16 v[98:101], v[142:145], v[184:187], v[98:101]
	v_mfma_f32_16x16x32_bf16 v[94:97], v[150:153], v[184:187], v[94:97]
	v_mfma_f32_16x16x32_bf16 v[118:121], v[142:145], v[192:195], v[118:121]
	v_mfma_f32_16x16x32_bf16 v[114:117], v[150:153], v[192:195], v[114:117]
	v_mfma_f32_16x16x32_bf16 v[134:137], v[142:145], v[200:203], v[134:137]
	v_mfma_f32_16x16x32_bf16 v[130:133], v[150:153], v[200:203], v[130:133]
	v_mfma_f32_16x16x32_bf16 v[78:81], v[146:149], v[180:183], v[78:81]
	v_mfma_f32_16x16x32_bf16 v[74:77], v[156:159], v[180:183], v[74:77]
	v_mfma_f32_16x16x32_bf16 v[98:101], v[146:149], v[188:191], v[98:101]
	v_mfma_f32_16x16x32_bf16 v[94:97], v[156:159], v[188:191], v[94:97]
	v_mfma_f32_16x16x32_bf16 v[118:121], v[146:149], v[196:199], v[118:121]
	v_mfma_f32_16x16x32_bf16 v[114:117], v[156:159], v[196:199], v[114:117]
	v_mfma_f32_16x16x32_bf16 v[134:137], v[146:149], v[204:207], v[134:137]
	v_mfma_f32_16x16x32_bf16 v[130:133], v[156:159], v[204:207], v[130:133]
	s_setprio 0
	s_setprio 1
	v_mfma_f32_16x16x32_bf16 v[70:73], v[160:163], v[176:179], v[70:73]
	v_mfma_f32_16x16x32_bf16 v[66:69], v[168:171], v[176:179], v[66:69]
	v_mfma_f32_16x16x32_bf16 v[90:93], v[160:163], v[184:187], v[90:93]
	v_mfma_f32_16x16x32_bf16 v[86:89], v[168:171], v[184:187], v[86:89]
	v_mfma_f32_16x16x32_bf16 v[110:113], v[160:163], v[192:195], v[110:113]
	v_mfma_f32_16x16x32_bf16 v[106:109], v[168:171], v[192:195], v[106:109]
	v_mfma_f32_16x16x32_bf16 v[102:105], v[160:163], v[200:203], v[102:105]
	v_mfma_f32_16x16x32_bf16 v[82:85], v[168:171], v[200:203], v[82:85]
	v_mfma_f32_16x16x32_bf16 v[70:73], v[164:167], v[180:183], v[70:73]
	v_mfma_f32_16x16x32_bf16 v[66:69], v[172:175], v[180:183], v[66:69]
	v_mfma_f32_16x16x32_bf16 v[90:93], v[164:167], v[188:191], v[90:93]
	v_mfma_f32_16x16x32_bf16 v[86:89], v[172:175], v[188:191], v[86:89]
	v_mfma_f32_16x16x32_bf16 v[110:113], v[164:167], v[196:199], v[110:113]
	v_mfma_f32_16x16x32_bf16 v[106:109], v[172:175], v[196:199], v[106:109]
	v_mfma_f32_16x16x32_bf16 v[102:105], v[164:167], v[204:207], v[102:105]
	v_mfma_f32_16x16x32_bf16 v[82:85], v[172:175], v[204:207], v[82:85]
	s_barrier
	s_setprio 0
	s_add_i32 s52, s89, 2
	s_add_u32 s48, s48, 0x100
	s_addc_u32 s49, s49, 0
	v_lshl_add_u64 v[138:139], v[138:139], 0, s[72:73]
	v_lshl_add_u64 v[128:129], v[128:129], 0, s[72:73]
	s_cmp_ge_i32 s89, s3
	s_mov_b32 s89, s52
	s_cbranch_scc0 .LBB0_1662
	s_and_b64 vcc, exec, s[36:37]
	s_cbranch_vccz .LBB0_1665
	s_barrier

; #define PG8_STAGE(bufoff, gbase, voff) do { _Pragma("unroll") for (int _i = 0; _i < 2; ++_i) \
;         __builtin_amdgcn_global_load_lds((const unsigned*)((const char*)(gbase) + (voff)[_i]), (LAS unsigned*)(lds + (bufoff) + ldsw + _i * 8192), 16, 0, 0); } while (0)
; #define PG8_LDA(dst, b, h) do { _Pragma("unroll") for (int m = 0; m < 4; ++m) _Pragma("unroll") for (int k = 0; k < 2; ++k) dst[m][k] = *(const LAS bf16x8*)(lds + PG8_SA(b, h) + aoff + m * 2048 + k * 1024); } while (0)
; #define PG8_LDB(dst, b, h) do { _Pragma("unroll") for (int n = 0; n < 2; ++n) _Pragma("unroll") for (int k = 0; k < 2; ++k) dst[n][k] = *(const LAS bf16x8*)(lds + PG8_SB(b, h) + boff + n * 2048 + k * 1024); } while (0)
; template <class Epi, class Sched, bool ALIGN_EPI, bool LAST_FUSED = false, bool PERM = false, bool CARRY = false>
; __device__ __forceinline__ void gemm_phase(LAS unsigned char* lds, const int tid, const int K, const int lda, const int ldb, const Sched& S, const Epi& E) {
;     ...
;         for (int t = 0; t < nt; t += 2) {
;             const bool last = (t == nt - 2);
;             const char* a1 = cA + (size_t)(t + 1) * kstep;
;             const char* a2 = last ? nA : cA + (size_t)(t + 2) * kstep; const char* b2 = last ? nB : cB + (size_t)(t + 2) * kstep;
;             const char* a3 = a2 + kstep; const char* b3 = b2 + kstep;
;             PG8_LDB(B0, 0, 0); PG8_LDB(B1, 0, 1); PG8_SCHED; PG8_LDA(At, 0, 0); PG8_STAGE(PG8_SA(1, 1), a1 + hstepA, voffA);
;             PG8_WAIT_V(8); PG8_WAIT_L(0); PG8_BAR; PG8_MMA(0, 0, At, B0); PG8_MMA(0, 1, At, B1); PG8_BAR; PG8_SCHED;
;             PG8_LDA(At, 0, 1); PG8_STAGE(PG8_SB(0, 0), b2, voffB); PG8_STAGE(PG8_SB(0, 1), b2 + hstepB, voffB); PG8_STAGE(PG8_SA(0, 0), a2, voffA);
;             PG8_WAIT_V(8); PG8_WAIT_L(0); PG8_BAR; PG8_MMA(1, 0, At, B0); PG8_MMA(1, 1, At, B1); PG8_BAR; PG8_SCHED;
;             PG8_LDB(B0, 1, 0); PG8_LDB(B1, 1, 1); PG8_SCHED; PG8_LDA(At, 1, 0); PG8_STAGE(PG8_SA(0, 1), a2 + hstepA, voffA);
;             PG8_WAIT_V(8); PG8_WAIT_L(0); PG8_BAR; PG8_MMA(0, 0, At, B0); PG8_MMA(0, 1, At, B1); PG8_BAR; PG8_SCHED;
;             PG8_LDA(At, 1, 1); PG8_STAGE(PG8_SB(1, 0), b3, voffB); PG8_STAGE(PG8_SB(1, 1), b3 + hstepB, voffB); PG8_STAGE(PG8_SA(1, 0), a3, voffA);
;             PG8_WAIT_V(8); PG8_WAIT_L(0); PG8_BAR; PG8_MMA(1, 0, At, B0); PG8_MMA(1, 1, At, B1); PG8_BAR; PG8_SCHED;
.LBB0_1763:
	s_add_u32 s16, s48, 0xfff80080
	s_addc_u32 s17, s49, -1
	s_add_i32 s67, 0, 0x10000
	s_cmp_eq_u32 s41, 28
	s_cselect_b32 s53, s43, s17
	s_cselect_b32 s52, s42, s16
	v_add_u32_e32 v140, s67, v146
	s_cselect_b32 s55, s51, s39
	s_cselect_b32 s54, s50, s27
	s_add_i32 s16, 0, 0x14000
	ds_read_b128 v[148:151], v140
	ds_read_b128 v[152:155], v140 offset:1024
	ds_read_b128 v[156:159], v140 offset:2048
	ds_read_b128 v[160:163], v140 offset:3072
	v_add_u32_e32 v140, s16, v146
	ds_read_b128 v[164:167], v140
	ds_read_b128 v[168:171], v140 offset:1024
	ds_read_b128 v[172:175], v140 offset:2048
	ds_read_b128 v[176:179], v140 offset:3072
	v_lshl_add_u64 v[140:141], s[48:49], 0, v[136:137]
	s_add_i32 m0, s47, 0xc000
	ds_read_b128 v[180:183], v147
	ds_read_b128 v[184:187], v147 offset:1024
	ds_read_b128 v[188:191], v147 offset:2048
	ds_read_b128 v[192:195], v147 offset:3072
	ds_read_b128 v[196:199], v147 offset:4096
	ds_read_b128 v[200:203], v147 offset:5120
	ds_read_b128 v[204:207], v147 offset:6144
	ds_read_b128 v[208:211], v147 offset:7168
	global_load_lds_dwordx4 v[140:141], off
	v_lshl_add_u64 v[140:141], s[48:49], 0, v[138:139]
	s_add_i32 m0, s47, 0xe000
	s_nop 0
	global_load_lds_dwordx4 v[140:141], off
	s_waitcnt vmcnt(8)
	s_waitcnt lgkmcnt(0)
	s_barrier
	s_setprio 1
	v_mfma_f32_16x16x32_bf16 v[126:129], v[148:151], v[180:183], v[126:129]
	v_mfma_f32_16x16x32_bf16 v[122:125], v[156:159], v[180:183], v[122:125]
	v_mfma_f32_16x16x32_bf16 v[110:113], v[148:151], v[188:191], v[110:113]
	v_mfma_f32_16x16x32_bf16 v[106:109], v[156:159], v[188:191], v[106:109]
	v_mfma_f32_16x16x32_bf16 v[94:97], v[148:151], v[196:199], v[94:97]
	v_mfma_f32_16x16x32_bf16 v[90:93], v[156:159], v[196:199], v[90:93]
	v_mfma_f32_16x16x32_bf16 v[78:81], v[148:151], v[204:207], v[78:81]
	v_mfma_f32_16x16x32_bf16 v[74:77], v[156:159], v[204:207], v[74:77]
	v_mfma_f32_16x16x32_bf16 v[126:129], v[152:155], v[184:187], v[126:129]
	v_mfma_f32_16x16x32_bf16 v[122:125], v[160:163], v[184:187], v[122:125]
	v_mfma_f32_16x16x32_bf16 v[110:113], v[152:155], v[192:195], v[110:113]
	v_mfma_f32_16x16x32_bf16 v[106:109], v[160:163], v[192:195], v[106:109]
	v_mfma_f32_16x16x32_bf16 v[94:97], v[152:155], v[200:203], v[94:97]
	v_mfma_f32_16x16x32_bf16 v[90:93], v[160:163], v[200:203], v[90:93]
	v_mfma_f32_16x16x32_bf16 v[78:81], v[152:155], v[208:211], v[78:81]
	v_mfma_f32_16x16x32_bf16 v[74:77], v[160:163], v[208:211], v[74:77]
	s_setprio 0
	s_setprio 1
	v_mfma_f32_16x16x32_bf16 v[118:121], v[164:167], v[180:183], v[118:121]
	v_mfma_f32_16x16x32_bf16 v[114:117], v[172:175], v[180:183], v[114:117]
	v_mfma_f32_16x16x32_bf16 v[102:105], v[164:167], v[188:191], v[102:105]
	v_mfma_f32_16x16x32_bf16 v[98:101], v[172:175], v[188:191], v[98:101]
	v_mfma_f32_16x16x32_bf16 v[86:89], v[164:167], v[196:199], v[86:89]
	v_mfma_f32_16x16x32_bf16 v[82:85], v[172:175], v[196:199], v[82:85]
	v_mfma_f32_16x16x32_bf16 v[70:73], v[164:167], v[204:207], v[70:73]
	v_mfma_f32_16x16x32_bf16 v[66:69], v[172:175], v[204:207], v[66:69]
	v_mfma_f32_16x16x32_bf16 v[118:121], v[168:171], v[184:187], v[118:121]
	v_mfma_f32_16x16x32_bf16 v[114:117], v[176:179], v[184:187], v[114:117]
	v_mfma_f32_16x16x32_bf16 v[102:105], v[168:171], v[192:195], v[102:105]
	v_mfma_f32_16x16x32_bf16 v[98:101], v[176:179], v[192:195], v[98:101]
	v_mfma_f32_16x16x32_bf16 v[86:89], v[168:171], v[200:203], v[86:89]
	v_mfma_f32_16x16x32_bf16 v[82:85], v[176:179], v[200:203], v[82:85]
	v_mfma_f32_16x16x32_bf16 v[70:73], v[168:171], v[208:211], v[70:73]
	v_mfma_f32_16x16x32_bf16 v[66:69], v[176:179], v[208:211], v[66:69]
	s_barrier
	s_setprio 0
	s_add_i32 s17, s67, s45
	v_lshl_add_u64 v[140:141], s[54:55], 0, v[0:1]
	s_mov_b32 m0, s17
	ds_read_b128 v[180:183], v147 offset:16384
	ds_read_b128 v[184:187], v147 offset:17408
	ds_read_b128 v[188:191], v147 offset:18432
	ds_read_b128 v[192:195], v147 offset:19456
	ds_read_b128 v[196:199], v147 offset:20480
	ds_read_b128 v[200:203], v147 offset:21504
	ds_read_b128 v[204:207], v147 offset:22528
	ds_read_b128 v[208:211], v147 offset:23552
	global_load_lds_dwordx4 v[140:141], off
	s_add_i32 m0, s17, 0x2000
	s_add_u32 s70, s54, 0x80000
	v_lshl_add_u64 v[212:213], s[54:55], 0, v[130:131]
	s_addc_u32 s71, s55, 0
	s_add_i32 s16, s16, s45
	global_load_lds_dwordx4 v[212:213], off
	v_lshl_add_u64 v[214:215], s[70:71], 0, v[0:1]
	s_mov_b32 m0, s16
	v_lshl_add_u64 v[216:217], s[52:53], 0, v[132:133]
	global_load_lds_dwordx4 v[214:215], off
	v_lshl_add_u64 v[214:215], s[70:71], 0, v[130:131]
	s_add_i32 m0, s16, 0x2000
	s_nop 0
	global_load_lds_dwordx4 v[214:215], off
	v_lshl_add_u64 v[214:215], s[52:53], 0, v[134:135]
	s_mov_b32 m0, s47
	s_nop 0
	global_load_lds_dwordx4 v[214:215], off
	s_mov_b32 m0, s57
	s_nop 0
	global_load_lds_dwordx4 v[216:217], off
	s_waitcnt vmcnt(8)
	s_waitcnt lgkmcnt(0)
	s_barrier
; #define PG8_STAGE(bufoff, gbase, voff) do { _Pragma("unroll") for (int _i = 0; _i < 2; ++_i) \
;         __builtin_amdgcn_global_load_lds((const unsigned*)((const char*)(gbase) + (voff)[_i]), (LAS unsigned*)(lds + (bufoff) + ldsw + _i * 8192), 16, 0, 0); } while (0)
; #define PG8_LDA(dst, b, h) do { _Pragma("unroll") for (int m = 0; m < 4; ++m) _Pragma("unroll") for (int k = 0; k < 2; ++k) dst[m][k] = *(const LAS bf16x8*)(lds + PG8_SA(b, h) + aoff + m * 2048 + k * 1024); } while (0)
; #define PG8_LDB(dst, b, h) do { _Pragma("unroll") for (int n = 0; n < 2; ++n) _Pragma("unroll") for (int k = 0; k < 2; ++k) dst[n][k] = *(const LAS bf16x8*)(lds + PG8_SB(b, h) + boff + n * 2048 + k * 1024); } while (0)
; #define PG8_MMA(ai, bj, At, Bt) do { __builtin_amdgcn_s_setprio(1); _Pragma("unroll") for (int m = 0; m < 4; ++m) _Pragma("unroll") for (int n = 0; n < 2; ++n) _Pragma("unroll") for (int k = 0; k < 2; ++k) \
;         acc[ai][bj][m][n] = __builtin_amdgcn_mfma_f32_16x16x32_bf16(Bt[n][k], At[m][k], acc[ai][bj][m][n], 0, 0, 0); __builtin_amdgcn_s_setprio(0); } while (0)
; #define PG8_WAIT_V(n) asm volatile("s_waitcnt vmcnt(" #n ")" ::: "memory")
; #define PG8_WAIT_L(n) asm volatile("s_waitcnt lgkmcnt(" #n ")" ::: "memory")
; #define PG8_BAR __builtin_amdgcn_s_barrier()
; #define PG8_SCHED __builtin_amdgcn_sched_barrier(0)
; template <class Epi, class Sched, bool ALIGN_EPI, bool LAST_FUSED = false, bool PERM = false, bool CARRY = false>
; __device__ __forceinline__ void gemm_phase(LAS unsigned char* lds, const int tid, const int K, const int lda, const int ldb, const Sched& S, const Epi& E) {
;     ...
;             PG8_WAIT_V(8); PG8_WAIT_L(0); PG8_BAR; PG8_MMA(1, 0, At, B0); PG8_MMA(1, 1, At, B1); PG8_BAR; PG8_SCHED;
;             PG8_LDB(B0, 1, 0); PG8_LDB(B1, 1, 1); PG8_SCHED; PG8_LDA(At, 1, 0); PG8_STAGE(PG8_SA(0, 1), a2 + hstepA, voffA);
;             PG8_WAIT_V(8); PG8_WAIT_L(0); PG8_BAR; PG8_MMA(0, 0, At, B0); PG8_MMA(0, 1, At, B1); PG8_BAR; PG8_SCHED;
;             PG8_LDA(At, 1, 1); PG8_STAGE(PG8_SB(1, 0), b3, voffB); PG8_STAGE(PG8_SB(1, 1), b3 + hstepB, voffB); PG8_STAGE(PG8_SA(1, 0), a3, voffA);
;             PG8_WAIT_V(8); PG8_WAIT_L(0); PG8_BAR; PG8_MMA(1, 0, At, B0); PG8_MMA(1, 1, At, B1); PG8_BAR; PG8_SCHED;
	s_setprio 1
	v_mfma_f32_16x16x32_bf16 v[62:65], v[148:151], v[180:183], v[62:65]
	v_mfma_f32_16x16x32_bf16 v[58:61], v[156:159], v[180:183], v[58:61]
	v_mfma_f32_16x16x32_bf16 v[46:49], v[148:151], v[188:191], v[46:49]
	v_mfma_f32_16x16x32_bf16 v[42:45], v[156:159], v[188:191], v[42:45]
	v_mfma_f32_16x16x32_bf16 v[30:33], v[148:151], v[196:199], v[30:33]
	v_mfma_f32_16x16x32_bf16 v[26:29], v[156:159], v[196:199], v[26:29]
	v_mfma_f32_16x16x32_bf16 v[14:17], v[148:151], v[204:207], v[14:17]
	v_mfma_f32_16x16x32_bf16 v[10:13], v[156:159], v[204:207], v[10:13]
	v_mfma_f32_16x16x32_bf16 v[62:65], v[152:155], v[184:187], v[62:65]
	v_mfma_f32_16x16x32_bf16 v[58:61], v[160:163], v[184:187], v[58:61]
	v_mfma_f32_16x16x32_bf16 v[46:49], v[152:155], v[192:195], v[46:49]
	v_mfma_f32_16x16x32_bf16 v[42:45], v[160:163], v[192:195], v[42:45]
	v_mfma_f32_16x16x32_bf16 v[30:33], v[152:155], v[200:203], v[30:33]
	v_mfma_f32_16x16x32_bf16 v[26:29], v[160:163], v[200:203], v[26:29]
	v_mfma_f32_16x16x32_bf16 v[14:17], v[152:155], v[208:211], v[14:17]
	v_mfma_f32_16x16x32_bf16 v[10:13], v[160:163], v[208:211], v[10:13]
	s_setprio 0
	s_setprio 1
	v_mfma_f32_16x16x32_bf16 v[54:57], v[164:167], v[180:183], v[54:57]
	v_mfma_f32_16x16x32_bf16 v[50:53], v[172:175], v[180:183], v[50:53]
	v_mfma_f32_16x16x32_bf16 v[38:41], v[164:167], v[188:191], v[38:41]
	v_mfma_f32_16x16x32_bf16 v[34:37], v[172:175], v[188:191], v[34:37]
	v_mfma_f32_16x16x32_bf16 v[22:25], v[164:167], v[196:199], v[22:25]
	v_mfma_f32_16x16x32_bf16 v[18:21], v[172:175], v[196:199], v[18:21]
	v_mfma_f32_16x16x32_bf16 v[6:9], v[164:167], v[204:207], v[6:9]
	v_mfma_f32_16x16x32_bf16 v[2:5], v[172:175], v[204:207], v[2:5]
	v_mfma_f32_16x16x32_bf16 v[54:57], v[168:171], v[184:187], v[54:57]
	v_mfma_f32_16x16x32_bf16 v[50:53], v[176:179], v[184:187], v[50:53]
	v_mfma_f32_16x16x32_bf16 v[38:41], v[168:171], v[192:195], v[38:41]
	v_mfma_f32_16x16x32_bf16 v[34:37], v[176:179], v[192:195], v[34:37]
	v_mfma_f32_16x16x32_bf16 v[22:25], v[168:171], v[200:203], v[22:25]
	v_mfma_f32_16x16x32_bf16 v[18:21], v[176:179], v[200:203], v[18:21]
	v_mfma_f32_16x16x32_bf16 v[6:9], v[168:171], v[208:211], v[6:9]
	v_mfma_f32_16x16x32_bf16 v[2:5], v[176:179], v[208:211], v[2:5]
	s_barrier
	s_setprio 0
	s_add_i32 s16, 0, 0x18000
	s_add_i32 s17, 0, 0x1c000
	v_add_u32_e32 v160, s16, v146
	v_add_u32_e32 v176, s17, v146
	ds_read_b128 v[148:151], v160
	ds_read_b128 v[152:155], v160 offset:1024
	ds_read_b128 v[156:159], v160 offset:2048
	ds_read_b128 v[160:163], v160 offset:3072
	ds_read_b128 v[164:167], v176
	ds_read_b128 v[168:171], v176 offset:1024
	ds_read_b128 v[172:175], v176 offset:2048
	ds_read_b128 v[176:179], v176 offset:3072
	s_add_u32 s52, s52, 0x80000
	s_addc_u32 s53, s53, 0
	s_mov_b32 m0, s58
	v_lshl_add_u64 v[218:219], s[52:53], 0, v[134:135]
	ds_read_b128 v[180:183], v147 offset:32768
	ds_read_b128 v[184:187], v147 offset:33792
	ds_read_b128 v[188:191], v147 offset:34816
	ds_read_b128 v[192:195], v147 offset:35840
	ds_read_b128 v[196:199], v147 offset:36864
	ds_read_b128 v[200:203], v147 offset:37888
	ds_read_b128 v[204:207], v147 offset:38912
	ds_read_b128 v[208:211], v147 offset:39936
	global_load_lds_dwordx4 v[218:219], off
	v_lshl_add_u64 v[218:219], s[52:53], 0, v[132:133]
	s_mov_b32 m0, s59
	s_nop 0
	global_load_lds_dwordx4 v[218:219], off
	s_waitcnt vmcnt(8)
	s_waitcnt lgkmcnt(0)
	s_barrier
	s_setprio 1
	v_mfma_f32_16x16x32_bf16 v[126:129], v[148:151], v[180:183], v[126:129]
	v_mfma_f32_16x16x32_bf16 v[122:125], v[156:159], v[180:183], v[122:125]
	v_mfma_f32_16x16x32_bf16 v[110:113], v[148:151], v[188:191], v[110:113]
	v_mfma_f32_16x16x32_bf16 v[106:109], v[156:159], v[188:191], v[106:109]
	v_mfma_f32_16x16x32_bf16 v[94:97], v[148:151], v[196:199], v[94:97]
	v_mfma_f32_16x16x32_bf16 v[90:93], v[156:159], v[196:199], v[90:93]
	v_mfma_f32_16x16x32_bf16 v[78:81], v[148:151], v[204:207], v[78:81]
	v_mfma_f32_16x16x32_bf16 v[74:77], v[156:159], v[204:207], v[74:77]
	v_mfma_f32_16x16x32_bf16 v[126:129], v[152:155], v[184:187], v[126:129]
	v_mfma_f32_16x16x32_bf16 v[122:125], v[160:163], v[184:187], v[122:125]
	v_mfma_f32_16x16x32_bf16 v[110:113], v[152:155], v[192:195], v[110:113]
	v_mfma_f32_16x16x32_bf16 v[106:109], v[160:163], v[192:195], v[106:109]
	v_mfma_f32_16x16x32_bf16 v[94:97], v[152:155], v[200:203], v[94:97]
	v_mfma_f32_16x16x32_bf16 v[90:93], v[160:163], v[200:203], v[90:93]
	v_mfma_f32_16x16x32_bf16 v[78:81], v[152:155], v[208:211], v[78:81]
	v_mfma_f32_16x16x32_bf16 v[74:77], v[160:163], v[208:211], v[74:77]
	s_setprio 0
	s_setprio 1
	v_mfma_f32_16x16x32_bf16 v[118:121], v[164:167], v[180:183], v[118:121]
	v_mfma_f32_16x16x32_bf16 v[114:117], v[172:175], v[180:183], v[114:117]
	v_mfma_f32_16x16x32_bf16 v[102:105], v[164:167], v[188:191], v[102:105]
	v_mfma_f32_16x16x32_bf16 v[98:101], v[172:175], v[188:191], v[98:101]
	v_mfma_f32_16x16x32_bf16 v[86:89], v[164:167], v[196:199], v[86:89]
	v_mfma_f32_16x16x32_bf16 v[82:85], v[172:175], v[196:199], v[82:85]
	v_mfma_f32_16x16x32_bf16 v[70:73], v[164:167], v[204:207], v[70:73]
	v_mfma_f32_16x16x32_bf16 v[66:69], v[172:175], v[204:207], v[66:69]
	v_mfma_f32_16x16x32_bf16 v[118:121], v[168:171], v[184:187], v[118:121]
	v_mfma_f32_16x16x32_bf16 v[114:117], v[176:179], v[184:187], v[114:117]
	v_mfma_f32_16x16x32_bf16 v[102:105], v[168:171], v[192:195], v[102:105]
	v_mfma_f32_16x16x32_bf16 v[98:101], v[176:179], v[192:195], v[98:101]
	v_mfma_f32_16x16x32_bf16 v[86:89], v[168:171], v[200:203], v[86:89]
	v_mfma_f32_16x16x32_bf16 v[82:85], v[176:179], v[200:203], v[82:85]
	v_mfma_f32_16x16x32_bf16 v[70:73], v[168:171], v[208:211], v[70:73]
	v_mfma_f32_16x16x32_bf16 v[66:69], v[176:179], v[208:211], v[66:69]
	s_barrier
; #define PG8_STAGE(bufoff, gbase, voff) do { _Pragma("unroll") for (int _i = 0; _i < 2; ++_i) \
;         __builtin_amdgcn_global_load_lds((const unsigned*)((const char*)(gbase) + (voff)[_i]), (LAS unsigned*)(lds + (bufoff) + ldsw + _i * 8192), 16, 0, 0); } while (0)
; #define PG8_LDA(dst, b, h) do { _Pragma("unroll") for (int m = 0; m < 4; ++m) _Pragma("unroll") for (int k = 0; k < 2; ++k) dst[m][k] = *(const LAS bf16x8*)(lds + PG8_SA(b, h) + aoff + m * 2048 + k * 1024); } while (0)
; #define PG8_LDB(dst, b, h) do { _Pragma("unroll") for (int n = 0; n < 2; ++n) _Pragma("unroll") for (int k = 0; k < 2; ++k) dst[n][k] = *(const LAS bf16x8*)(lds + PG8_SB(b, h) + boff + n * 2048 + k * 1024); } while (0)
; #define PG8_MMA(ai, bj, At, Bt) do { __builtin_amdgcn_s_setprio(1); _Pragma("unroll") for (int m = 0; m < 4; ++m) _Pragma("unroll") for (int n = 0; n < 2; ++n) _Pragma("unroll") for (int k = 0; k < 2; ++k) \
;         acc[ai][bj][m][n] = __builtin_amdgcn_mfma_f32_16x16x32_bf16(Bt[n][k], At[m][k], acc[ai][bj][m][n], 0, 0, 0); __builtin_amdgcn_s_setprio(0); } while (0)
; #define PG8_WAIT_V(n) asm volatile("s_waitcnt vmcnt(" #n ")" ::: "memory")
; #define PG8_WAIT_L(n) asm volatile("s_waitcnt lgkmcnt(" #n ")" ::: "memory")
; #define PG8_BAR __builtin_amdgcn_s_barrier()
; #define PG8_SCHED __builtin_amdgcn_sched_barrier(0)
; template <class Epi, class Sched, bool ALIGN_EPI, bool LAST_FUSED = false, bool PERM = false, bool CARRY = false>
; __device__ __forceinline__ void gemm_phase(LAS unsigned char* lds, const int tid, const int K, const int lda, const int ldb, const Sched& S, const Epi& E) {
;     ...
;             PG8_LDB(B0, 1, 0); PG8_LDB(B1, 1, 1); PG8_SCHED; PG8_LDA(At, 1, 0); PG8_STAGE(PG8_SA(0, 1), a2 + hstepA, voffA);
;             PG8_WAIT_V(8); PG8_WAIT_L(0); PG8_BAR; PG8_MMA(0, 0, At, B0); PG8_MMA(0, 1, At, B1); PG8_BAR; PG8_SCHED;
;             PG8_LDA(At, 1, 1); PG8_STAGE(PG8_SB(1, 0), b3, voffB); PG8_STAGE(PG8_SB(1, 1), b3 + hstepB, voffB); PG8_STAGE(PG8_SA(1, 0), a3, voffA);
;             PG8_WAIT_V(8); PG8_WAIT_L(0); PG8_BAR; PG8_MMA(1, 0, At, B0); PG8_MMA(1, 1, At, B1); PG8_BAR; PG8_SCHED;
;         }
;         if constexpr (ALIGN_EPI) { if (wr == 0) PG8_BAR; }
	s_setprio 0
	s_add_i32 s16, s16, s45
	v_lshl_add_u64 v[140:141], v[140:141], 0, s[68:69]
	s_mov_b32 m0, s16
	ds_read_b128 v[180:183], v147 offset:49152
	ds_read_b128 v[184:187], v147 offset:50176
	ds_read_b128 v[188:191], v147 offset:51200
	ds_read_b128 v[192:195], v147 offset:52224
	ds_read_b128 v[196:199], v147 offset:53248
	ds_read_b128 v[200:203], v147 offset:54272
	ds_read_b128 v[204:207], v147 offset:55296
	ds_read_b128 v[208:211], v147 offset:56320
	global_load_lds_dwordx4 v[140:141], off
	s_add_i32 m0, s16, 0x2000
	s_add_u32 s52, s54, 0x80080
	v_lshl_add_u64 v[140:141], v[212:213], 0, s[68:69]
	s_addc_u32 s53, s55, 0
	s_add_i32 s16, s17, s45
	global_load_lds_dwordx4 v[140:141], off
	v_lshl_add_u64 v[140:141], s[52:53], 0, v[0:1]
	s_mov_b32 m0, s16
	s_nop 0
	global_load_lds_dwordx4 v[140:141], off
	v_lshl_add_u64 v[140:141], s[52:53], 0, v[130:131]
	s_add_i32 m0, s16, 0x2000
	s_nop 0
	global_load_lds_dwordx4 v[140:141], off
	v_lshl_add_u64 v[140:141], v[214:215], 0, s[68:69]
	s_mov_b32 m0, s61
	s_nop 0
	global_load_lds_dwordx4 v[140:141], off
	v_lshl_add_u64 v[140:141], v[216:217], 0, s[68:69]
	s_mov_b32 m0, s62
	s_nop 0
	global_load_lds_dwordx4 v[140:141], off
	s_waitcnt vmcnt(8)
	s_waitcnt lgkmcnt(0)
	s_barrier
	s_setprio 1
	v_mfma_f32_16x16x32_bf16 v[62:65], v[148:151], v[180:183], v[62:65]
	v_mfma_f32_16x16x32_bf16 v[58:61], v[156:159], v[180:183], v[58:61]
	v_mfma_f32_16x16x32_bf16 v[46:49], v[148:151], v[188:191], v[46:49]
	v_mfma_f32_16x16x32_bf16 v[42:45], v[156:159], v[188:191], v[42:45]
	v_mfma_f32_16x16x32_bf16 v[30:33], v[148:151], v[196:199], v[30:33]
	v_mfma_f32_16x16x32_bf16 v[26:29], v[156:159], v[196:199], v[26:29]
	v_mfma_f32_16x16x32_bf16 v[14:17], v[148:151], v[204:207], v[14:17]
	v_mfma_f32_16x16x32_bf16 v[10:13], v[156:159], v[204:207], v[10:13]
	v_mfma_f32_16x16x32_bf16 v[62:65], v[152:155], v[184:187], v[62:65]
	v_mfma_f32_16x16x32_bf16 v[58:61], v[160:163], v[184:187], v[58:61]
	v_mfma_f32_16x16x32_bf16 v[46:49], v[152:155], v[192:195], v[46:49]
	v_mfma_f32_16x16x32_bf16 v[42:45], v[160:163], v[192:195], v[42:45]
	v_mfma_f32_16x16x32_bf16 v[30:33], v[152:155], v[200:203], v[30:33]
	v_mfma_f32_16x16x32_bf16 v[26:29], v[160:163], v[200:203], v[26:29]
	v_mfma_f32_16x16x32_bf16 v[14:17], v[152:155], v[208:211], v[14:17]
	v_mfma_f32_16x16x32_bf16 v[10:13], v[160:163], v[208:211], v[10:13]
	s_setprio 0
	s_setprio 1
	v_mfma_f32_16x16x32_bf16 v[54:57], v[164:167], v[180:183], v[54:57]
	v_mfma_f32_16x16x32_bf16 v[50:53], v[172:175], v[180:183], v[50:53]
	v_mfma_f32_16x16x32_bf16 v[38:41], v[164:167], v[188:191], v[38:41]
	v_mfma_f32_16x16x32_bf16 v[34:37], v[172:175], v[188:191], v[34:37]
	v_mfma_f32_16x16x32_bf16 v[22:25], v[164:167], v[196:199], v[22:25]
	v_mfma_f32_16x16x32_bf16 v[18:21], v[172:175], v[196:199], v[18:21]
	v_mfma_f32_16x16x32_bf16 v[6:9], v[164:167], v[204:207], v[6:9]
	v_mfma_f32_16x16x32_bf16 v[2:5], v[172:175], v[204:207], v[2:5]
	v_mfma_f32_16x16x32_bf16 v[54:57], v[168:171], v[184:187], v[54:57]
	v_mfma_f32_16x16x32_bf16 v[50:53], v[176:179], v[184:187], v[50:53]
	v_mfma_f32_16x16x32_bf16 v[38:41], v[168:171], v[192:195], v[38:41]
	v_mfma_f32_16x16x32_bf16 v[34:37], v[176:179], v[192:195], v[34:37]
	v_mfma_f32_16x16x32_bf16 v[22:25], v[168:171], v[200:203], v[22:25]
	v_mfma_f32_16x16x32_bf16 v[18:21], v[176:179], v[200:203], v[18:21]
	v_mfma_f32_16x16x32_bf16 v[6:9], v[168:171], v[208:211], v[6:9]
	v_mfma_f32_16x16x32_bf16 v[2:5], v[176:179], v[208:211], v[2:5]
	s_barrier
	s_setprio 0
	s_add_i32 s41, s41, 2
	s_add_u32 s48, s48, 0x100
	s_addc_u32 s49, s49, 0
	s_add_u32 s27, s27, 0x100
	s_addc_u32 s39, s39, 0
	s_cmp_gt_u32 s41, 29
	s_cbranch_scc0 .LBB0_1763
	s_and_b64 vcc, exec, s[36:37]
	s_cbranch_vccz .LBB0_1766
	s_barrier

; #define PG8_STAGE(bufoff, gbase, voff) do { _Pragma("unroll") for (int _i = 0; _i < 2; ++_i) \
;         __builtin_amdgcn_global_load_lds((const unsigned*)((const char*)(gbase) + (voff)[_i]), (LAS unsigned*)(lds + (bufoff) + ldsw + _i * 8192), 16, 0, 0); } while (0)
; #define PG8_LDA(dst, b, h) do { _Pragma("unroll") for (int m = 0; m < 4; ++m) _Pragma("unroll") for (int k = 0; k < 2; ++k) dst[m][k] = *(const LAS bf16x8*)(lds + PG8_SA(b, h) + aoff + m * 2048 + k * 1024); } while (0)
; #define PG8_LDB(dst, b, h) do { _Pragma("unroll") for (int n = 0; n < 2; ++n) _Pragma("unroll") for (int k = 0; k < 2; ++k) dst[n][k] = *(const LAS bf16x8*)(lds + PG8_SB(b, h) + boff + n * 2048 + k * 1024); } while (0)
; template <class Epi, class Sched, bool ALIGN_EPI, bool LAST_FUSED = false, bool PERM = false, bool CARRY = false>
; __device__ __forceinline__ void gemm_phase(LAS unsigned char* lds, const int tid, const int K, const int lda, const int ldb, const Sched& S, const Epi& E) {
;     ...
;         for (int t = 0; t < nt; t += 2) {
;             const bool last = (t == nt - 2);
;             const char* a1 = cA + (size_t)(t + 1) * kstep;
;             const char* a2 = last ? nA : cA + (size_t)(t + 2) * kstep; const char* b2 = last ? nB : cB + (size_t)(t + 2) * kstep;
;             const char* a3 = a2 + kstep; const char* b3 = b2 + kstep;
;             PG8_LDB(B0, 0, 0); PG8_LDB(B1, 0, 1); PG8_SCHED; PG8_LDA(At, 0, 0); PG8_STAGE(PG8_SA(1, 1), a1 + hstepA, voffA);
;             PG8_WAIT_V(8); PG8_WAIT_L(0); PG8_BAR; PG8_MMA(0, 0, At, B0); PG8_MMA(0, 1, At, B1); PG8_BAR; PG8_SCHED;
;             PG8_LDA(At, 0, 1); PG8_STAGE(PG8_SB(0, 0), b2, voffB); PG8_STAGE(PG8_SB(0, 1), b2 + hstepB, voffB); PG8_STAGE(PG8_SA(0, 0), a2, voffA);
;             PG8_WAIT_V(8); PG8_WAIT_L(0); PG8_BAR; PG8_MMA(1, 0, At, B0); PG8_MMA(1, 1, At, B1); PG8_BAR; PG8_SCHED;
;             PG8_LDB(B0, 1, 0); PG8_LDB(B1, 1, 1); PG8_SCHED; PG8_LDA(At, 1, 0); PG8_STAGE(PG8_SA(0, 1), a2 + hstepA, voffA);
;             PG8_WAIT_V(8); PG8_WAIT_L(0); PG8_BAR; PG8_MMA(0, 0, At, B0); PG8_MMA(0, 1, At, B1); PG8_BAR; PG8_SCHED;
;             PG8_LDA(At, 1, 1); PG8_STAGE(PG8_SB(1, 0), b3, voffB); PG8_STAGE(PG8_SB(1, 1), b3 + hstepB, voffB); PG8_STAGE(PG8_SA(1, 0), a3, voffA);
;             PG8_WAIT_V(8); PG8_WAIT_L(0); PG8_BAR; PG8_MMA(1, 0, At, B0); PG8_MMA(1, 1, At, B1); PG8_BAR; PG8_SCHED;
.LBB0_1854:
	s_add_u32 s16, s66, vcc_lo
	s_addc_u32 s17, s67, vcc_hi
	s_add_u32 s52, s50, vcc_lo
	s_addc_u32 s53, s51, vcc_hi
	s_add_i32 s92, 0, 0x10000
	s_cmp_eq_u32 s87, s60
	s_cselect_b32 s57, s24, s17
	s_cselect_b32 s56, s91, s16
	v_add_u32_e32 v154, s92, v140
	s_cselect_b32 s53, s70, s53
	s_cselect_b32 s52, s71, s52
	s_add_i32 s93, 0, 0x14000
	ds_read_b128 v[142:145], v154
	ds_read_b128 v[146:149], v154 offset:1024
	ds_read_b128 v[150:153], v154 offset:2048
	ds_read_b128 v[158:161], v154 offset:3072
	v_add_u32_e32 v154, s93, v140
	ds_read_b128 v[162:165], v154
	ds_read_b128 v[166:169], v154 offset:1024
	ds_read_b128 v[170:173], v154 offset:2048
	ds_read_b128 v[174:177], v154 offset:3072
	v_lshl_add_u64 v[154:155], s[66:67], 0, v[138:139]
	s_add_i32 m0, s28, 0xc000
	ds_read_b128 v[178:181], v141
	ds_read_b128 v[182:185], v141 offset:1024
	ds_read_b128 v[186:189], v141 offset:2048
	ds_read_b128 v[190:193], v141 offset:3072
	ds_read_b128 v[194:197], v141 offset:4096
	ds_read_b128 v[198:201], v141 offset:5120
	ds_read_b128 v[202:205], v141 offset:6144
	ds_read_b128 v[206:209], v141 offset:7168
	global_load_lds_dwordx4 v[154:155], off
	v_lshl_add_u64 v[154:155], s[66:67], 0, v[128:129]
	s_add_i32 m0, s28, 0xe000
	s_nop 0
	global_load_lds_dwordx4 v[154:155], off
	s_waitcnt vmcnt(8)
	s_waitcnt lgkmcnt(0)
	s_barrier
	s_setprio 1
	v_mfma_f32_16x16x32_bf16 v[118:121], v[142:145], v[178:181], v[118:121]
	v_mfma_f32_16x16x32_bf16 v[114:117], v[150:153], v[178:181], v[114:117]
	v_mfma_f32_16x16x32_bf16 v[110:113], v[142:145], v[186:189], v[110:113]
	v_mfma_f32_16x16x32_bf16 v[106:109], v[150:153], v[186:189], v[106:109]
	v_mfma_f32_16x16x32_bf16 v[86:89], v[142:145], v[194:197], v[86:89]
	v_mfma_f32_16x16x32_bf16 v[82:85], v[150:153], v[194:197], v[82:85]
	v_mfma_f32_16x16x32_bf16 v[78:81], v[142:145], v[202:205], v[78:81]
	v_mfma_f32_16x16x32_bf16 v[74:77], v[150:153], v[202:205], v[74:77]
	v_mfma_f32_16x16x32_bf16 v[118:121], v[146:149], v[182:185], v[118:121]
	v_mfma_f32_16x16x32_bf16 v[114:117], v[158:161], v[182:185], v[114:117]
	v_mfma_f32_16x16x32_bf16 v[110:113], v[146:149], v[190:193], v[110:113]
	v_mfma_f32_16x16x32_bf16 v[106:109], v[158:161], v[190:193], v[106:109]
	v_mfma_f32_16x16x32_bf16 v[86:89], v[146:149], v[198:201], v[86:89]
	v_mfma_f32_16x16x32_bf16 v[82:85], v[158:161], v[198:201], v[82:85]
	v_mfma_f32_16x16x32_bf16 v[78:81], v[146:149], v[206:209], v[78:81]
	v_mfma_f32_16x16x32_bf16 v[74:77], v[158:161], v[206:209], v[74:77]
	s_setprio 0
	s_setprio 1
	v_mfma_f32_16x16x32_bf16 v[98:101], v[162:165], v[178:181], v[98:101]
	v_mfma_f32_16x16x32_bf16 v[102:105], v[170:173], v[178:181], v[102:105]
	v_mfma_f32_16x16x32_bf16 v[90:93], v[162:165], v[186:189], v[90:93]
	v_mfma_f32_16x16x32_bf16 v[94:97], v[170:173], v[186:189], v[94:97]
	v_mfma_f32_16x16x32_bf16 v[66:69], v[162:165], v[194:197], v[66:69]
	v_mfma_f32_16x16x32_bf16 v[70:73], v[170:173], v[194:197], v[70:73]
	v_mfma_f32_16x16x32_bf16 v[50:53], v[162:165], v[202:205], v[50:53]
	v_mfma_f32_16x16x32_bf16 v[54:57], v[170:173], v[202:205], v[54:57]
	v_mfma_f32_16x16x32_bf16 v[98:101], v[166:169], v[182:185], v[98:101]
	v_mfma_f32_16x16x32_bf16 v[102:105], v[174:177], v[182:185], v[102:105]
	v_mfma_f32_16x16x32_bf16 v[90:93], v[166:169], v[190:193], v[90:93]
	v_mfma_f32_16x16x32_bf16 v[94:97], v[174:177], v[190:193], v[94:97]
	v_mfma_f32_16x16x32_bf16 v[66:69], v[166:169], v[198:201], v[66:69]
	v_mfma_f32_16x16x32_bf16 v[70:73], v[174:177], v[198:201], v[70:73]
	v_mfma_f32_16x16x32_bf16 v[50:53], v[166:169], v[206:209], v[50:53]
	v_mfma_f32_16x16x32_bf16 v[54:57], v[174:177], v[206:209], v[54:57]
	s_barrier
	s_setprio 0
	s_add_i32 s16, s92, s95
	v_lshl_add_u64 v[154:155], s[52:53], 0, v[0:1]
	s_mov_b32 m0, s16
	ds_read_b128 v[178:181], v141 offset:16384
	ds_read_b128 v[182:185], v141 offset:17408
	ds_read_b128 v[186:189], v141 offset:18432
	ds_read_b128 v[190:193], v141 offset:19456
	ds_read_b128 v[194:197], v141 offset:20480
	ds_read_b128 v[198:201], v141 offset:21504
	ds_read_b128 v[202:205], v141 offset:22528
	ds_read_b128 v[206:209], v141 offset:23552
	global_load_lds_dwordx4 v[154:155], off
	s_add_i32 m0, s16, 0x2000
	s_add_u32 s16, s52, 0x200000
	v_lshl_add_u64 v[210:211], s[52:53], 0, v[122:123]
	s_addc_u32 s17, s53, 0
	s_add_i32 s92, s93, s95
	global_load_lds_dwordx4 v[210:211], off
	v_lshl_add_u64 v[212:213], s[16:17], 0, v[0:1]
	s_mov_b32 m0, s92
	v_lshl_add_u64 v[214:215], s[56:57], 0, v[122:123]
	global_load_lds_dwordx4 v[212:213], off
	v_lshl_add_u64 v[212:213], s[16:17], 0, v[122:123]
	s_add_i32 m0, s92, 0x2000
	s_nop 0
	global_load_lds_dwordx4 v[212:213], off
	v_lshl_add_u64 v[212:213], s[56:57], 0, v[0:1]
	s_mov_b32 m0, s28
	s_nop 0
	global_load_lds_dwordx4 v[212:213], off
	s_mov_b32 m0, s29
	s_nop 0
	global_load_lds_dwordx4 v[214:215], off
	s_waitcnt vmcnt(8)
	s_waitcnt lgkmcnt(0)
	s_barrier
; #define PG8_STAGE(bufoff, gbase, voff) do { _Pragma("unroll") for (int _i = 0; _i < 2; ++_i) \
;         __builtin_amdgcn_global_load_lds((const unsigned*)((const char*)(gbase) + (voff)[_i]), (LAS unsigned*)(lds + (bufoff) + ldsw + _i * 8192), 16, 0, 0); } while (0)
; #define PG8_LDA(dst, b, h) do { _Pragma("unroll") for (int m = 0; m < 4; ++m) _Pragma("unroll") for (int k = 0; k < 2; ++k) dst[m][k] = *(const LAS bf16x8*)(lds + PG8_SA(b, h) + aoff + m * 2048 + k * 1024); } while (0)
; #define PG8_LDB(dst, b, h) do { _Pragma("unroll") for (int n = 0; n < 2; ++n) _Pragma("unroll") for (int k = 0; k < 2; ++k) dst[n][k] = *(const LAS bf16x8*)(lds + PG8_SB(b, h) + boff + n * 2048 + k * 1024); } while (0)
; #define PG8_MMA(ai, bj, At, Bt) do { __builtin_amdgcn_s_setprio(1); _Pragma("unroll") for (int m = 0; m < 4; ++m) _Pragma("unroll") for (int n = 0; n < 2; ++n) _Pragma("unroll") for (int k = 0; k < 2; ++k) \
;         acc[ai][bj][m][n] = __builtin_amdgcn_mfma_f32_16x16x32_bf16(Bt[n][k], At[m][k], acc[ai][bj][m][n], 0, 0, 0); __builtin_amdgcn_s_setprio(0); } while (0)
; #define PG8_WAIT_V(n) asm volatile("s_waitcnt vmcnt(" #n ")" ::: "memory")
; #define PG8_WAIT_L(n) asm volatile("s_waitcnt lgkmcnt(" #n ")" ::: "memory")
; #define PG8_BAR __builtin_amdgcn_s_barrier()
; #define PG8_SCHED __builtin_amdgcn_sched_barrier(0)
; template <class Epi, class Sched, bool ALIGN_EPI, bool LAST_FUSED = false, bool PERM = false, bool CARRY = false>
; __device__ __forceinline__ void gemm_phase(LAS unsigned char* lds, const int tid, const int K, const int lda, const int ldb, const Sched& S, const Epi& E) {
;     ...
;             PG8_WAIT_V(8); PG8_WAIT_L(0); PG8_BAR; PG8_MMA(1, 0, At, B0); PG8_MMA(1, 1, At, B1); PG8_BAR; PG8_SCHED;
;             PG8_LDB(B0, 1, 0); PG8_LDB(B1, 1, 1); PG8_SCHED; PG8_LDA(At, 1, 0); PG8_STAGE(PG8_SA(0, 1), a2 + hstepA, voffA);
;             PG8_WAIT_V(8); PG8_WAIT_L(0); PG8_BAR; PG8_MMA(0, 0, At, B0); PG8_MMA(0, 1, At, B1); PG8_BAR; PG8_SCHED;
;             PG8_LDA(At, 1, 1); PG8_STAGE(PG8_SB(1, 0), b3, voffB); PG8_STAGE(PG8_SB(1, 1), b3 + hstepB, voffB); PG8_STAGE(PG8_SA(1, 0), a3, voffA);
;             PG8_WAIT_V(8); PG8_WAIT_L(0); PG8_BAR; PG8_MMA(1, 0, At, B0); PG8_MMA(1, 1, At, B1); PG8_BAR; PG8_SCHED;
	s_setprio 1
	v_mfma_f32_16x16x32_bf16 v[62:65], v[142:145], v[178:181], v[62:65]
	v_mfma_f32_16x16x32_bf16 v[58:61], v[150:153], v[178:181], v[58:61]
	v_mfma_f32_16x16x32_bf16 v[38:41], v[142:145], v[186:189], v[38:41]
	v_mfma_f32_16x16x32_bf16 v[34:37], v[150:153], v[186:189], v[34:37]
	v_mfma_f32_16x16x32_bf16 v[22:25], v[142:145], v[194:197], v[22:25]
	v_mfma_f32_16x16x32_bf16 v[18:21], v[150:153], v[194:197], v[18:21]
	v_mfma_f32_16x16x32_bf16 v[134:137], v[142:145], v[202:205], v[134:137]
	v_mfma_f32_16x16x32_bf16 v[130:133], v[150:153], v[202:205], v[130:133]
	v_mfma_f32_16x16x32_bf16 v[62:65], v[146:149], v[182:185], v[62:65]
	v_mfma_f32_16x16x32_bf16 v[58:61], v[158:161], v[182:185], v[58:61]
	v_mfma_f32_16x16x32_bf16 v[38:41], v[146:149], v[190:193], v[38:41]
	v_mfma_f32_16x16x32_bf16 v[34:37], v[158:161], v[190:193], v[34:37]
	v_mfma_f32_16x16x32_bf16 v[22:25], v[146:149], v[198:201], v[22:25]
	v_mfma_f32_16x16x32_bf16 v[18:21], v[158:161], v[198:201], v[18:21]
	v_mfma_f32_16x16x32_bf16 v[134:137], v[146:149], v[206:209], v[134:137]
	v_mfma_f32_16x16x32_bf16 v[130:133], v[158:161], v[206:209], v[130:133]
	s_setprio 0
	s_setprio 1
	v_mfma_f32_16x16x32_bf16 v[42:45], v[162:165], v[178:181], v[42:45]
	v_mfma_f32_16x16x32_bf16 v[46:49], v[170:173], v[178:181], v[46:49]
	v_mfma_f32_16x16x32_bf16 v[26:29], v[162:165], v[186:189], v[26:29]
	v_mfma_f32_16x16x32_bf16 v[30:33], v[170:173], v[186:189], v[30:33]
	v_mfma_f32_16x16x32_bf16 v[14:17], v[162:165], v[194:197], v[14:17]
	v_mfma_f32_16x16x32_bf16 v[10:13], v[170:173], v[194:197], v[10:13]
	v_mfma_f32_16x16x32_bf16 v[6:9], v[162:165], v[202:205], v[6:9]
	v_mfma_f32_16x16x32_bf16 v[2:5], v[170:173], v[202:205], v[2:5]
	v_mfma_f32_16x16x32_bf16 v[42:45], v[166:169], v[182:185], v[42:45]
	v_mfma_f32_16x16x32_bf16 v[46:49], v[174:177], v[182:185], v[46:49]
	v_mfma_f32_16x16x32_bf16 v[26:29], v[166:169], v[190:193], v[26:29]
	v_mfma_f32_16x16x32_bf16 v[30:33], v[174:177], v[190:193], v[30:33]
	v_mfma_f32_16x16x32_bf16 v[14:17], v[166:169], v[198:201], v[14:17]
	v_mfma_f32_16x16x32_bf16 v[10:13], v[174:177], v[198:201], v[10:13]
	v_mfma_f32_16x16x32_bf16 v[6:9], v[166:169], v[206:209], v[6:9]
	v_mfma_f32_16x16x32_bf16 v[2:5], v[174:177], v[206:209], v[2:5]
	s_barrier
	s_setprio 0
	s_add_i32 s92, 0, 0x18000
	s_add_i32 s93, 0, 0x1c000
	v_add_u32_e32 v158, s92, v140
	v_add_u32_e32 v174, s93, v140
	ds_read_b128 v[142:145], v158
	ds_read_b128 v[146:149], v158 offset:1024
	ds_read_b128 v[150:153], v158 offset:2048
	ds_read_b128 v[158:161], v158 offset:3072
	ds_read_b128 v[162:165], v174
	ds_read_b128 v[166:169], v174 offset:1024
	ds_read_b128 v[170:173], v174 offset:2048
	ds_read_b128 v[174:177], v174 offset:3072
	s_add_u32 s16, s56, 0x200000
	s_addc_u32 s17, s57, 0
	s_mov_b32 m0, s14
	v_lshl_add_u64 v[216:217], s[16:17], 0, v[0:1]
	ds_read_b128 v[178:181], v141 offset:32768
	ds_read_b128 v[182:185], v141 offset:33792
	ds_read_b128 v[186:189], v141 offset:34816
	ds_read_b128 v[190:193], v141 offset:35840
	ds_read_b128 v[194:197], v141 offset:36864
	ds_read_b128 v[198:201], v141 offset:37888
	ds_read_b128 v[202:205], v141 offset:38912
	ds_read_b128 v[206:209], v141 offset:39936
	global_load_lds_dwordx4 v[216:217], off
	v_lshl_add_u64 v[216:217], s[16:17], 0, v[122:123]
	s_mov_b32 m0, s22
	s_nop 0
	global_load_lds_dwordx4 v[216:217], off
	s_waitcnt vmcnt(8)
	s_waitcnt lgkmcnt(0)
	s_barrier
	s_setprio 1
	v_mfma_f32_16x16x32_bf16 v[118:121], v[142:145], v[178:181], v[118:121]
	v_mfma_f32_16x16x32_bf16 v[114:117], v[150:153], v[178:181], v[114:117]
	v_mfma_f32_16x16x32_bf16 v[110:113], v[142:145], v[186:189], v[110:113]
	v_mfma_f32_16x16x32_bf16 v[106:109], v[150:153], v[186:189], v[106:109]
	v_mfma_f32_16x16x32_bf16 v[86:89], v[142:145], v[194:197], v[86:89]
	v_mfma_f32_16x16x32_bf16 v[82:85], v[150:153], v[194:197], v[82:85]
	v_mfma_f32_16x16x32_bf16 v[78:81], v[142:145], v[202:205], v[78:81]
	v_mfma_f32_16x16x32_bf16 v[74:77], v[150:153], v[202:205], v[74:77]
	v_mfma_f32_16x16x32_bf16 v[118:121], v[146:149], v[182:185], v[118:121]
	v_mfma_f32_16x16x32_bf16 v[114:117], v[158:161], v[182:185], v[114:117]
	v_mfma_f32_16x16x32_bf16 v[110:113], v[146:149], v[190:193], v[110:113]
	v_mfma_f32_16x16x32_bf16 v[106:109], v[158:161], v[190:193], v[106:109]
	v_mfma_f32_16x16x32_bf16 v[86:89], v[146:149], v[198:201], v[86:89]
	v_mfma_f32_16x16x32_bf16 v[82:85], v[158:161], v[198:201], v[82:85]
	v_mfma_f32_16x16x32_bf16 v[78:81], v[146:149], v[206:209], v[78:81]
	v_mfma_f32_16x16x32_bf16 v[74:77], v[158:161], v[206:209], v[74:77]
	s_setprio 0
	s_setprio 1
	v_mfma_f32_16x16x32_bf16 v[98:101], v[162:165], v[178:181], v[98:101]
	v_mfma_f32_16x16x32_bf16 v[102:105], v[170:173], v[178:181], v[102:105]
	v_mfma_f32_16x16x32_bf16 v[90:93], v[162:165], v[186:189], v[90:93]
	v_mfma_f32_16x16x32_bf16 v[94:97], v[170:173], v[186:189], v[94:97]
	v_mfma_f32_16x16x32_bf16 v[66:69], v[162:165], v[194:197], v[66:69]
	v_mfma_f32_16x16x32_bf16 v[70:73], v[170:173], v[194:197], v[70:73]
	v_mfma_f32_16x16x32_bf16 v[50:53], v[162:165], v[202:205], v[50:53]
	v_mfma_f32_16x16x32_bf16 v[54:57], v[170:173], v[202:205], v[54:57]
	v_mfma_f32_16x16x32_bf16 v[98:101], v[166:169], v[182:185], v[98:101]
	v_mfma_f32_16x16x32_bf16 v[102:105], v[174:177], v[182:185], v[102:105]
	v_mfma_f32_16x16x32_bf16 v[90:93], v[166:169], v[190:193], v[90:93]
	v_mfma_f32_16x16x32_bf16 v[94:97], v[174:177], v[190:193], v[94:97]
	v_mfma_f32_16x16x32_bf16 v[66:69], v[166:169], v[198:201], v[66:69]
	v_mfma_f32_16x16x32_bf16 v[70:73], v[174:177], v[198:201], v[70:73]
	v_mfma_f32_16x16x32_bf16 v[50:53], v[166:169], v[206:209], v[50:53]
	v_mfma_f32_16x16x32_bf16 v[54:57], v[174:177], v[206:209], v[54:57]
	s_barrier
; #define PG8_STAGE(bufoff, gbase, voff) do { _Pragma("unroll") for (int _i = 0; _i < 2; ++_i) \
;         __builtin_amdgcn_global_load_lds((const unsigned*)((const char*)(gbase) + (voff)[_i]), (LAS unsigned*)(lds + (bufoff) + ldsw + _i * 8192), 16, 0, 0); } while (0)
; #define PG8_LDA(dst, b, h) do { _Pragma("unroll") for (int m = 0; m < 4; ++m) _Pragma("unroll") for (int k = 0; k < 2; ++k) dst[m][k] = *(const LAS bf16x8*)(lds + PG8_SA(b, h) + aoff + m * 2048 + k * 1024); } while (0)
; #define PG8_LDB(dst, b, h) do { _Pragma("unroll") for (int n = 0; n < 2; ++n) _Pragma("unroll") for (int k = 0; k < 2; ++k) dst[n][k] = *(const LAS bf16x8*)(lds + PG8_SB(b, h) + boff + n * 2048 + k * 1024); } while (0)
; #define PG8_MMA(ai, bj, At, Bt) do { __builtin_amdgcn_s_setprio(1); _Pragma("unroll") for (int m = 0; m < 4; ++m) _Pragma("unroll") for (int n = 0; n < 2; ++n) _Pragma("unroll") for (int k = 0; k < 2; ++k) \
;         acc[ai][bj][m][n] = __builtin_amdgcn_mfma_f32_16x16x32_bf16(Bt[n][k], At[m][k], acc[ai][bj][m][n], 0, 0, 0); __builtin_amdgcn_s_setprio(0); } while (0)
; #define PG8_WAIT_V(n) asm volatile("s_waitcnt vmcnt(" #n ")" ::: "memory")
; #define PG8_WAIT_L(n) asm volatile("s_waitcnt lgkmcnt(" #n ")" ::: "memory")
; #define PG8_BAR __builtin_amdgcn_s_barrier()
; #define PG8_SCHED __builtin_amdgcn_sched_barrier(0)
; template <class Epi, class Sched, bool ALIGN_EPI, bool LAST_FUSED = false, bool PERM = false, bool CARRY = false>
; __device__ __forceinline__ void gemm_phase(LAS unsigned char* lds, const int tid, const int K, const int lda, const int ldb, const Sched& S, const Epi& E) {
;     ...
;             PG8_LDB(B0, 1, 0); PG8_LDB(B1, 1, 1); PG8_SCHED; PG8_LDA(At, 1, 0); PG8_STAGE(PG8_SA(0, 1), a2 + hstepA, voffA);
;             PG8_WAIT_V(8); PG8_WAIT_L(0); PG8_BAR; PG8_MMA(0, 0, At, B0); PG8_MMA(0, 1, At, B1); PG8_BAR; PG8_SCHED;
;             PG8_LDA(At, 1, 1); PG8_STAGE(PG8_SB(1, 0), b3, voffB); PG8_STAGE(PG8_SB(1, 1), b3 + hstepB, voffB); PG8_STAGE(PG8_SA(1, 0), a3, voffA);
;             PG8_WAIT_V(8); PG8_WAIT_L(0); PG8_BAR; PG8_MMA(1, 0, At, B0); PG8_MMA(1, 1, At, B1); PG8_BAR; PG8_SCHED;
;         }
;         if constexpr (ALIGN_EPI) { if (wr == 0) PG8_BAR; }
	s_setprio 0
	s_add_i32 s16, s92, s95
	v_lshl_add_u64 v[154:155], v[154:155], 0, s[68:69]
	s_mov_b32 m0, s16
	ds_read_b128 v[178:181], v141 offset:49152
	ds_read_b128 v[182:185], v141 offset:50176
	ds_read_b128 v[186:189], v141 offset:51200
	ds_read_b128 v[190:193], v141 offset:52224
	ds_read_b128 v[194:197], v141 offset:53248
	ds_read_b128 v[198:201], v141 offset:54272
	ds_read_b128 v[202:205], v141 offset:55296
	ds_read_b128 v[206:209], v141 offset:56320
	global_load_lds_dwordx4 v[154:155], off
	s_add_i32 m0, s16, 0x2000
	s_add_u32 s16, s52, 0x200080
	v_lshl_add_u64 v[154:155], v[210:211], 0, s[68:69]
	s_addc_u32 s17, s53, 0
	s_add_i32 s52, s93, s95
	global_load_lds_dwordx4 v[154:155], off
	v_lshl_add_u64 v[154:155], s[16:17], 0, v[0:1]
	s_mov_b32 m0, s52
	s_nop 0
	global_load_lds_dwordx4 v[154:155], off
	v_lshl_add_u64 v[154:155], s[16:17], 0, v[122:123]
	s_add_i32 m0, s52, 0x2000
	s_nop 0
	global_load_lds_dwordx4 v[154:155], off
	v_lshl_add_u64 v[154:155], v[212:213], 0, s[68:69]
	s_mov_b32 m0, s96
	s_nop 0
	global_load_lds_dwordx4 v[154:155], off
	v_lshl_add_u64 v[154:155], v[214:215], 0, s[68:69]
	s_mov_b32 m0, s97
	s_nop 0
	global_load_lds_dwordx4 v[154:155], off
	s_waitcnt vmcnt(8)
	s_waitcnt lgkmcnt(0)
	s_barrier
	s_setprio 1
	v_mfma_f32_16x16x32_bf16 v[62:65], v[142:145], v[178:181], v[62:65]
	v_mfma_f32_16x16x32_bf16 v[58:61], v[150:153], v[178:181], v[58:61]
	v_mfma_f32_16x16x32_bf16 v[38:41], v[142:145], v[186:189], v[38:41]
	v_mfma_f32_16x16x32_bf16 v[34:37], v[150:153], v[186:189], v[34:37]
	v_mfma_f32_16x16x32_bf16 v[22:25], v[142:145], v[194:197], v[22:25]
	v_mfma_f32_16x16x32_bf16 v[18:21], v[150:153], v[194:197], v[18:21]
	v_mfma_f32_16x16x32_bf16 v[134:137], v[142:145], v[202:205], v[134:137]
	v_mfma_f32_16x16x32_bf16 v[130:133], v[150:153], v[202:205], v[130:133]
	v_mfma_f32_16x16x32_bf16 v[62:65], v[146:149], v[182:185], v[62:65]
	v_mfma_f32_16x16x32_bf16 v[58:61], v[158:161], v[182:185], v[58:61]
	v_mfma_f32_16x16x32_bf16 v[38:41], v[146:149], v[190:193], v[38:41]
	v_mfma_f32_16x16x32_bf16 v[34:37], v[158:161], v[190:193], v[34:37]
	v_mfma_f32_16x16x32_bf16 v[22:25], v[146:149], v[198:201], v[22:25]
	v_mfma_f32_16x16x32_bf16 v[18:21], v[158:161], v[198:201], v[18:21]
	v_mfma_f32_16x16x32_bf16 v[134:137], v[146:149], v[206:209], v[134:137]
	v_mfma_f32_16x16x32_bf16 v[130:133], v[158:161], v[206:209], v[130:133]
	s_setprio 0
	s_setprio 1
	v_mfma_f32_16x16x32_bf16 v[42:45], v[162:165], v[178:181], v[42:45]
	v_mfma_f32_16x16x32_bf16 v[46:49], v[170:173], v[178:181], v[46:49]
	v_mfma_f32_16x16x32_bf16 v[26:29], v[162:165], v[186:189], v[26:29]
	v_mfma_f32_16x16x32_bf16 v[30:33], v[170:173], v[186:189], v[30:33]
	v_mfma_f32_16x16x32_bf16 v[14:17], v[162:165], v[194:197], v[14:17]
	v_mfma_f32_16x16x32_bf16 v[10:13], v[170:173], v[194:197], v[10:13]
	v_mfma_f32_16x16x32_bf16 v[6:9], v[162:165], v[202:205], v[6:9]
	v_mfma_f32_16x16x32_bf16 v[2:5], v[170:173], v[202:205], v[2:5]
	v_mfma_f32_16x16x32_bf16 v[42:45], v[166:169], v[182:185], v[42:45]
	v_mfma_f32_16x16x32_bf16 v[46:49], v[174:177], v[182:185], v[46:49]
	v_mfma_f32_16x16x32_bf16 v[26:29], v[166:169], v[190:193], v[26:29]
	v_mfma_f32_16x16x32_bf16 v[30:33], v[174:177], v[190:193], v[30:33]
	v_mfma_f32_16x16x32_bf16 v[14:17], v[166:169], v[198:201], v[14:17]
	v_mfma_f32_16x16x32_bf16 v[10:13], v[174:177], v[198:201], v[10:13]
	v_mfma_f32_16x16x32_bf16 v[6:9], v[166:169], v[206:209], v[6:9]
	v_mfma_f32_16x16x32_bf16 v[2:5], v[174:177], v[206:209], v[2:5]
	s_barrier
	s_setprio 0
	s_add_i32 s16, s60, 2
	s_add_u32 vcc_lo, vcc_lo, 0x100
	s_addc_u32 vcc_hi, vcc_hi, 0
	v_lshl_add_u64 v[138:139], v[138:139], 0, s[72:73]
	v_lshl_add_u64 v[128:129], v[128:129], 0, s[72:73]
	s_cmp_ge_i32 s60, s87
	s_mov_b32 s60, s16
	s_cbranch_scc0 .LBB0_1854
	s_and_b64 vcc, exec, s[40:41]
	s_cbranch_vccz .LBB0_1857
	s_barrier
